# GEMM main loops: an extra s_setprio 0/1 flip after every 8th MFMA of each 16-MFMA run (issue window for the loading wave half)
# baseline (speedup 1.0000x reference)
; #define PG8_STAGE(bufoff, gbase, voff) do { _Pragma("unroll") for (int _i = 0; _i < 2; ++_i) \
;         __builtin_amdgcn_global_load_lds((const GAS unsigned*)((const GAS char*)(gbase) + (size_t)_i * r64##voff + (vo##voff)), (LAS unsigned*)(lds + (bufoff) + ldsw + _i * 8192), 16, 0, 0); } while (0)
; #define PG8_LDA(dst, b, h) do { _Pragma("unroll") for (int m = 0; m < 4; ++m) _Pragma("unroll") for (int k = 0; k < 2; ++k) dst[m][k] = *(const LAS bf16x8*)(lds + PG8_SA(b, h) + aoff + m * 2048 + k * 1024); } while (0)
; #define PG8_LDB(dst, b, h) do { _Pragma("unroll") for (int n = 0; n < 2; ++n) _Pragma("unroll") for (int k = 0; k < 2; ++k) dst[n][k] = *(const LAS bf16x8*)(lds + PG8_SB(b, h) + boff + n * 2048 + k * 1024); } while (0)
; #define PG8_MMA(ai, bj, At, Bt) do { __builtin_amdgcn_s_setprio(1); _Pragma("unroll") for (int m = 0; m < 4; ++m) _Pragma("unroll") for (int n = 0; n < 2; ++n) _Pragma("unroll") for (int k = 0; k < 2; ++k) \
;         acc[ai][bj][m][n] = __builtin_amdgcn_mfma_f32_16x16x32_bf16(Bt[n][k], At[m][k], acc[ai][bj][m][n], 0, 0, 0); __builtin_amdgcn_s_setprio(0); } while (0)
; #define PG8_WAIT_V(n) asm volatile("s_waitcnt vmcnt(" #n ")" ::: "memory")
; #define PG8_WAIT_L(n) asm volatile("s_waitcnt lgkmcnt(" #n ")" ::: "memory")
; template <class Epi, class Map, bool ALIGN_EPI>
; __device__ __forceinline__ void gemm_phase(const int tid, LAS unsigned char* lds, const int lda, const int ldb, const int K, const Map& MP, const StaticOrder& S, const Epi& E) {
;     ...
;         for (int t = 0; t < nt; t += 2) {
;             const bool last = (t == nt - 2);
;             const char* a1 = cA + (size_t)(t + 1) * kstep;
;             const char* a2 = last ? nA : cA + (size_t)(t + 2) * kstep; const char* b2 = last ? nB : cB + (size_t)(t + 2) * kstep;
;             const char* a3 = a2 + kstep; const char* b3 = b2 + kstep;
;             PG8_LDB(B0, 0, 0); PG8_LDB(B1, 0, 1); PG8_SCHED; PG8_LDA(At, 0, 0); PG8_STAGE(PG8_SA(1, 1), a1 + hstepA, A);
;             PG8_WAIT_V(8); PG8_WAIT_L(0); PG8_BAR; PG8_MMA(0, 0, At, B0); PG8_MMA(0, 1, At, B1); PG8_BAR; PG8_SCHED;
;             PG8_LDA(At, 0, 1); PG8_STAGE(PG8_SB(0, 0), b2, B); PG8_STAGE(PG8_SB(0, 1), b2 + hstepB, B); PG8_STAGE(PG8_SA(0, 0), a2, A);
;             PG8_WAIT_V(8); PG8_WAIT_L(0); PG8_BAR; PG8_MMA(1, 0, At, B0); PG8_MMA(1, 1, At, B1); PG8_BAR; PG8_SCHED;
.LBB0_131:
	s_add_u32 s44, s42, 0xfffc0080
	s_addc_u32 s45, s43, -1
	s_add_i32 s49, 0, 0x10000
	s_cmp_eq_u32 s48, 12
	s_cselect_b32 s45, s23, s45
	s_cselect_b32 s44, s22, s44
	s_cselect_b32 s57, s47, s21
	s_cselect_b32 s56, s46, s17
	s_add_i32 s53, 0, 0x14000
	v_add_u32_e32 v108, s49, v214
	v_add_u32_e32 v124, s53, v214
	ds_read_b128 v[80:83], v108
	ds_read_b128 v[96:99], v108 offset:1024
	ds_read_b128 v[104:107], v108 offset:2048
	ds_read_b128 v[108:111], v108 offset:3072
	ds_read_b128 v[112:115], v124
	ds_read_b128 v[116:119], v124 offset:1024
	ds_read_b128 v[120:123], v124 offset:2048
	ds_read_b128 v[124:127], v124 offset:3072
	v_lshl_add_u64 v[192:193], s[42:43], 0, v[202:203]
	s_add_i32 m0, s24, 0xc000
	ds_read_b128 v[160:163], v215
	ds_read_b128 v[164:167], v215 offset:1024
	ds_read_b128 v[168:171], v215 offset:2048
	ds_read_b128 v[172:175], v215 offset:3072
	ds_read_b128 v[176:179], v215 offset:4096
	ds_read_b128 v[180:183], v215 offset:5120
	ds_read_b128 v[184:187], v215 offset:6144
	ds_read_b128 v[188:191], v215 offset:7168
	global_load_lds_dwordx4 v[192:193], off
	v_lshl_add_u64 v[192:193], v[192:193], 0, s[90:91]
	s_add_i32 m0, s24, 0xe000
	s_nop 0
	global_load_lds_dwordx4 v[192:193], off
	s_waitcnt vmcnt(8)
	s_waitcnt lgkmcnt(0)
	s_barrier
	s_setprio 1
	v_mfma_f32_16x16x32_bf16 v[156:159], v[80:83], v[160:163], v[156:159]
	v_mfma_f32_16x16x32_bf16 v[60:63], v[104:107], v[160:163], v[60:63]
	v_mfma_f32_16x16x32_bf16 v[148:151], v[80:83], v[168:171], v[148:151]
	v_mfma_f32_16x16x32_bf16 v[52:55], v[104:107], v[168:171], v[52:55]
	v_mfma_f32_16x16x32_bf16 v[152:155], v[80:83], v[176:179], v[152:155]
	v_mfma_f32_16x16x32_bf16 v[56:59], v[104:107], v[176:179], v[56:59]
	v_mfma_f32_16x16x32_bf16 v[136:139], v[80:83], v[184:187], v[136:139]
	v_mfma_f32_16x16x32_bf16 v[48:51], v[104:107], v[184:187], v[48:51]
	s_setprio 0
	s_setprio 1
	v_mfma_f32_16x16x32_bf16 v[156:159], v[96:99], v[164:167], v[156:159]
	v_mfma_f32_16x16x32_bf16 v[60:63], v[108:111], v[164:167], v[60:63]
	v_mfma_f32_16x16x32_bf16 v[148:151], v[96:99], v[172:175], v[148:151]
	v_mfma_f32_16x16x32_bf16 v[52:55], v[108:111], v[172:175], v[52:55]
	v_mfma_f32_16x16x32_bf16 v[152:155], v[96:99], v[180:183], v[152:155]
	v_mfma_f32_16x16x32_bf16 v[56:59], v[108:111], v[180:183], v[56:59]
	v_mfma_f32_16x16x32_bf16 v[136:139], v[96:99], v[188:191], v[136:139]
	v_mfma_f32_16x16x32_bf16 v[48:51], v[108:111], v[188:191], v[48:51]
	s_setprio 0
	s_setprio 1
	v_mfma_f32_16x16x32_bf16 v[144:147], v[112:115], v[160:163], v[144:147]
	v_mfma_f32_16x16x32_bf16 v[36:39], v[120:123], v[160:163], v[36:39]
	v_mfma_f32_16x16x32_bf16 v[128:131], v[112:115], v[168:171], v[128:131]
	v_mfma_f32_16x16x32_bf16 v[32:35], v[120:123], v[168:171], v[32:35]
	v_mfma_f32_16x16x32_bf16 v[140:143], v[112:115], v[176:179], v[140:143]
	v_mfma_f32_16x16x32_bf16 v[44:47], v[120:123], v[176:179], v[44:47]
	v_mfma_f32_16x16x32_bf16 v[132:135], v[112:115], v[184:187], v[132:135]
	v_mfma_f32_16x16x32_bf16 v[40:43], v[120:123], v[184:187], v[40:43]
	s_setprio 0
	s_setprio 1
	v_mfma_f32_16x16x32_bf16 v[144:147], v[116:119], v[164:167], v[144:147]
	v_mfma_f32_16x16x32_bf16 v[36:39], v[124:127], v[164:167], v[36:39]
	v_mfma_f32_16x16x32_bf16 v[128:131], v[116:119], v[172:175], v[128:131]
	v_mfma_f32_16x16x32_bf16 v[32:35], v[124:127], v[172:175], v[32:35]
	v_mfma_f32_16x16x32_bf16 v[140:143], v[116:119], v[180:183], v[140:143]
	v_mfma_f32_16x16x32_bf16 v[44:47], v[124:127], v[180:183], v[44:47]
	v_mfma_f32_16x16x32_bf16 v[132:135], v[116:119], v[188:191], v[132:135]
	v_mfma_f32_16x16x32_bf16 v[40:43], v[124:127], v[188:191], v[40:43]
	s_setprio 0
	s_barrier
	s_add_i32 s49, s49, s19
	v_lshl_add_u64 v[192:193], s[56:57], 0, v[200:201]
	s_mov_b32 m0, s49
	ds_read_b128 v[160:163], v215 offset:16384
	ds_read_b128 v[164:167], v215 offset:17408
	ds_read_b128 v[168:171], v215 offset:18432
	ds_read_b128 v[172:175], v215 offset:19456
	ds_read_b128 v[176:179], v215 offset:20480
	ds_read_b128 v[180:183], v215 offset:21504
	ds_read_b128 v[184:187], v215 offset:22528
	ds_read_b128 v[188:191], v215 offset:23552
	global_load_lds_dwordx4 v[192:193], off
	v_lshl_add_u64 v[194:195], v[192:193], 0, s[90:91]
	s_add_i32 m0, s49, 0x2000
	s_add_i32 s49, s53, s19
	global_load_lds_dwordx4 v[194:195], off
	v_lshl_add_u64 v[194:195], v[192:193], 0, s[74:75]
	s_mov_b32 m0, s49
	s_nop 0
	global_load_lds_dwordx4 v[194:195], off
	v_lshl_add_u64 v[194:195], v[192:193], 0, s[94:95]
	s_add_i32 m0, s49, 0x2000
	s_nop 0
	global_load_lds_dwordx4 v[194:195], off
	v_lshl_add_u64 v[194:195], s[44:45], 0, v[202:203]
	s_mov_b32 m0, s24
	v_lshl_add_u64 v[196:197], v[194:195], 0, s[90:91]
	global_load_lds_dwordx4 v[194:195], off
	s_mov_b32 m0, s28
	s_nop 0
	global_load_lds_dwordx4 v[196:197], off
	s_waitcnt vmcnt(8)
	s_waitcnt lgkmcnt(0)
	s_barrier
; #define PG8_STAGE(bufoff, gbase, voff) do { _Pragma("unroll") for (int _i = 0; _i < 2; ++_i) \
;         __builtin_amdgcn_global_load_lds((const GAS unsigned*)((const GAS char*)(gbase) + (size_t)_i * r64##voff + (vo##voff)), (LAS unsigned*)(lds + (bufoff) + ldsw + _i * 8192), 16, 0, 0); } while (0)
; #define PG8_LDA(dst, b, h) do { _Pragma("unroll") for (int m = 0; m < 4; ++m) _Pragma("unroll") for (int k = 0; k < 2; ++k) dst[m][k] = *(const LAS bf16x8*)(lds + PG8_SA(b, h) + aoff + m * 2048 + k * 1024); } while (0)
; #define PG8_LDB(dst, b, h) do { _Pragma("unroll") for (int n = 0; n < 2; ++n) _Pragma("unroll") for (int k = 0; k < 2; ++k) dst[n][k] = *(const LAS bf16x8*)(lds + PG8_SB(b, h) + boff + n * 2048 + k * 1024); } while (0)
; #define PG8_MMA(ai, bj, At, Bt) do { __builtin_amdgcn_s_setprio(1); _Pragma("unroll") for (int m = 0; m < 4; ++m) _Pragma("unroll") for (int n = 0; n < 2; ++n) _Pragma("unroll") for (int k = 0; k < 2; ++k) \
;         acc[ai][bj][m][n] = __builtin_amdgcn_mfma_f32_16x16x32_bf16(Bt[n][k], At[m][k], acc[ai][bj][m][n], 0, 0, 0); __builtin_amdgcn_s_setprio(0); } while (0)
; #define PG8_WAIT_V(n) asm volatile("s_waitcnt vmcnt(" #n ")" ::: "memory")
; #define PG8_WAIT_L(n) asm volatile("s_waitcnt lgkmcnt(" #n ")" ::: "memory")
; #define PG8_BAR __builtin_amdgcn_s_barrier()
; #define PG8_SCHED __builtin_amdgcn_sched_barrier(0)
; template <class Epi, class Map, bool ALIGN_EPI>
; __device__ __forceinline__ void gemm_phase(const int tid, LAS unsigned char* lds, const int lda, const int ldb, const int K, const Map& MP, const StaticOrder& S, const Epi& E) {
;     ...
;             PG8_LDB(B0, 0, 0); PG8_LDB(B1, 0, 1); PG8_SCHED; PG8_LDA(At, 0, 0); PG8_STAGE(PG8_SA(1, 1), a1 + hstepA, A);
;             PG8_WAIT_V(8); PG8_WAIT_L(0); PG8_BAR; PG8_MMA(0, 0, At, B0); PG8_MMA(0, 1, At, B1); PG8_BAR; PG8_SCHED;
;             PG8_LDA(At, 0, 1); PG8_STAGE(PG8_SB(0, 0), b2, B); PG8_STAGE(PG8_SB(0, 1), b2 + hstepB, B); PG8_STAGE(PG8_SA(0, 0), a2, A);
;             PG8_WAIT_V(8); PG8_WAIT_L(0); PG8_BAR; PG8_MMA(1, 0, At, B0); PG8_MMA(1, 1, At, B1); PG8_BAR; PG8_SCHED;
;             PG8_LDB(B0, 1, 0); PG8_LDB(B1, 1, 1); PG8_SCHED; PG8_LDA(At, 1, 0); PG8_STAGE(PG8_SA(0, 1), a2 + hstepA, A);
;             PG8_WAIT_V(8); PG8_WAIT_L(0); PG8_BAR; PG8_MMA(0, 0, At, B0); PG8_MMA(0, 1, At, B1); PG8_BAR; PG8_SCHED;
	s_setprio 1
	v_mfma_f32_16x16x32_bf16 v[100:103], v[80:83], v[160:163], v[100:103]
	v_mfma_f32_16x16x32_bf16 v[4:7], v[104:107], v[160:163], v[4:7]
	v_mfma_f32_16x16x32_bf16 v[64:67], v[80:83], v[168:171], v[64:67]
	v_mfma_f32_16x16x32_bf16 v[0:3], v[104:107], v[168:171], v[0:3]
	v_mfma_f32_16x16x32_bf16 v[92:95], v[80:83], v[176:179], v[92:95]
	v_mfma_f32_16x16x32_bf16 v[16:19], v[104:107], v[176:179], v[16:19]
	v_mfma_f32_16x16x32_bf16 v[68:71], v[80:83], v[184:187], v[68:71]
	v_mfma_f32_16x16x32_bf16 v[8:11], v[104:107], v[184:187], v[8:11]
	s_setprio 0
	s_setprio 1
	v_mfma_f32_16x16x32_bf16 v[100:103], v[96:99], v[164:167], v[100:103]
	v_mfma_f32_16x16x32_bf16 v[4:7], v[108:111], v[164:167], v[4:7]
	v_mfma_f32_16x16x32_bf16 v[64:67], v[96:99], v[172:175], v[64:67]
	v_mfma_f32_16x16x32_bf16 v[0:3], v[108:111], v[172:175], v[0:3]
	v_mfma_f32_16x16x32_bf16 v[92:95], v[96:99], v[180:183], v[92:95]
	v_mfma_f32_16x16x32_bf16 v[16:19], v[108:111], v[180:183], v[16:19]
	v_mfma_f32_16x16x32_bf16 v[68:71], v[96:99], v[188:191], v[68:71]
	v_mfma_f32_16x16x32_bf16 v[8:11], v[108:111], v[188:191], v[8:11]
	s_setprio 0
	s_setprio 1
	v_mfma_f32_16x16x32_bf16 v[20:23], v[120:123], v[160:163], v[20:23]
	v_mfma_f32_16x16x32_bf16 v[72:75], v[112:115], v[168:171], v[72:75]
	v_mfma_f32_16x16x32_bf16 v[12:15], v[120:123], v[168:171], v[12:15]
	v_mfma_f32_16x16x32_bf16 v[84:87], v[112:115], v[176:179], v[84:87]
	v_mfma_f32_16x16x32_bf16 v[28:31], v[120:123], v[176:179], v[28:31]
	v_mfma_f32_16x16x32_bf16 v[76:79], v[112:115], v[184:187], v[76:79]
	v_mfma_f32_16x16x32_bf16 v[24:27], v[120:123], v[184:187], v[24:27]
	v_mfma_f32_16x16x32_bf16 v[80:83], v[112:115], v[160:163], v[88:91]
	s_setprio 0
	s_setprio 1
	v_mfma_f32_16x16x32_bf16 v[20:23], v[124:127], v[164:167], v[20:23]
	v_mfma_f32_16x16x32_bf16 v[72:75], v[116:119], v[172:175], v[72:75]
	v_mfma_f32_16x16x32_bf16 v[12:15], v[124:127], v[172:175], v[12:15]
	v_mfma_f32_16x16x32_bf16 v[84:87], v[116:119], v[180:183], v[84:87]
	v_mfma_f32_16x16x32_bf16 v[28:31], v[124:127], v[180:183], v[28:31]
	v_mfma_f32_16x16x32_bf16 v[76:79], v[116:119], v[188:191], v[76:79]
	v_mfma_f32_16x16x32_bf16 v[24:27], v[124:127], v[188:191], v[24:27]
	v_mfma_f32_16x16x32_bf16 v[80:83], v[116:119], v[164:167], v[80:83]
	s_setprio 0
	s_barrier
	s_add_i32 s44, 0, 0x18000
	s_add_i32 s45, 0, 0x1c000
	v_add_u32_e32 v108, s44, v214
	v_add_u32_e32 v124, s45, v214
	ds_read_b128 v[88:91], v108
	ds_read_b128 v[96:99], v108 offset:1024
	ds_read_b128 v[104:107], v108 offset:2048
	ds_read_b128 v[108:111], v108 offset:3072
	ds_read_b128 v[112:115], v124
	ds_read_b128 v[116:119], v124 offset:1024
	ds_read_b128 v[120:123], v124 offset:2048
	ds_read_b128 v[124:127], v124 offset:3072
	s_mov_b32 m0, s29
	v_lshl_add_u64 v[196:197], v[194:195], 0, s[74:75]
	ds_read_b128 v[160:163], v215 offset:32768
	ds_read_b128 v[164:167], v215 offset:33792
	ds_read_b128 v[168:171], v215 offset:34816
	ds_read_b128 v[172:175], v215 offset:35840
	ds_read_b128 v[176:179], v215 offset:36864
	ds_read_b128 v[180:183], v215 offset:37888
	ds_read_b128 v[184:187], v215 offset:38912
	ds_read_b128 v[188:191], v215 offset:39936
	global_load_lds_dwordx4 v[196:197], off
	v_lshl_add_u64 v[196:197], v[194:195], 0, s[94:95]
	s_mov_b32 m0, s30
	s_nop 0
	global_load_lds_dwordx4 v[196:197], off
	s_waitcnt vmcnt(8)
	s_waitcnt lgkmcnt(0)
	s_barrier
	s_setprio 1
	v_mfma_f32_16x16x32_bf16 v[156:159], v[88:91], v[160:163], v[156:159]
	v_mfma_f32_16x16x32_bf16 v[60:63], v[104:107], v[160:163], v[60:63]
	v_mfma_f32_16x16x32_bf16 v[148:151], v[88:91], v[168:171], v[148:151]
	v_mfma_f32_16x16x32_bf16 v[52:55], v[104:107], v[168:171], v[52:55]
	v_mfma_f32_16x16x32_bf16 v[152:155], v[88:91], v[176:179], v[152:155]
	v_mfma_f32_16x16x32_bf16 v[56:59], v[104:107], v[176:179], v[56:59]
	v_mfma_f32_16x16x32_bf16 v[136:139], v[88:91], v[184:187], v[136:139]
	v_mfma_f32_16x16x32_bf16 v[48:51], v[104:107], v[184:187], v[48:51]
	s_setprio 0
	s_setprio 1
	v_mfma_f32_16x16x32_bf16 v[156:159], v[96:99], v[164:167], v[156:159]
	v_mfma_f32_16x16x32_bf16 v[60:63], v[108:111], v[164:167], v[60:63]
	v_mfma_f32_16x16x32_bf16 v[148:151], v[96:99], v[172:175], v[148:151]
	v_mfma_f32_16x16x32_bf16 v[52:55], v[108:111], v[172:175], v[52:55]
	v_mfma_f32_16x16x32_bf16 v[152:155], v[96:99], v[180:183], v[152:155]
	v_mfma_f32_16x16x32_bf16 v[56:59], v[108:111], v[180:183], v[56:59]
	v_mfma_f32_16x16x32_bf16 v[136:139], v[96:99], v[188:191], v[136:139]
	v_mfma_f32_16x16x32_bf16 v[48:51], v[108:111], v[188:191], v[48:51]
	s_setprio 0
	s_setprio 1
	v_mfma_f32_16x16x32_bf16 v[144:147], v[112:115], v[160:163], v[144:147]
	v_mfma_f32_16x16x32_bf16 v[36:39], v[120:123], v[160:163], v[36:39]
	v_mfma_f32_16x16x32_bf16 v[128:131], v[112:115], v[168:171], v[128:131]
	v_mfma_f32_16x16x32_bf16 v[32:35], v[120:123], v[168:171], v[32:35]
	v_mfma_f32_16x16x32_bf16 v[140:143], v[112:115], v[176:179], v[140:143]
	v_mfma_f32_16x16x32_bf16 v[44:47], v[120:123], v[176:179], v[44:47]
	v_mfma_f32_16x16x32_bf16 v[132:135], v[112:115], v[184:187], v[132:135]
	v_mfma_f32_16x16x32_bf16 v[40:43], v[120:123], v[184:187], v[40:43]
	s_setprio 0
	s_setprio 1
	v_mfma_f32_16x16x32_bf16 v[144:147], v[116:119], v[164:167], v[144:147]
	v_mfma_f32_16x16x32_bf16 v[36:39], v[124:127], v[164:167], v[36:39]
	v_mfma_f32_16x16x32_bf16 v[128:131], v[116:119], v[172:175], v[128:131]
	v_mfma_f32_16x16x32_bf16 v[32:35], v[124:127], v[172:175], v[32:35]
	v_mfma_f32_16x16x32_bf16 v[140:143], v[116:119], v[180:183], v[140:143]
	v_mfma_f32_16x16x32_bf16 v[44:47], v[124:127], v[180:183], v[44:47]
	v_mfma_f32_16x16x32_bf16 v[132:135], v[116:119], v[188:191], v[132:135]
	v_mfma_f32_16x16x32_bf16 v[40:43], v[124:127], v[188:191], v[40:43]
	s_setprio 0
	s_barrier
; #define PG8_STAGE(bufoff, gbase, voff) do { _Pragma("unroll") for (int _i = 0; _i < 2; ++_i) \
;         __builtin_amdgcn_global_load_lds((const GAS unsigned*)((const GAS char*)(gbase) + (size_t)_i * r64##voff + (vo##voff)), (LAS unsigned*)(lds + (bufoff) + ldsw + _i * 8192), 16, 0, 0); } while (0)
; #define PG8_LDA(dst, b, h) do { _Pragma("unroll") for (int m = 0; m < 4; ++m) _Pragma("unroll") for (int k = 0; k < 2; ++k) dst[m][k] = *(const LAS bf16x8*)(lds + PG8_SA(b, h) + aoff + m * 2048 + k * 1024); } while (0)
; #define PG8_MMA(ai, bj, At, Bt) do { __builtin_amdgcn_s_setprio(1); _Pragma("unroll") for (int m = 0; m < 4; ++m) _Pragma("unroll") for (int n = 0; n < 2; ++n) _Pragma("unroll") for (int k = 0; k < 2; ++k) \
;         acc[ai][bj][m][n] = __builtin_amdgcn_mfma_f32_16x16x32_bf16(Bt[n][k], At[m][k], acc[ai][bj][m][n], 0, 0, 0); __builtin_amdgcn_s_setprio(0); } while (0)
; #define PG8_WAIT_V(n) asm volatile("s_waitcnt vmcnt(" #n ")" ::: "memory")
; #define PG8_WAIT_L(n) asm volatile("s_waitcnt lgkmcnt(" #n ")" ::: "memory")
; #define PG8_BAR __builtin_amdgcn_s_barrier()
; #define PG8_SCHED __builtin_amdgcn_sched_barrier(0)
; template <class Epi, class Map, bool ALIGN_EPI>
; __device__ __forceinline__ void gemm_phase(const int tid, LAS unsigned char* lds, const int lda, const int ldb, const int K, const Map& MP, const StaticOrder& S, const Epi& E) {
;     ...
;             PG8_LDA(At, 1, 1); PG8_STAGE(PG8_SB(1, 0), b3, B); PG8_STAGE(PG8_SB(1, 1), b3 + hstepB, B); PG8_STAGE(PG8_SA(1, 0), a3, A);
;             PG8_WAIT_V(8); PG8_WAIT_L(0); PG8_BAR; PG8_MMA(1, 0, At, B0); PG8_MMA(1, 1, At, B1); PG8_BAR; PG8_SCHED;
;         }
	s_add_i32 s44, s44, s19
	v_lshl_add_u64 v[196:197], v[192:193], 0, s[50:51]
	s_mov_b32 m0, s44
	ds_read_b128 v[160:163], v215 offset:49152
	ds_read_b128 v[164:167], v215 offset:50176
	ds_read_b128 v[168:171], v215 offset:51200
	ds_read_b128 v[172:175], v215 offset:52224
	ds_read_b128 v[176:179], v215 offset:53248
	ds_read_b128 v[180:183], v215 offset:54272
	ds_read_b128 v[184:187], v215 offset:55296
	ds_read_b128 v[188:191], v215 offset:56320
	global_load_lds_dwordx4 v[196:197], off
	v_lshl_add_u64 v[196:197], v[192:193], 0, s[54:55]
	s_add_i32 m0, s44, 0x2000
	s_add_i32 s44, s45, s19
	global_load_lds_dwordx4 v[196:197], off
	v_lshl_add_u64 v[196:197], v[192:193], 0, s[96:97]
	s_mov_b32 m0, s44
	v_lshl_add_u64 v[192:193], v[192:193], 0, s[6:7]
	global_load_lds_dwordx4 v[196:197], off
	s_add_i32 m0, s44, 0x2000
	s_nop 0
	global_load_lds_dwordx4 v[192:193], off
	v_lshl_add_u64 v[192:193], v[194:195], 0, s[50:51]
	s_mov_b32 m0, s39
	s_nop 0
	global_load_lds_dwordx4 v[192:193], off
	v_lshl_add_u64 v[192:193], v[194:195], 0, s[54:55]
	s_mov_b32 m0, s58
	s_nop 0
	global_load_lds_dwordx4 v[192:193], off
	s_waitcnt vmcnt(8)
	s_waitcnt lgkmcnt(0)
	s_barrier
	s_setprio 1
	v_mfma_f32_16x16x32_bf16 v[100:103], v[88:91], v[160:163], v[100:103]
	v_mfma_f32_16x16x32_bf16 v[4:7], v[104:107], v[160:163], v[4:7]
	v_mfma_f32_16x16x32_bf16 v[64:67], v[88:91], v[168:171], v[64:67]
	v_mfma_f32_16x16x32_bf16 v[0:3], v[104:107], v[168:171], v[0:3]
	v_mfma_f32_16x16x32_bf16 v[92:95], v[88:91], v[176:179], v[92:95]
	v_mfma_f32_16x16x32_bf16 v[16:19], v[104:107], v[176:179], v[16:19]
	v_mfma_f32_16x16x32_bf16 v[68:71], v[88:91], v[184:187], v[68:71]
	v_mfma_f32_16x16x32_bf16 v[8:11], v[104:107], v[184:187], v[8:11]
	s_setprio 0
	s_setprio 1
	v_mfma_f32_16x16x32_bf16 v[100:103], v[96:99], v[164:167], v[100:103]
	v_mfma_f32_16x16x32_bf16 v[4:7], v[108:111], v[164:167], v[4:7]
	v_mfma_f32_16x16x32_bf16 v[64:67], v[96:99], v[172:175], v[64:67]
	v_mfma_f32_16x16x32_bf16 v[0:3], v[108:111], v[172:175], v[0:3]
	v_mfma_f32_16x16x32_bf16 v[92:95], v[96:99], v[180:183], v[92:95]
	v_mfma_f32_16x16x32_bf16 v[16:19], v[108:111], v[180:183], v[16:19]
	v_mfma_f32_16x16x32_bf16 v[68:71], v[96:99], v[188:191], v[68:71]
	v_mfma_f32_16x16x32_bf16 v[8:11], v[108:111], v[188:191], v[8:11]
	s_setprio 0
	s_setprio 1
	v_mfma_f32_16x16x32_bf16 v[80:83], v[112:115], v[160:163], v[80:83]
	v_mfma_f32_16x16x32_bf16 v[88:91], v[116:119], v[164:167], v[80:83]
	v_mfma_f32_16x16x32_bf16 v[20:23], v[120:123], v[160:163], v[20:23]
	v_mfma_f32_16x16x32_bf16 v[72:75], v[112:115], v[168:171], v[72:75]
	v_mfma_f32_16x16x32_bf16 v[12:15], v[120:123], v[168:171], v[12:15]
	v_mfma_f32_16x16x32_bf16 v[80:83], v[112:115], v[176:179], v[84:87]
	v_mfma_f32_16x16x32_bf16 v[28:31], v[120:123], v[176:179], v[28:31]
	v_mfma_f32_16x16x32_bf16 v[76:79], v[112:115], v[184:187], v[76:79]
	s_setprio 0
	s_setprio 1
	v_mfma_f32_16x16x32_bf16 v[24:27], v[120:123], v[184:187], v[24:27]
	v_mfma_f32_16x16x32_bf16 v[20:23], v[124:127], v[164:167], v[20:23]
	v_mfma_f32_16x16x32_bf16 v[72:75], v[116:119], v[172:175], v[72:75]
	v_mfma_f32_16x16x32_bf16 v[12:15], v[124:127], v[172:175], v[12:15]
	v_mfma_f32_16x16x32_bf16 v[84:87], v[116:119], v[180:183], v[80:83]
	v_mfma_f32_16x16x32_bf16 v[28:31], v[124:127], v[180:183], v[28:31]
	v_mfma_f32_16x16x32_bf16 v[76:79], v[116:119], v[188:191], v[76:79]
	v_mfma_f32_16x16x32_bf16 v[24:27], v[124:127], v[188:191], v[24:27]
	s_setprio 0
	s_barrier
	s_add_i32 s48, s48, 2
	s_add_u32 s17, s17, 0x100
	s_addc_u32 s21, s21, 0
	s_add_u32 s42, s42, 0x100
	s_addc_u32 s43, s43, 0
	s_cmp_gt_u32 s48, 13
	s_cbranch_scc0 .LBB0_131
	s_and_b64 vcc, exec, s[10:11]
	s_cbranch_vccz .LBB0_134
	s_barrier

; #define PG8_STAGE(bufoff, gbase, voff) do { _Pragma("unroll") for (int _i = 0; _i < 2; ++_i) \
;         __builtin_amdgcn_global_load_lds((const GAS unsigned*)((const GAS char*)(gbase) + (size_t)_i * r64##voff + (vo##voff)), (LAS unsigned*)(lds + (bufoff) + ldsw + _i * 8192), 16, 0, 0); } while (0)
; #define PG8_LDA(dst, b, h) do { _Pragma("unroll") for (int m = 0; m < 4; ++m) _Pragma("unroll") for (int k = 0; k < 2; ++k) dst[m][k] = *(const LAS bf16x8*)(lds + PG8_SA(b, h) + aoff + m * 2048 + k * 1024); } while (0)
; #define PG8_LDB(dst, b, h) do { _Pragma("unroll") for (int n = 0; n < 2; ++n) _Pragma("unroll") for (int k = 0; k < 2; ++k) dst[n][k] = *(const LAS bf16x8*)(lds + PG8_SB(b, h) + boff + n * 2048 + k * 1024); } while (0)
; #define PG8_MMA(ai, bj, At, Bt) do { __builtin_amdgcn_s_setprio(1); _Pragma("unroll") for (int m = 0; m < 4; ++m) _Pragma("unroll") for (int n = 0; n < 2; ++n) _Pragma("unroll") for (int k = 0; k < 2; ++k) \
;         acc[ai][bj][m][n] = __builtin_amdgcn_mfma_f32_16x16x32_bf16(Bt[n][k], At[m][k], acc[ai][bj][m][n], 0, 0, 0); __builtin_amdgcn_s_setprio(0); } while (0)
; #define PG8_WAIT_V(n) asm volatile("s_waitcnt vmcnt(" #n ")" ::: "memory")
; #define PG8_WAIT_L(n) asm volatile("s_waitcnt lgkmcnt(" #n ")" ::: "memory")
; template <class Epi, class Map, bool ALIGN_EPI>
; __device__ __forceinline__ void gemm_phase(const int tid, LAS unsigned char* lds, const int lda, const int ldb, const int K, const Map& MP, const StaticOrder& S, const Epi& E) {
;     ...
;         for (int t = 0; t < nt; t += 2) {
;             const bool last = (t == nt - 2);
;             const char* a1 = cA + (size_t)(t + 1) * kstep;
;             const char* a2 = last ? nA : cA + (size_t)(t + 2) * kstep; const char* b2 = last ? nB : cB + (size_t)(t + 2) * kstep;
;             const char* a3 = a2 + kstep; const char* b3 = b2 + kstep;
;             PG8_LDB(B0, 0, 0); PG8_LDB(B1, 0, 1); PG8_SCHED; PG8_LDA(At, 0, 0); PG8_STAGE(PG8_SA(1, 1), a1 + hstepA, A);
;             PG8_WAIT_V(8); PG8_WAIT_L(0); PG8_BAR; PG8_MMA(0, 0, At, B0); PG8_MMA(0, 1, At, B1); PG8_BAR; PG8_SCHED;
;             PG8_LDA(At, 0, 1); PG8_STAGE(PG8_SB(0, 0), b2, B); PG8_STAGE(PG8_SB(0, 1), b2 + hstepB, B); PG8_STAGE(PG8_SA(0, 0), a2, A);
;             PG8_WAIT_V(8); PG8_WAIT_L(0); PG8_BAR; PG8_MMA(1, 0, At, B0); PG8_MMA(1, 1, At, B1); PG8_BAR; PG8_SCHED;
.LBB0_284:
	s_add_u32 s42, s10, 0xfffc0080
	s_addc_u32 s43, s11, -1
	s_add_i32 s45, 0, 0x10000
	s_cmp_eq_u32 s44, 12
	s_cselect_b32 s43, s53, s43
	s_cselect_b32 s42, s52, s42
	s_cselect_b32 s59, s57, s47
	s_cselect_b32 s58, s56, s23
	s_add_i32 s49, 0, 0x14000
	v_add_u32_e32 v144, s45, v148
	v_add_u32_e32 v162, s49, v148
	ds_read_b128 v[132:135], v144
	ds_read_b128 v[136:139], v144 offset:1024
	ds_read_b128 v[140:143], v144 offset:2048
	ds_read_b128 v[144:147], v144 offset:3072
	ds_read_b128 v[150:153], v162
	ds_read_b128 v[154:157], v162 offset:1024
	ds_read_b128 v[158:161], v162 offset:2048
	ds_read_b128 v[162:165], v162 offset:3072
	v_lshl_add_u64 v[198:199], s[10:11], 0, v[130:131]
	s_add_i32 m0, s19, 0xc000
	ds_read_b128 v[166:169], v149
	ds_read_b128 v[170:173], v149 offset:1024
	ds_read_b128 v[174:177], v149 offset:2048
	ds_read_b128 v[178:181], v149 offset:3072
	ds_read_b128 v[182:185], v149 offset:4096
	ds_read_b128 v[186:189], v149 offset:5120
	ds_read_b128 v[190:193], v149 offset:6144
	ds_read_b128 v[194:197], v149 offset:7168
	global_load_lds_dwordx4 v[198:199], off
	v_lshl_add_u64 v[198:199], v[198:199], 0, s[90:91]
	s_add_i32 m0, s19, 0xe000
	s_nop 0
	global_load_lds_dwordx4 v[198:199], off
	s_waitcnt vmcnt(8)
	s_waitcnt lgkmcnt(0)
	s_barrier
	s_setprio 1
	v_mfma_f32_16x16x32_bf16 v[124:127], v[132:135], v[166:169], v[124:127]
	v_mfma_f32_16x16x32_bf16 v[120:123], v[140:143], v[166:169], v[120:123]
	v_mfma_f32_16x16x32_bf16 v[108:111], v[132:135], v[174:177], v[108:111]
	v_mfma_f32_16x16x32_bf16 v[104:107], v[140:143], v[174:177], v[104:107]
	v_mfma_f32_16x16x32_bf16 v[92:95], v[132:135], v[182:185], v[92:95]
	v_mfma_f32_16x16x32_bf16 v[88:91], v[140:143], v[182:185], v[88:91]
	v_mfma_f32_16x16x32_bf16 v[76:79], v[132:135], v[190:193], v[76:79]
	v_mfma_f32_16x16x32_bf16 v[72:75], v[140:143], v[190:193], v[72:75]
	s_setprio 0
	s_setprio 1
	v_mfma_f32_16x16x32_bf16 v[124:127], v[136:139], v[170:173], v[124:127]
	v_mfma_f32_16x16x32_bf16 v[120:123], v[144:147], v[170:173], v[120:123]
	v_mfma_f32_16x16x32_bf16 v[108:111], v[136:139], v[178:181], v[108:111]
	v_mfma_f32_16x16x32_bf16 v[104:107], v[144:147], v[178:181], v[104:107]
	v_mfma_f32_16x16x32_bf16 v[92:95], v[136:139], v[186:189], v[92:95]
	v_mfma_f32_16x16x32_bf16 v[88:91], v[144:147], v[186:189], v[88:91]
	v_mfma_f32_16x16x32_bf16 v[76:79], v[136:139], v[194:197], v[76:79]
	v_mfma_f32_16x16x32_bf16 v[72:75], v[144:147], v[194:197], v[72:75]
	s_setprio 0
	s_setprio 1
	v_mfma_f32_16x16x32_bf16 v[116:119], v[150:153], v[166:169], v[116:119]
	v_mfma_f32_16x16x32_bf16 v[112:115], v[158:161], v[166:169], v[112:115]
	v_mfma_f32_16x16x32_bf16 v[100:103], v[150:153], v[174:177], v[100:103]
	v_mfma_f32_16x16x32_bf16 v[96:99], v[158:161], v[174:177], v[96:99]
	v_mfma_f32_16x16x32_bf16 v[84:87], v[150:153], v[182:185], v[84:87]
	v_mfma_f32_16x16x32_bf16 v[80:83], v[158:161], v[182:185], v[80:83]
	v_mfma_f32_16x16x32_bf16 v[68:71], v[150:153], v[190:193], v[68:71]
	v_mfma_f32_16x16x32_bf16 v[64:67], v[158:161], v[190:193], v[64:67]
	s_setprio 0
	s_setprio 1
	v_mfma_f32_16x16x32_bf16 v[116:119], v[154:157], v[170:173], v[116:119]
	v_mfma_f32_16x16x32_bf16 v[112:115], v[162:165], v[170:173], v[112:115]
	v_mfma_f32_16x16x32_bf16 v[100:103], v[154:157], v[178:181], v[100:103]
	v_mfma_f32_16x16x32_bf16 v[96:99], v[162:165], v[178:181], v[96:99]
	v_mfma_f32_16x16x32_bf16 v[84:87], v[154:157], v[186:189], v[84:87]
	v_mfma_f32_16x16x32_bf16 v[80:83], v[162:165], v[186:189], v[80:83]
	v_mfma_f32_16x16x32_bf16 v[68:71], v[154:157], v[194:197], v[68:71]
	v_mfma_f32_16x16x32_bf16 v[64:67], v[162:165], v[194:197], v[64:67]
	s_setprio 0
	s_barrier
	s_add_i32 s45, s45, s18
	v_lshl_add_u64 v[198:199], s[58:59], 0, v[128:129]
	s_mov_b32 m0, s45
	ds_read_b128 v[166:169], v149 offset:16384
	ds_read_b128 v[170:173], v149 offset:17408
	ds_read_b128 v[174:177], v149 offset:18432
	ds_read_b128 v[178:181], v149 offset:19456
	ds_read_b128 v[182:185], v149 offset:20480
	ds_read_b128 v[186:189], v149 offset:21504
	ds_read_b128 v[190:193], v149 offset:22528
	ds_read_b128 v[194:197], v149 offset:23552
	global_load_lds_dwordx4 v[198:199], off
	v_lshl_add_u64 v[200:201], v[198:199], 0, s[90:91]
	s_add_i32 m0, s45, 0x2000
	s_add_i32 s45, s49, s18
	global_load_lds_dwordx4 v[200:201], off
	v_lshl_add_u64 v[200:201], v[198:199], 0, s[74:75]
	s_mov_b32 m0, s45
	s_nop 0
	global_load_lds_dwordx4 v[200:201], off
	v_lshl_add_u64 v[200:201], v[198:199], 0, s[94:95]
	s_add_i32 m0, s45, 0x2000
	s_nop 0
	global_load_lds_dwordx4 v[200:201], off
	v_lshl_add_u64 v[200:201], s[42:43], 0, v[130:131]
	s_mov_b32 m0, s19
	v_lshl_add_u64 v[202:203], v[200:201], 0, s[90:91]
	global_load_lds_dwordx4 v[200:201], off
	s_mov_b32 m0, s24
	s_nop 0
	global_load_lds_dwordx4 v[202:203], off
	s_waitcnt vmcnt(8)
	s_waitcnt lgkmcnt(0)
	s_barrier
; #define PG8_STAGE(bufoff, gbase, voff) do { _Pragma("unroll") for (int _i = 0; _i < 2; ++_i) \
;         __builtin_amdgcn_global_load_lds((const GAS unsigned*)((const GAS char*)(gbase) + (size_t)_i * r64##voff + (vo##voff)), (LAS unsigned*)(lds + (bufoff) + ldsw + _i * 8192), 16, 0, 0); } while (0)
; #define PG8_LDA(dst, b, h) do { _Pragma("unroll") for (int m = 0; m < 4; ++m) _Pragma("unroll") for (int k = 0; k < 2; ++k) dst[m][k] = *(const LAS bf16x8*)(lds + PG8_SA(b, h) + aoff + m * 2048 + k * 1024); } while (0)
; #define PG8_LDB(dst, b, h) do { _Pragma("unroll") for (int n = 0; n < 2; ++n) _Pragma("unroll") for (int k = 0; k < 2; ++k) dst[n][k] = *(const LAS bf16x8*)(lds + PG8_SB(b, h) + boff + n * 2048 + k * 1024); } while (0)
; #define PG8_MMA(ai, bj, At, Bt) do { __builtin_amdgcn_s_setprio(1); _Pragma("unroll") for (int m = 0; m < 4; ++m) _Pragma("unroll") for (int n = 0; n < 2; ++n) _Pragma("unroll") for (int k = 0; k < 2; ++k) \
;         acc[ai][bj][m][n] = __builtin_amdgcn_mfma_f32_16x16x32_bf16(Bt[n][k], At[m][k], acc[ai][bj][m][n], 0, 0, 0); __builtin_amdgcn_s_setprio(0); } while (0)
; #define PG8_WAIT_V(n) asm volatile("s_waitcnt vmcnt(" #n ")" ::: "memory")
; #define PG8_WAIT_L(n) asm volatile("s_waitcnt lgkmcnt(" #n ")" ::: "memory")
; #define PG8_BAR __builtin_amdgcn_s_barrier()
; #define PG8_SCHED __builtin_amdgcn_sched_barrier(0)
; template <class Epi, class Map, bool ALIGN_EPI>
; __device__ __forceinline__ void gemm_phase(const int tid, LAS unsigned char* lds, const int lda, const int ldb, const int K, const Map& MP, const StaticOrder& S, const Epi& E) {
;     ...
;             PG8_LDB(B0, 0, 0); PG8_LDB(B1, 0, 1); PG8_SCHED; PG8_LDA(At, 0, 0); PG8_STAGE(PG8_SA(1, 1), a1 + hstepA, A);
;             PG8_WAIT_V(8); PG8_WAIT_L(0); PG8_BAR; PG8_MMA(0, 0, At, B0); PG8_MMA(0, 1, At, B1); PG8_BAR; PG8_SCHED;
;             PG8_LDA(At, 0, 1); PG8_STAGE(PG8_SB(0, 0), b2, B); PG8_STAGE(PG8_SB(0, 1), b2 + hstepB, B); PG8_STAGE(PG8_SA(0, 0), a2, A);
;             PG8_WAIT_V(8); PG8_WAIT_L(0); PG8_BAR; PG8_MMA(1, 0, At, B0); PG8_MMA(1, 1, At, B1); PG8_BAR; PG8_SCHED;
;             PG8_LDB(B0, 1, 0); PG8_LDB(B1, 1, 1); PG8_SCHED; PG8_LDA(At, 1, 0); PG8_STAGE(PG8_SA(0, 1), a2 + hstepA, A);
;             PG8_WAIT_V(8); PG8_WAIT_L(0); PG8_BAR; PG8_MMA(0, 0, At, B0); PG8_MMA(0, 1, At, B1); PG8_BAR; PG8_SCHED;
	s_setprio 1
	v_mfma_f32_16x16x32_bf16 v[60:63], v[132:135], v[166:169], v[60:63]
	v_mfma_f32_16x16x32_bf16 v[56:59], v[140:143], v[166:169], v[56:59]
	v_mfma_f32_16x16x32_bf16 v[44:47], v[132:135], v[174:177], v[44:47]
	v_mfma_f32_16x16x32_bf16 v[40:43], v[140:143], v[174:177], v[40:43]
	v_mfma_f32_16x16x32_bf16 v[28:31], v[132:135], v[182:185], v[28:31]
	v_mfma_f32_16x16x32_bf16 v[24:27], v[140:143], v[182:185], v[24:27]
	v_mfma_f32_16x16x32_bf16 v[12:15], v[132:135], v[190:193], v[12:15]
	v_mfma_f32_16x16x32_bf16 v[8:11], v[140:143], v[190:193], v[8:11]
	s_setprio 0
	s_setprio 1
	v_mfma_f32_16x16x32_bf16 v[60:63], v[136:139], v[170:173], v[60:63]
	v_mfma_f32_16x16x32_bf16 v[56:59], v[144:147], v[170:173], v[56:59]
	v_mfma_f32_16x16x32_bf16 v[44:47], v[136:139], v[178:181], v[44:47]
	v_mfma_f32_16x16x32_bf16 v[40:43], v[144:147], v[178:181], v[40:43]
	v_mfma_f32_16x16x32_bf16 v[28:31], v[136:139], v[186:189], v[28:31]
	v_mfma_f32_16x16x32_bf16 v[24:27], v[144:147], v[186:189], v[24:27]
	v_mfma_f32_16x16x32_bf16 v[12:15], v[136:139], v[194:197], v[12:15]
	v_mfma_f32_16x16x32_bf16 v[8:11], v[144:147], v[194:197], v[8:11]
	s_setprio 0
	s_setprio 1
	v_mfma_f32_16x16x32_bf16 v[52:55], v[150:153], v[166:169], v[52:55]
	v_mfma_f32_16x16x32_bf16 v[48:51], v[158:161], v[166:169], v[48:51]
	v_mfma_f32_16x16x32_bf16 v[36:39], v[150:153], v[174:177], v[36:39]
	v_mfma_f32_16x16x32_bf16 v[32:35], v[158:161], v[174:177], v[32:35]
	v_mfma_f32_16x16x32_bf16 v[20:23], v[150:153], v[182:185], v[20:23]
	v_mfma_f32_16x16x32_bf16 v[16:19], v[158:161], v[182:185], v[16:19]
	v_mfma_f32_16x16x32_bf16 v[4:7], v[150:153], v[190:193], v[4:7]
	v_mfma_f32_16x16x32_bf16 v[0:3], v[158:161], v[190:193], v[0:3]
	s_setprio 0
	s_setprio 1
	v_mfma_f32_16x16x32_bf16 v[52:55], v[154:157], v[170:173], v[52:55]
	v_mfma_f32_16x16x32_bf16 v[48:51], v[162:165], v[170:173], v[48:51]
	v_mfma_f32_16x16x32_bf16 v[36:39], v[154:157], v[178:181], v[36:39]
	v_mfma_f32_16x16x32_bf16 v[32:35], v[162:165], v[178:181], v[32:35]
	v_mfma_f32_16x16x32_bf16 v[20:23], v[154:157], v[186:189], v[20:23]
	v_mfma_f32_16x16x32_bf16 v[16:19], v[162:165], v[186:189], v[16:19]
	v_mfma_f32_16x16x32_bf16 v[4:7], v[154:157], v[194:197], v[4:7]
	v_mfma_f32_16x16x32_bf16 v[0:3], v[162:165], v[194:197], v[0:3]
	s_setprio 0
	s_barrier
	s_add_i32 s42, 0, 0x18000
	s_add_i32 s43, 0, 0x1c000
	v_add_u32_e32 v144, s42, v148
	v_add_u32_e32 v162, s43, v148
	ds_read_b128 v[132:135], v144
	ds_read_b128 v[136:139], v144 offset:1024
	ds_read_b128 v[140:143], v144 offset:2048
	ds_read_b128 v[144:147], v144 offset:3072
	ds_read_b128 v[150:153], v162
	ds_read_b128 v[154:157], v162 offset:1024
	ds_read_b128 v[158:161], v162 offset:2048
	ds_read_b128 v[162:165], v162 offset:3072
	s_mov_b32 m0, s28
	v_lshl_add_u64 v[202:203], v[200:201], 0, s[74:75]
	ds_read_b128 v[166:169], v149 offset:32768
	ds_read_b128 v[170:173], v149 offset:33792
	ds_read_b128 v[174:177], v149 offset:34816
	ds_read_b128 v[178:181], v149 offset:35840
	ds_read_b128 v[182:185], v149 offset:36864
	ds_read_b128 v[186:189], v149 offset:37888
	ds_read_b128 v[190:193], v149 offset:38912
	ds_read_b128 v[194:197], v149 offset:39936
	global_load_lds_dwordx4 v[202:203], off
	v_lshl_add_u64 v[202:203], v[200:201], 0, s[94:95]
	s_mov_b32 m0, s29
	s_nop 0
	global_load_lds_dwordx4 v[202:203], off
	s_waitcnt vmcnt(8)
	s_waitcnt lgkmcnt(0)
	s_barrier
	s_setprio 1
	v_mfma_f32_16x16x32_bf16 v[124:127], v[132:135], v[166:169], v[124:127]
	v_mfma_f32_16x16x32_bf16 v[120:123], v[140:143], v[166:169], v[120:123]
	v_mfma_f32_16x16x32_bf16 v[108:111], v[132:135], v[174:177], v[108:111]
	v_mfma_f32_16x16x32_bf16 v[104:107], v[140:143], v[174:177], v[104:107]
	v_mfma_f32_16x16x32_bf16 v[92:95], v[132:135], v[182:185], v[92:95]
	v_mfma_f32_16x16x32_bf16 v[88:91], v[140:143], v[182:185], v[88:91]
	v_mfma_f32_16x16x32_bf16 v[76:79], v[132:135], v[190:193], v[76:79]
	v_mfma_f32_16x16x32_bf16 v[72:75], v[140:143], v[190:193], v[72:75]
	s_setprio 0
	s_setprio 1
	v_mfma_f32_16x16x32_bf16 v[124:127], v[136:139], v[170:173], v[124:127]
	v_mfma_f32_16x16x32_bf16 v[120:123], v[144:147], v[170:173], v[120:123]
	v_mfma_f32_16x16x32_bf16 v[108:111], v[136:139], v[178:181], v[108:111]
	v_mfma_f32_16x16x32_bf16 v[104:107], v[144:147], v[178:181], v[104:107]
	v_mfma_f32_16x16x32_bf16 v[92:95], v[136:139], v[186:189], v[92:95]
	v_mfma_f32_16x16x32_bf16 v[88:91], v[144:147], v[186:189], v[88:91]
	v_mfma_f32_16x16x32_bf16 v[76:79], v[136:139], v[194:197], v[76:79]
	v_mfma_f32_16x16x32_bf16 v[72:75], v[144:147], v[194:197], v[72:75]
	s_setprio 0
	s_setprio 1
	v_mfma_f32_16x16x32_bf16 v[116:119], v[150:153], v[166:169], v[116:119]
	v_mfma_f32_16x16x32_bf16 v[112:115], v[158:161], v[166:169], v[112:115]
	v_mfma_f32_16x16x32_bf16 v[100:103], v[150:153], v[174:177], v[100:103]
	v_mfma_f32_16x16x32_bf16 v[96:99], v[158:161], v[174:177], v[96:99]
	v_mfma_f32_16x16x32_bf16 v[84:87], v[150:153], v[182:185], v[84:87]
	v_mfma_f32_16x16x32_bf16 v[80:83], v[158:161], v[182:185], v[80:83]
	v_mfma_f32_16x16x32_bf16 v[68:71], v[150:153], v[190:193], v[68:71]
	v_mfma_f32_16x16x32_bf16 v[64:67], v[158:161], v[190:193], v[64:67]
	s_setprio 0
	s_setprio 1
	v_mfma_f32_16x16x32_bf16 v[116:119], v[154:157], v[170:173], v[116:119]
	v_mfma_f32_16x16x32_bf16 v[112:115], v[162:165], v[170:173], v[112:115]
	v_mfma_f32_16x16x32_bf16 v[100:103], v[154:157], v[178:181], v[100:103]
	v_mfma_f32_16x16x32_bf16 v[96:99], v[162:165], v[178:181], v[96:99]
	v_mfma_f32_16x16x32_bf16 v[84:87], v[154:157], v[186:189], v[84:87]
	v_mfma_f32_16x16x32_bf16 v[80:83], v[162:165], v[186:189], v[80:83]
	v_mfma_f32_16x16x32_bf16 v[68:71], v[154:157], v[194:197], v[68:71]
	v_mfma_f32_16x16x32_bf16 v[64:67], v[162:165], v[194:197], v[64:67]
	s_setprio 0
	s_barrier
; #define PG8_STAGE(bufoff, gbase, voff) do { _Pragma("unroll") for (int _i = 0; _i < 2; ++_i) \
;         __builtin_amdgcn_global_load_lds((const GAS unsigned*)((const GAS char*)(gbase) + (size_t)_i * r64##voff + (vo##voff)), (LAS unsigned*)(lds + (bufoff) + ldsw + _i * 8192), 16, 0, 0); } while (0)
; #define PG8_LDA(dst, b, h) do { _Pragma("unroll") for (int m = 0; m < 4; ++m) _Pragma("unroll") for (int k = 0; k < 2; ++k) dst[m][k] = *(const LAS bf16x8*)(lds + PG8_SA(b, h) + aoff + m * 2048 + k * 1024); } while (0)
; #define PG8_MMA(ai, bj, At, Bt) do { __builtin_amdgcn_s_setprio(1); _Pragma("unroll") for (int m = 0; m < 4; ++m) _Pragma("unroll") for (int n = 0; n < 2; ++n) _Pragma("unroll") for (int k = 0; k < 2; ++k) \
;         acc[ai][bj][m][n] = __builtin_amdgcn_mfma_f32_16x16x32_bf16(Bt[n][k], At[m][k], acc[ai][bj][m][n], 0, 0, 0); __builtin_amdgcn_s_setprio(0); } while (0)
; #define PG8_WAIT_V(n) asm volatile("s_waitcnt vmcnt(" #n ")" ::: "memory")
; #define PG8_WAIT_L(n) asm volatile("s_waitcnt lgkmcnt(" #n ")" ::: "memory")
; #define PG8_BAR __builtin_amdgcn_s_barrier()
; #define PG8_SCHED __builtin_amdgcn_sched_barrier(0)
; template <class Epi, class Map, bool ALIGN_EPI>
; __device__ __forceinline__ void gemm_phase(const int tid, LAS unsigned char* lds, const int lda, const int ldb, const int K, const Map& MP, const StaticOrder& S, const Epi& E) {
;     ...
;             PG8_LDA(At, 1, 1); PG8_STAGE(PG8_SB(1, 0), b3, B); PG8_STAGE(PG8_SB(1, 1), b3 + hstepB, B); PG8_STAGE(PG8_SA(1, 0), a3, A);
;             PG8_WAIT_V(8); PG8_WAIT_L(0); PG8_BAR; PG8_MMA(1, 0, At, B0); PG8_MMA(1, 1, At, B1); PG8_BAR; PG8_SCHED;
;         }
	s_add_i32 s42, s42, s18
	v_lshl_add_u64 v[202:203], v[198:199], 0, s[50:51]
	s_mov_b32 m0, s42
	ds_read_b128 v[166:169], v149 offset:49152
	ds_read_b128 v[170:173], v149 offset:50176
	ds_read_b128 v[174:177], v149 offset:51200
	ds_read_b128 v[178:181], v149 offset:52224
	ds_read_b128 v[182:185], v149 offset:53248
	ds_read_b128 v[186:189], v149 offset:54272
	ds_read_b128 v[190:193], v149 offset:55296
	ds_read_b128 v[194:197], v149 offset:56320
	global_load_lds_dwordx4 v[202:203], off
	v_lshl_add_u64 v[202:203], v[198:199], 0, s[54:55]
	s_add_i32 m0, s42, 0x2000
	s_add_i32 s42, s43, s18
	global_load_lds_dwordx4 v[202:203], off
	v_lshl_add_u64 v[202:203], v[198:199], 0, s[96:97]
	s_mov_b32 m0, s42
	v_lshl_add_u64 v[198:199], v[198:199], 0, s[6:7]
	global_load_lds_dwordx4 v[202:203], off
	s_add_i32 m0, s42, 0x2000
	s_nop 0
	global_load_lds_dwordx4 v[198:199], off
	v_lshl_add_u64 v[198:199], v[200:201], 0, s[50:51]
	s_mov_b32 m0, s34
	s_nop 0
	global_load_lds_dwordx4 v[198:199], off
	v_lshl_add_u64 v[198:199], v[200:201], 0, s[54:55]
	s_mov_b32 m0, s35
	s_nop 0
	global_load_lds_dwordx4 v[198:199], off
	s_waitcnt vmcnt(8)
	s_waitcnt lgkmcnt(0)
	s_barrier
	s_setprio 1
	v_mfma_f32_16x16x32_bf16 v[60:63], v[132:135], v[166:169], v[60:63]
	v_mfma_f32_16x16x32_bf16 v[56:59], v[140:143], v[166:169], v[56:59]
	v_mfma_f32_16x16x32_bf16 v[44:47], v[132:135], v[174:177], v[44:47]
	v_mfma_f32_16x16x32_bf16 v[40:43], v[140:143], v[174:177], v[40:43]
	v_mfma_f32_16x16x32_bf16 v[28:31], v[132:135], v[182:185], v[28:31]
	v_mfma_f32_16x16x32_bf16 v[24:27], v[140:143], v[182:185], v[24:27]
	v_mfma_f32_16x16x32_bf16 v[12:15], v[132:135], v[190:193], v[12:15]
	v_mfma_f32_16x16x32_bf16 v[8:11], v[140:143], v[190:193], v[8:11]
	s_setprio 0
	s_setprio 1
	v_mfma_f32_16x16x32_bf16 v[60:63], v[136:139], v[170:173], v[60:63]
	v_mfma_f32_16x16x32_bf16 v[56:59], v[144:147], v[170:173], v[56:59]
	v_mfma_f32_16x16x32_bf16 v[44:47], v[136:139], v[178:181], v[44:47]
	v_mfma_f32_16x16x32_bf16 v[40:43], v[144:147], v[178:181], v[40:43]
	v_mfma_f32_16x16x32_bf16 v[28:31], v[136:139], v[186:189], v[28:31]
	v_mfma_f32_16x16x32_bf16 v[24:27], v[144:147], v[186:189], v[24:27]
	v_mfma_f32_16x16x32_bf16 v[12:15], v[136:139], v[194:197], v[12:15]
	v_mfma_f32_16x16x32_bf16 v[8:11], v[144:147], v[194:197], v[8:11]
	s_setprio 0
	s_setprio 1
	v_mfma_f32_16x16x32_bf16 v[52:55], v[150:153], v[166:169], v[52:55]
	v_mfma_f32_16x16x32_bf16 v[48:51], v[158:161], v[166:169], v[48:51]
	v_mfma_f32_16x16x32_bf16 v[36:39], v[150:153], v[174:177], v[36:39]
	v_mfma_f32_16x16x32_bf16 v[32:35], v[158:161], v[174:177], v[32:35]
	v_mfma_f32_16x16x32_bf16 v[20:23], v[150:153], v[182:185], v[20:23]
	v_mfma_f32_16x16x32_bf16 v[16:19], v[158:161], v[182:185], v[16:19]
	v_mfma_f32_16x16x32_bf16 v[4:7], v[150:153], v[190:193], v[4:7]
	v_mfma_f32_16x16x32_bf16 v[0:3], v[158:161], v[190:193], v[0:3]
	s_setprio 0
	s_setprio 1
	v_mfma_f32_16x16x32_bf16 v[52:55], v[154:157], v[170:173], v[52:55]
	v_mfma_f32_16x16x32_bf16 v[48:51], v[162:165], v[170:173], v[48:51]
	v_mfma_f32_16x16x32_bf16 v[36:39], v[154:157], v[178:181], v[36:39]
	v_mfma_f32_16x16x32_bf16 v[32:35], v[162:165], v[178:181], v[32:35]
	v_mfma_f32_16x16x32_bf16 v[20:23], v[154:157], v[186:189], v[20:23]
	v_mfma_f32_16x16x32_bf16 v[16:19], v[162:165], v[186:189], v[16:19]
	v_mfma_f32_16x16x32_bf16 v[4:7], v[154:157], v[194:197], v[4:7]
	v_mfma_f32_16x16x32_bf16 v[0:3], v[162:165], v[194:197], v[0:3]
	s_setprio 0
	s_barrier
	s_add_i32 s44, s44, 2
	s_add_u32 s23, s23, 0x100
	s_addc_u32 s47, s47, 0
	s_add_u32 s10, s10, 0x100
	s_addc_u32 s11, s11, 0
	s_cmp_gt_u32 s44, 13
	s_cbranch_scc0 .LBB0_284
	s_and_b64 vcc, exec, s[16:17]
	s_cbranch_vccz .LBB0_287
	s_barrier

; #define PG8_STAGE(bufoff, gbase, voff) do { _Pragma("unroll") for (int _i = 0; _i < 2; ++_i) \
;         __builtin_amdgcn_global_load_lds((const GAS unsigned*)((const GAS char*)(gbase) + (size_t)_i * r64##voff + (vo##voff)), (LAS unsigned*)(lds + (bufoff) + ldsw + _i * 8192), 16, 0, 0); } while (0)
; #define PG8_LDA(dst, b, h) do { _Pragma("unroll") for (int m = 0; m < 4; ++m) _Pragma("unroll") for (int k = 0; k < 2; ++k) dst[m][k] = *(const LAS bf16x8*)(lds + PG8_SA(b, h) + aoff + m * 2048 + k * 1024); } while (0)
; #define PG8_LDB(dst, b, h) do { _Pragma("unroll") for (int n = 0; n < 2; ++n) _Pragma("unroll") for (int k = 0; k < 2; ++k) dst[n][k] = *(const LAS bf16x8*)(lds + PG8_SB(b, h) + boff + n * 2048 + k * 1024); } while (0)
; #define PG8_BAR __builtin_amdgcn_s_barrier()
; template <class Epi, class Map, bool ALIGN_EPI>
; __device__ __forceinline__ void gemm_phase(const int tid, LAS unsigned char* lds, const int lda, const int ldb, const int K, const Map& MP, const StaticOrder& S, const Epi& E) {
;     ...
;         for (int t = 0; t < nt; t += 2) {
;             const bool last = (t == nt - 2);
;             const char* a1 = cA + (size_t)(t + 1) * kstep;
;             const char* a2 = last ? nA : cA + (size_t)(t + 2) * kstep; const char* b2 = last ? nB : cB + (size_t)(t + 2) * kstep;
;             const char* a3 = a2 + kstep; const char* b3 = b2 + kstep;
;             PG8_LDB(B0, 0, 0); PG8_LDB(B1, 0, 1); PG8_SCHED; PG8_LDA(At, 0, 0); PG8_STAGE(PG8_SA(1, 1), a1 + hstepA, A);
;             PG8_WAIT_V(8); PG8_WAIT_L(0); PG8_BAR; PG8_MMA(0, 0, At, B0); PG8_MMA(0, 1, At, B1); PG8_BAR; PG8_SCHED;
;             PG8_LDA(At, 0, 1); PG8_STAGE(PG8_SB(0, 0), b2, B); PG8_STAGE(PG8_SB(0, 1), b2 + hstepB, B); PG8_STAGE(PG8_SA(0, 0), a2, A);
;             PG8_WAIT_V(8); PG8_WAIT_L(0); PG8_BAR; PG8_MMA(1, 0, At, B0); PG8_MMA(1, 1, At, B1); PG8_BAR; PG8_SCHED;
;             PG8_LDB(B0, 1, 0); PG8_LDB(B1, 1, 1); PG8_SCHED; PG8_LDA(At, 1, 0); PG8_STAGE(PG8_SA(0, 1), a2 + hstepA, A);
;             PG8_WAIT_V(8); PG8_WAIT_L(0); PG8_BAR; PG8_MMA(0, 0, At, B0); PG8_MMA(0, 1, At, B1); PG8_BAR; PG8_SCHED;
;             PG8_LDA(At, 1, 1); PG8_STAGE(PG8_SB(1, 0), b3, B); PG8_STAGE(PG8_SB(1, 1), b3 + hstepB, B); PG8_STAGE(PG8_SA(1, 0), a3, A);
;             PG8_WAIT_V(8); PG8_WAIT_L(0); PG8_BAR; PG8_MMA(1, 0, At, B0); PG8_MMA(1, 1, At, B1); PG8_BAR; PG8_SCHED;
;         }
.LBB0_673:
	s_add_i32 s52, 0, 0x10000
	s_add_i32 s56, 0, 0x14000
	v_add_u32_e32 v202, s52, v130
	v_add_u32_e32 v203, s56, v130
	ds_read_b128 v[2:5], v202
	ds_read_b128 v[6:9], v202 offset:1024
	ds_read_b128 v[10:13], v202 offset:2048
	ds_read_b128 v[14:17], v202 offset:3072
	ds_read_b128 v[18:21], v203
	ds_read_b128 v[22:25], v203 offset:1024
	ds_read_b128 v[26:29], v203 offset:2048
	ds_read_b128 v[30:33], v203 offset:3072
	v_lshl_add_u64 v[0:1], s[48:49], 0, v[128:129]
	s_mov_b64 s[44:45], 0x10080
	s_add_i32 s48, s19, 0xc000
	v_lshl_add_u64 v[66:67], v[0:1], 0, s[44:45]
	s_mov_b32 m0, s48
	s_mov_b64 s[44:45], 0x18080
	s_add_i32 s17, s19, 0xe000
	ds_read_b128 v[34:37], v131
	ds_read_b128 v[38:41], v131 offset:1024
	ds_read_b128 v[42:45], v131 offset:2048
	ds_read_b128 v[46:49], v131 offset:3072
	ds_read_b128 v[50:53], v131 offset:4096
	ds_read_b128 v[54:57], v131 offset:5120
	ds_read_b128 v[58:61], v131 offset:6144
	ds_read_b128 v[62:65], v131 offset:7168
	global_load_lds_dwordx4 v[66:67], off
	v_lshl_add_u64 v[66:67], v[0:1], 0, s[44:45]
	s_mov_b32 m0, s17
	s_nop 0
	global_load_lds_dwordx4 v[66:67], off
	s_waitcnt vmcnt(8)
	s_waitcnt lgkmcnt(0)
	s_barrier
	s_setprio 1
	v_mfma_f32_16x16x32_bf16 v[66:69], v[2:5], v[34:37], 0
	v_mfma_f32_16x16x32_bf16 v[70:73], v[10:13], v[34:37], 0
	v_mfma_f32_16x16x32_bf16 v[74:77], v[2:5], v[42:45], 0
	v_mfma_f32_16x16x32_bf16 v[78:81], v[10:13], v[42:45], 0
	v_mfma_f32_16x16x32_bf16 v[82:85], v[2:5], v[50:53], 0
	v_mfma_f32_16x16x32_bf16 v[86:89], v[10:13], v[50:53], 0
	v_mfma_f32_16x16x32_bf16 v[90:93], v[2:5], v[58:61], 0
	v_mfma_f32_16x16x32_bf16 v[94:97], v[10:13], v[58:61], 0
	s_setprio 0
	s_setprio 1
	v_mfma_f32_16x16x32_bf16 v[66:69], v[6:9], v[38:41], v[66:69]
	v_mfma_f32_16x16x32_bf16 v[70:73], v[14:17], v[38:41], v[70:73]
	v_mfma_f32_16x16x32_bf16 v[74:77], v[6:9], v[46:49], v[74:77]
	v_mfma_f32_16x16x32_bf16 v[78:81], v[14:17], v[46:49], v[78:81]
	v_mfma_f32_16x16x32_bf16 v[82:85], v[6:9], v[54:57], v[82:85]
	v_mfma_f32_16x16x32_bf16 v[86:89], v[14:17], v[54:57], v[86:89]
	v_mfma_f32_16x16x32_bf16 v[90:93], v[6:9], v[62:65], v[90:93]
	v_mfma_f32_16x16x32_bf16 v[94:97], v[14:17], v[62:65], v[94:97]
	s_setprio 0
	s_setprio 1
	v_mfma_f32_16x16x32_bf16 v[98:101], v[18:21], v[34:37], 0
	v_mfma_f32_16x16x32_bf16 v[34:37], v[26:29], v[34:37], 0
	v_mfma_f32_16x16x32_bf16 v[98:101], v[22:25], v[38:41], v[98:101]
	v_mfma_f32_16x16x32_bf16 v[34:37], v[30:33], v[38:41], v[34:37]
	v_mfma_f32_16x16x32_bf16 v[38:41], v[18:21], v[42:45], 0
	v_mfma_f32_16x16x32_bf16 v[42:45], v[26:29], v[42:45], 0
	v_mfma_f32_16x16x32_bf16 v[38:41], v[22:25], v[46:49], v[38:41]
	v_mfma_f32_16x16x32_bf16 v[42:45], v[30:33], v[46:49], v[42:45]
	s_setprio 0
	s_setprio 1
	v_mfma_f32_16x16x32_bf16 v[46:49], v[18:21], v[50:53], 0
	v_mfma_f32_16x16x32_bf16 v[50:53], v[26:29], v[50:53], 0
	v_mfma_f32_16x16x32_bf16 v[46:49], v[22:25], v[54:57], v[46:49]
	v_mfma_f32_16x16x32_bf16 v[50:53], v[30:33], v[54:57], v[50:53]
	v_mfma_f32_16x16x32_bf16 v[54:57], v[18:21], v[58:61], 0
	v_mfma_f32_16x16x32_bf16 v[58:61], v[26:29], v[58:61], 0
	v_mfma_f32_16x16x32_bf16 v[54:57], v[22:25], v[62:65], v[54:57]
	v_mfma_f32_16x16x32_bf16 v[58:61], v[30:33], v[62:65], v[58:61]
	s_setprio 0
	s_barrier
	v_lshl_add_u64 v[126:127], s[46:47], 0, v[216:217]
	s_mov_b64 s[58:59], 0x100
	s_add_i32 s47, s52, s18
	v_lshl_add_u64 v[136:137], v[126:127], 0, s[58:59]
	s_mov_b32 m0, s47
	s_mov_b64 s[44:45], 0x20100
	ds_read_b128 v[62:65], v131 offset:16384
	ds_read_b128 v[102:105], v131 offset:17408
	ds_read_b128 v[106:109], v131 offset:18432
	ds_read_b128 v[110:113], v131 offset:19456
	ds_read_b128 v[114:117], v131 offset:20480
	ds_read_b128 v[118:121], v131 offset:21504
	ds_read_b128 v[122:125], v131 offset:22528
	ds_read_b128 v[132:135], v131 offset:23552
	global_load_lds_dwordx4 v[136:137], off
	v_lshl_add_u64 v[136:137], v[126:127], 0, s[44:45]
	s_add_i32 s44, s47, 0x2000
	s_mov_b32 m0, s44
	s_mov_b64 s[52:53], 0x40100
	s_add_i32 s45, s56, s18
	global_load_lds_dwordx4 v[136:137], off
	v_lshl_add_u64 v[136:137], v[126:127], 0, s[52:53]
	s_mov_b32 m0, s45
	s_mov_b64 s[52:53], 0x60100
	s_add_i32 s46, s45, 0x2000
	global_load_lds_dwordx4 v[136:137], off
	v_lshl_add_u64 v[136:137], v[126:127], 0, s[52:53]
	s_mov_b32 m0, s46
	s_mov_b64 s[52:53], 0x8100
	global_load_lds_dwordx4 v[136:137], off
	v_lshl_add_u64 v[136:137], v[0:1], 0, s[58:59]
	s_mov_b32 m0, s19
	s_nop 0
	global_load_lds_dwordx4 v[136:137], off
	v_lshl_add_u64 v[136:137], v[0:1], 0, s[52:53]
	s_mov_b32 m0, s24
	s_nop 0
	global_load_lds_dwordx4 v[136:137], off
	s_waitcnt vmcnt(8)
	s_waitcnt lgkmcnt(0)
	s_barrier
; #define PG8_STAGE(bufoff, gbase, voff) do { _Pragma("unroll") for (int _i = 0; _i < 2; ++_i) \
;         __builtin_amdgcn_global_load_lds((const GAS unsigned*)((const GAS char*)(gbase) + (size_t)_i * r64##voff + (vo##voff)), (LAS unsigned*)(lds + (bufoff) + ldsw + _i * 8192), 16, 0, 0); } while (0)
; #define PG8_LDA(dst, b, h) do { _Pragma("unroll") for (int m = 0; m < 4; ++m) _Pragma("unroll") for (int k = 0; k < 2; ++k) dst[m][k] = *(const LAS bf16x8*)(lds + PG8_SA(b, h) + aoff + m * 2048 + k * 1024); } while (0)
; #define PG8_LDB(dst, b, h) do { _Pragma("unroll") for (int n = 0; n < 2; ++n) _Pragma("unroll") for (int k = 0; k < 2; ++k) dst[n][k] = *(const LAS bf16x8*)(lds + PG8_SB(b, h) + boff + n * 2048 + k * 1024); } while (0)
; #define PG8_BAR __builtin_amdgcn_s_barrier()
; template <class Epi, class Map, bool ALIGN_EPI>
; __device__ __forceinline__ void gemm_phase(const int tid, LAS unsigned char* lds, const int lda, const int ldb, const int K, const Map& MP, const StaticOrder& S, const Epi& E) {
;     ...
;         for (int t = 0; t < nt; t += 2) {
;             const bool last = (t == nt - 2);
;             const char* a1 = cA + (size_t)(t + 1) * kstep;
;             const char* a2 = last ? nA : cA + (size_t)(t + 2) * kstep; const char* b2 = last ? nB : cB + (size_t)(t + 2) * kstep;
;             const char* a3 = a2 + kstep; const char* b3 = b2 + kstep;
;             PG8_LDB(B0, 0, 0); PG8_LDB(B1, 0, 1); PG8_SCHED; PG8_LDA(At, 0, 0); PG8_STAGE(PG8_SA(1, 1), a1 + hstepA, A);
;             PG8_WAIT_V(8); PG8_WAIT_L(0); PG8_BAR; PG8_MMA(0, 0, At, B0); PG8_MMA(0, 1, At, B1); PG8_BAR; PG8_SCHED;
;             PG8_LDA(At, 0, 1); PG8_STAGE(PG8_SB(0, 0), b2, B); PG8_STAGE(PG8_SB(0, 1), b2 + hstepB, B); PG8_STAGE(PG8_SA(0, 0), a2, A);
;             PG8_WAIT_V(8); PG8_WAIT_L(0); PG8_BAR; PG8_MMA(1, 0, At, B0); PG8_MMA(1, 1, At, B1); PG8_BAR; PG8_SCHED;
;             PG8_LDB(B0, 1, 0); PG8_LDB(B1, 1, 1); PG8_SCHED; PG8_LDA(At, 1, 0); PG8_STAGE(PG8_SA(0, 1), a2 + hstepA, A);
;             PG8_WAIT_V(8); PG8_WAIT_L(0); PG8_BAR; PG8_MMA(0, 0, At, B0); PG8_MMA(0, 1, At, B1); PG8_BAR; PG8_SCHED;
;             PG8_LDA(At, 1, 1); PG8_STAGE(PG8_SB(1, 0), b3, B); PG8_STAGE(PG8_SB(1, 1), b3 + hstepB, B); PG8_STAGE(PG8_SA(1, 0), a3, A);
;             PG8_WAIT_V(8); PG8_WAIT_L(0); PG8_BAR; PG8_MMA(1, 0, At, B0); PG8_MMA(1, 1, At, B1); PG8_BAR; PG8_SCHED;
;         }
	s_setprio 1
	v_mfma_f32_16x16x32_bf16 v[136:139], v[2:5], v[62:65], 0
	v_mfma_f32_16x16x32_bf16 v[144:147], v[2:5], v[106:109], 0
	v_mfma_f32_16x16x32_bf16 v[152:155], v[2:5], v[114:117], 0
	v_mfma_f32_16x16x32_bf16 v[2:5], v[2:5], v[122:125], 0
	v_mfma_f32_16x16x32_bf16 v[136:139], v[6:9], v[102:105], v[136:139]
	v_mfma_f32_16x16x32_bf16 v[144:147], v[6:9], v[110:113], v[144:147]
	v_mfma_f32_16x16x32_bf16 v[152:155], v[6:9], v[118:121], v[152:155]
	v_mfma_f32_16x16x32_bf16 v[2:5], v[6:9], v[132:135], v[2:5]
	s_setprio 0
	s_setprio 1
	v_mfma_f32_16x16x32_bf16 v[6:9], v[10:13], v[122:125], 0
	v_mfma_f32_16x16x32_bf16 v[140:143], v[10:13], v[62:65], 0
	v_mfma_f32_16x16x32_bf16 v[148:151], v[10:13], v[106:109], 0
	v_mfma_f32_16x16x32_bf16 v[156:159], v[10:13], v[114:117], 0
	v_mfma_f32_16x16x32_bf16 v[6:9], v[14:17], v[132:135], v[6:9]
	v_mfma_f32_16x16x32_bf16 v[140:143], v[14:17], v[102:105], v[140:143]
	v_mfma_f32_16x16x32_bf16 v[148:151], v[14:17], v[110:113], v[148:151]
	v_mfma_f32_16x16x32_bf16 v[156:159], v[14:17], v[118:121], v[156:159]
	s_setprio 0
	s_setprio 1
	v_mfma_f32_16x16x32_bf16 v[10:13], v[18:21], v[62:65], 0
	v_mfma_f32_16x16x32_bf16 v[14:17], v[26:29], v[62:65], 0
	v_mfma_f32_16x16x32_bf16 v[10:13], v[22:25], v[102:105], v[10:13]
	v_mfma_f32_16x16x32_bf16 v[14:17], v[30:33], v[102:105], v[14:17]
	v_mfma_f32_16x16x32_bf16 v[62:65], v[18:21], v[106:109], 0
	v_mfma_f32_16x16x32_bf16 v[102:105], v[26:29], v[106:109], 0
	v_mfma_f32_16x16x32_bf16 v[106:109], v[18:21], v[114:117], 0
	v_mfma_f32_16x16x32_bf16 v[18:21], v[18:21], v[122:125], 0
	s_setprio 0
	s_setprio 1
	v_mfma_f32_16x16x32_bf16 v[62:65], v[22:25], v[110:113], v[62:65]
	v_mfma_f32_16x16x32_bf16 v[102:105], v[30:33], v[110:113], v[102:105]
	v_mfma_f32_16x16x32_bf16 v[106:109], v[22:25], v[118:121], v[106:109]
	v_mfma_f32_16x16x32_bf16 v[110:113], v[26:29], v[114:117], 0
	v_mfma_f32_16x16x32_bf16 v[18:21], v[22:25], v[132:135], v[18:21]
	v_mfma_f32_16x16x32_bf16 v[22:25], v[26:29], v[122:125], 0
	v_mfma_f32_16x16x32_bf16 v[110:113], v[30:33], v[118:121], v[110:113]
	v_mfma_f32_16x16x32_bf16 v[22:25], v[30:33], v[132:135], v[22:25]
	s_setprio 0
	s_barrier
	s_add_i32 s56, 0, 0x18000
	s_add_i32 s57, 0, 0x1c000
	v_add_u32_e32 v218, s56, v130
	v_add_u32_e32 v219, s57, v130
	ds_read_b128 v[26:29], v218
	ds_read_b128 v[30:33], v218 offset:1024
	ds_read_b128 v[114:117], v218 offset:2048
	ds_read_b128 v[118:121], v218 offset:3072
	ds_read_b128 v[122:125], v219
	ds_read_b128 v[132:135], v219 offset:1024
	ds_read_b128 v[160:163], v219 offset:2048
	ds_read_b128 v[164:167], v219 offset:3072
	s_mov_b64 s[52:53], 0x10100
	s_mov_b32 m0, s28
	v_lshl_add_u64 v[200:201], v[0:1], 0, s[52:53]
	s_mov_b64 s[52:53], 0x18100
	ds_read_b128 v[168:171], v131 offset:32768
	ds_read_b128 v[172:175], v131 offset:33792
	ds_read_b128 v[176:179], v131 offset:34816
	ds_read_b128 v[180:183], v131 offset:35840
	ds_read_b128 v[184:187], v131 offset:36864
	ds_read_b128 v[188:191], v131 offset:37888
	ds_read_b128 v[192:195], v131 offset:38912
	ds_read_b128 v[196:199], v131 offset:39936
	global_load_lds_dwordx4 v[200:201], off
	v_lshl_add_u64 v[200:201], v[0:1], 0, s[52:53]
	s_mov_b32 m0, s29
	s_nop 0
	global_load_lds_dwordx4 v[200:201], off
	s_waitcnt vmcnt(8)
	s_waitcnt lgkmcnt(0)
	s_barrier
	s_setprio 1
	v_mfma_f32_16x16x32_bf16 v[66:69], v[26:29], v[168:171], v[66:69]
	v_mfma_f32_16x16x32_bf16 v[70:73], v[114:117], v[168:171], v[70:73]
	v_mfma_f32_16x16x32_bf16 v[74:77], v[26:29], v[176:179], v[74:77]
	v_mfma_f32_16x16x32_bf16 v[78:81], v[114:117], v[176:179], v[78:81]
	v_mfma_f32_16x16x32_bf16 v[82:85], v[26:29], v[184:187], v[82:85]
	v_mfma_f32_16x16x32_bf16 v[86:89], v[114:117], v[184:187], v[86:89]
	v_mfma_f32_16x16x32_bf16 v[90:93], v[26:29], v[192:195], v[90:93]
	v_mfma_f32_16x16x32_bf16 v[94:97], v[114:117], v[192:195], v[94:97]
	s_setprio 0
	s_setprio 1
	v_mfma_f32_16x16x32_bf16 v[66:69], v[30:33], v[172:175], v[66:69]
	v_mfma_f32_16x16x32_bf16 v[70:73], v[118:121], v[172:175], v[70:73]
	v_mfma_f32_16x16x32_bf16 v[74:77], v[30:33], v[180:183], v[74:77]
	v_mfma_f32_16x16x32_bf16 v[78:81], v[118:121], v[180:183], v[78:81]
	v_mfma_f32_16x16x32_bf16 v[82:85], v[30:33], v[188:191], v[82:85]
	v_mfma_f32_16x16x32_bf16 v[86:89], v[118:121], v[188:191], v[86:89]
	v_mfma_f32_16x16x32_bf16 v[90:93], v[30:33], v[196:199], v[90:93]
	v_mfma_f32_16x16x32_bf16 v[94:97], v[118:121], v[196:199], v[94:97]
	s_setprio 0
	s_setprio 1
	v_mfma_f32_16x16x32_bf16 v[98:101], v[122:125], v[168:171], v[98:101]
	v_mfma_f32_16x16x32_bf16 v[34:37], v[160:163], v[168:171], v[34:37]
	v_mfma_f32_16x16x32_bf16 v[38:41], v[122:125], v[176:179], v[38:41]
	v_mfma_f32_16x16x32_bf16 v[42:45], v[160:163], v[176:179], v[42:45]
	v_mfma_f32_16x16x32_bf16 v[46:49], v[122:125], v[184:187], v[46:49]
	v_mfma_f32_16x16x32_bf16 v[50:53], v[160:163], v[184:187], v[50:53]
	v_mfma_f32_16x16x32_bf16 v[54:57], v[122:125], v[192:195], v[54:57]
	v_mfma_f32_16x16x32_bf16 v[58:61], v[160:163], v[192:195], v[58:61]
	s_setprio 0
	s_setprio 1
	v_mfma_f32_16x16x32_bf16 v[98:101], v[132:135], v[172:175], v[98:101]
	v_mfma_f32_16x16x32_bf16 v[34:37], v[164:167], v[172:175], v[34:37]
	v_mfma_f32_16x16x32_bf16 v[38:41], v[132:135], v[180:183], v[38:41]
	v_mfma_f32_16x16x32_bf16 v[42:45], v[164:167], v[180:183], v[42:45]
	v_mfma_f32_16x16x32_bf16 v[46:49], v[132:135], v[188:191], v[46:49]
	v_mfma_f32_16x16x32_bf16 v[50:53], v[164:167], v[188:191], v[50:53]
	v_mfma_f32_16x16x32_bf16 v[54:57], v[132:135], v[196:199], v[54:57]
	v_mfma_f32_16x16x32_bf16 v[58:61], v[164:167], v[196:199], v[58:61]
	s_setprio 0
	s_barrier
; #define PG8_STAGE(bufoff, gbase, voff) do { _Pragma("unroll") for (int _i = 0; _i < 2; ++_i) \
;         __builtin_amdgcn_global_load_lds((const GAS unsigned*)((const GAS char*)(gbase) + (size_t)_i * r64##voff + (vo##voff)), (LAS unsigned*)(lds + (bufoff) + ldsw + _i * 8192), 16, 0, 0); } while (0)
; #define PG8_LDA(dst, b, h) do { _Pragma("unroll") for (int m = 0; m < 4; ++m) _Pragma("unroll") for (int k = 0; k < 2; ++k) dst[m][k] = *(const LAS bf16x8*)(lds + PG8_SA(b, h) + aoff + m * 2048 + k * 1024); } while (0)
; #define PG8_LDB(dst, b, h) do { _Pragma("unroll") for (int n = 0; n < 2; ++n) _Pragma("unroll") for (int k = 0; k < 2; ++k) dst[n][k] = *(const LAS bf16x8*)(lds + PG8_SB(b, h) + boff + n * 2048 + k * 1024); } while (0)
; #define PG8_BAR __builtin_amdgcn_s_barrier()
; template <class Epi, class Map, bool ALIGN_EPI>
; __device__ __forceinline__ void gemm_phase(const int tid, LAS unsigned char* lds, const int lda, const int ldb, const int K, const Map& MP, const StaticOrder& S, const Epi& E) {
;     ...
;         for (int t = 0; t < nt; t += 2) {
;             const bool last = (t == nt - 2);
;             const char* a1 = cA + (size_t)(t + 1) * kstep;
;             const char* a2 = last ? nA : cA + (size_t)(t + 2) * kstep; const char* b2 = last ? nB : cB + (size_t)(t + 2) * kstep;
;             const char* a3 = a2 + kstep; const char* b3 = b2 + kstep;
;             PG8_LDB(B0, 0, 0); PG8_LDB(B1, 0, 1); PG8_SCHED; PG8_LDA(At, 0, 0); PG8_STAGE(PG8_SA(1, 1), a1 + hstepA, A);
;             PG8_WAIT_V(8); PG8_WAIT_L(0); PG8_BAR; PG8_MMA(0, 0, At, B0); PG8_MMA(0, 1, At, B1); PG8_BAR; PG8_SCHED;
;             PG8_LDA(At, 0, 1); PG8_STAGE(PG8_SB(0, 0), b2, B); PG8_STAGE(PG8_SB(0, 1), b2 + hstepB, B); PG8_STAGE(PG8_SA(0, 0), a2, A);
;             PG8_WAIT_V(8); PG8_WAIT_L(0); PG8_BAR; PG8_MMA(1, 0, At, B0); PG8_MMA(1, 1, At, B1); PG8_BAR; PG8_SCHED;
;             PG8_LDB(B0, 1, 0); PG8_LDB(B1, 1, 1); PG8_SCHED; PG8_LDA(At, 1, 0); PG8_STAGE(PG8_SA(0, 1), a2 + hstepA, A);
;             PG8_WAIT_V(8); PG8_WAIT_L(0); PG8_BAR; PG8_MMA(0, 0, At, B0); PG8_MMA(0, 1, At, B1); PG8_BAR; PG8_SCHED;
;             PG8_LDA(At, 1, 1); PG8_STAGE(PG8_SB(1, 0), b3, B); PG8_STAGE(PG8_SB(1, 1), b3 + hstepB, B); PG8_STAGE(PG8_SA(1, 0), a3, A);
;             PG8_WAIT_V(8); PG8_WAIT_L(0); PG8_BAR; PG8_MMA(1, 0, At, B0); PG8_MMA(1, 1, At, B1); PG8_BAR; PG8_SCHED;
;         }
	s_mov_b64 s[62:63], 0x180
	s_add_i32 s56, s56, s18
	v_lshl_add_u64 v[200:201], v[126:127], 0, s[62:63]
	s_mov_b32 m0, s56
	s_mov_b64 s[52:53], 0x20180
	s_add_i32 s49, s56, 0x2000
	ds_read_b128 v[168:171], v131 offset:49152
	ds_read_b128 v[172:175], v131 offset:50176
	ds_read_b128 v[176:179], v131 offset:51200
	ds_read_b128 v[180:183], v131 offset:52224
	ds_read_b128 v[184:187], v131 offset:53248
	ds_read_b128 v[188:191], v131 offset:54272
	ds_read_b128 v[192:195], v131 offset:55296
	ds_read_b128 v[196:199], v131 offset:56320
	global_load_lds_dwordx4 v[200:201], off
	v_lshl_add_u64 v[200:201], v[126:127], 0, s[52:53]
	s_mov_b32 m0, s49
	s_mov_b64 s[52:53], 0x40180
	global_load_lds_dwordx4 v[200:201], off
	v_lshl_add_u64 v[200:201], v[126:127], 0, s[52:53]
	s_add_i32 s52, s57, s18
	s_mov_b32 m0, s52
	s_mov_b64 s[58:59], 0x60180
	s_add_i32 s53, s52, 0x2000
	global_load_lds_dwordx4 v[200:201], off
	v_lshl_add_u64 v[126:127], v[126:127], 0, s[58:59]
	s_mov_b32 m0, s53
	s_mov_b64 s[58:59], 0x8180
	global_load_lds_dwordx4 v[126:127], off
	v_lshl_add_u64 v[126:127], v[0:1], 0, s[62:63]
	s_mov_b32 m0, s33
	s_nop 0
	global_load_lds_dwordx4 v[126:127], off
	v_lshl_add_u64 v[126:127], v[0:1], 0, s[58:59]
	s_mov_b32 m0, s34
	s_nop 0
	global_load_lds_dwordx4 v[126:127], off
	s_waitcnt vmcnt(8)
	s_waitcnt lgkmcnt(0)
	s_barrier
	s_setprio 1
	v_mfma_f32_16x16x32_bf16 v[2:5], v[26:29], v[192:195], v[2:5]
	v_mfma_f32_16x16x32_bf16 v[6:9], v[114:117], v[192:195], v[6:9]
	v_mfma_f32_16x16x32_bf16 v[136:139], v[26:29], v[168:171], v[136:139]
	v_mfma_f32_16x16x32_bf16 v[140:143], v[114:117], v[168:171], v[140:143]
	v_mfma_f32_16x16x32_bf16 v[144:147], v[26:29], v[176:179], v[144:147]
	v_mfma_f32_16x16x32_bf16 v[148:151], v[114:117], v[176:179], v[148:151]
	v_mfma_f32_16x16x32_bf16 v[152:155], v[26:29], v[184:187], v[152:155]
	v_mfma_f32_16x16x32_bf16 v[156:159], v[114:117], v[184:187], v[156:159]
	s_setprio 0
	s_setprio 1
	v_mfma_f32_16x16x32_bf16 v[2:5], v[30:33], v[196:199], v[2:5]
	v_mfma_f32_16x16x32_bf16 v[6:9], v[118:121], v[196:199], v[6:9]
	v_mfma_f32_16x16x32_bf16 v[136:139], v[30:33], v[172:175], v[136:139]
	v_mfma_f32_16x16x32_bf16 v[140:143], v[118:121], v[172:175], v[140:143]
	v_mfma_f32_16x16x32_bf16 v[144:147], v[30:33], v[180:183], v[144:147]
	v_mfma_f32_16x16x32_bf16 v[148:151], v[118:121], v[180:183], v[148:151]
	v_mfma_f32_16x16x32_bf16 v[152:155], v[30:33], v[188:191], v[152:155]
	v_mfma_f32_16x16x32_bf16 v[156:159], v[118:121], v[188:191], v[156:159]
	s_setprio 0
	s_setprio 1
	v_mfma_f32_16x16x32_bf16 v[10:13], v[122:125], v[168:171], v[10:13]
	v_mfma_f32_16x16x32_bf16 v[14:17], v[160:163], v[168:171], v[14:17]
	v_mfma_f32_16x16x32_bf16 v[26:29], v[122:125], v[176:179], v[62:65]
	v_mfma_f32_16x16x32_bf16 v[30:33], v[160:163], v[176:179], v[102:105]
	v_mfma_f32_16x16x32_bf16 v[62:65], v[122:125], v[184:187], v[106:109]
	v_mfma_f32_16x16x32_bf16 v[102:105], v[160:163], v[184:187], v[110:113]
	v_mfma_f32_16x16x32_bf16 v[18:21], v[122:125], v[192:195], v[18:21]
	v_mfma_f32_16x16x32_bf16 v[22:25], v[160:163], v[192:195], v[22:25]
	s_setprio 0
	s_setprio 1
	v_mfma_f32_16x16x32_bf16 v[10:13], v[132:135], v[172:175], v[10:13]
	v_mfma_f32_16x16x32_bf16 v[14:17], v[164:167], v[172:175], v[14:17]
	v_mfma_f32_16x16x32_bf16 v[26:29], v[132:135], v[180:183], v[26:29]
	v_mfma_f32_16x16x32_bf16 v[30:33], v[164:167], v[180:183], v[30:33]
	v_mfma_f32_16x16x32_bf16 v[62:65], v[132:135], v[188:191], v[62:65]
	v_mfma_f32_16x16x32_bf16 v[102:105], v[164:167], v[188:191], v[102:105]
	v_mfma_f32_16x16x32_bf16 v[18:21], v[132:135], v[196:199], v[18:21]
	v_mfma_f32_16x16x32_bf16 v[22:25], v[164:167], v[196:199], v[22:25]
	s_setprio 0
	s_barrier
	ds_read_b128 v[106:109], v202
	ds_read_b128 v[110:113], v202 offset:1024
	ds_read_b128 v[114:117], v202 offset:2048
	ds_read_b128 v[118:121], v202 offset:3072
	ds_read_b128 v[122:125], v203
	ds_read_b128 v[132:135], v203 offset:1024
	ds_read_b128 v[160:163], v203 offset:2048
	ds_read_b128 v[164:167], v203 offset:3072
	s_mov_b64 s[58:59], 0x10180
	s_mov_b32 m0, s48
	v_lshl_add_u64 v[126:127], v[0:1], 0, s[58:59]
	s_mov_b64 s[58:59], 0x18180
	ds_read_b128 v[168:171], v131
	ds_read_b128 v[172:175], v131 offset:1024
	ds_read_b128 v[176:179], v131 offset:2048
	ds_read_b128 v[180:183], v131 offset:3072
	ds_read_b128 v[184:187], v131 offset:4096
	ds_read_b128 v[188:191], v131 offset:5120
	ds_read_b128 v[192:195], v131 offset:6144
	ds_read_b128 v[196:199], v131 offset:7168
	global_load_lds_dwordx4 v[126:127], off
	v_lshl_add_u64 v[0:1], v[0:1], 0, s[58:59]
	s_mov_b32 m0, s17
	s_nop 0
	global_load_lds_dwordx4 v[0:1], off
	s_waitcnt vmcnt(8)
	s_waitcnt lgkmcnt(0)
	s_barrier
; #define PG8_STAGE(bufoff, gbase, voff) do { _Pragma("unroll") for (int _i = 0; _i < 2; ++_i) \
;         __builtin_amdgcn_global_load_lds((const GAS unsigned*)((const GAS char*)(gbase) + (size_t)_i * r64##voff + (vo##voff)), (LAS unsigned*)(lds + (bufoff) + ldsw + _i * 8192), 16, 0, 0); } while (0)
; #define PG8_LDA(dst, b, h) do { _Pragma("unroll") for (int m = 0; m < 4; ++m) _Pragma("unroll") for (int k = 0; k < 2; ++k) dst[m][k] = *(const LAS bf16x8*)(lds + PG8_SA(b, h) + aoff + m * 2048 + k * 1024); } while (0)
; #define PG8_LDB(dst, b, h) do { _Pragma("unroll") for (int n = 0; n < 2; ++n) _Pragma("unroll") for (int k = 0; k < 2; ++k) dst[n][k] = *(const LAS bf16x8*)(lds + PG8_SB(b, h) + boff + n * 2048 + k * 1024); } while (0)
; #define PG8_BAR __builtin_amdgcn_s_barrier()
; template <class Epi, class Map, bool ALIGN_EPI>
; __device__ __forceinline__ void gemm_phase(const int tid, LAS unsigned char* lds, const int lda, const int ldb, const int K, const Map& MP, const StaticOrder& S, const Epi& E) {
;     ...
;         for (int t = 0; t < nt; t += 2) {
;             const bool last = (t == nt - 2);
;             const char* a1 = cA + (size_t)(t + 1) * kstep;
;             const char* a2 = last ? nA : cA + (size_t)(t + 2) * kstep; const char* b2 = last ? nB : cB + (size_t)(t + 2) * kstep;
;             const char* a3 = a2 + kstep; const char* b3 = b2 + kstep;
;             PG8_LDB(B0, 0, 0); PG8_LDB(B1, 0, 1); PG8_SCHED; PG8_LDA(At, 0, 0); PG8_STAGE(PG8_SA(1, 1), a1 + hstepA, A);
;             PG8_WAIT_V(8); PG8_WAIT_L(0); PG8_BAR; PG8_MMA(0, 0, At, B0); PG8_MMA(0, 1, At, B1); PG8_BAR; PG8_SCHED;
;             PG8_LDA(At, 0, 1); PG8_STAGE(PG8_SB(0, 0), b2, B); PG8_STAGE(PG8_SB(0, 1), b2 + hstepB, B); PG8_STAGE(PG8_SA(0, 0), a2, A);
;             PG8_WAIT_V(8); PG8_WAIT_L(0); PG8_BAR; PG8_MMA(1, 0, At, B0); PG8_MMA(1, 1, At, B1); PG8_BAR; PG8_SCHED;
;             PG8_LDB(B0, 1, 0); PG8_LDB(B1, 1, 1); PG8_SCHED; PG8_LDA(At, 1, 0); PG8_STAGE(PG8_SA(0, 1), a2 + hstepA, A);
;             PG8_WAIT_V(8); PG8_WAIT_L(0); PG8_BAR; PG8_MMA(0, 0, At, B0); PG8_MMA(0, 1, At, B1); PG8_BAR; PG8_SCHED;
;             PG8_LDA(At, 1, 1); PG8_STAGE(PG8_SB(1, 0), b3, B); PG8_STAGE(PG8_SB(1, 1), b3 + hstepB, B); PG8_STAGE(PG8_SA(1, 0), a3, A);
;             PG8_WAIT_V(8); PG8_WAIT_L(0); PG8_BAR; PG8_MMA(1, 0, At, B0); PG8_MMA(1, 1, At, B1); PG8_BAR; PG8_SCHED;
;         }
	s_setprio 1
	v_mfma_f32_16x16x32_bf16 v[66:69], v[106:109], v[168:171], v[66:69]
	v_mfma_f32_16x16x32_bf16 v[70:73], v[114:117], v[168:171], v[70:73]
	v_mfma_f32_16x16x32_bf16 v[74:77], v[106:109], v[176:179], v[74:77]
	v_mfma_f32_16x16x32_bf16 v[78:81], v[114:117], v[176:179], v[78:81]
	v_mfma_f32_16x16x32_bf16 v[82:85], v[106:109], v[184:187], v[82:85]
	v_mfma_f32_16x16x32_bf16 v[86:89], v[114:117], v[184:187], v[86:89]
	v_mfma_f32_16x16x32_bf16 v[90:93], v[106:109], v[192:195], v[90:93]
	v_mfma_f32_16x16x32_bf16 v[66:69], v[110:113], v[172:175], v[66:69]
	s_setprio 0
	s_setprio 1
	v_mfma_f32_16x16x32_bf16 v[70:73], v[118:121], v[172:175], v[70:73]
	v_mfma_f32_16x16x32_bf16 v[74:77], v[110:113], v[180:183], v[74:77]
	v_mfma_f32_16x16x32_bf16 v[78:81], v[118:121], v[180:183], v[78:81]
	v_mfma_f32_16x16x32_bf16 v[82:85], v[110:113], v[188:191], v[82:85]
	v_mfma_f32_16x16x32_bf16 v[86:89], v[118:121], v[188:191], v[86:89]
	v_mfma_f32_16x16x32_bf16 v[200:203], v[110:113], v[196:199], v[90:93]
	v_mfma_f32_16x16x32_bf16 v[90:93], v[114:117], v[192:195], v[94:97]
	v_mfma_f32_16x16x32_bf16 v[204:207], v[118:121], v[196:199], v[90:93]
	s_setprio 0
	s_setprio 1
	v_mfma_f32_16x16x32_bf16 v[90:93], v[122:125], v[168:171], v[98:101]
	v_mfma_f32_16x16x32_bf16 v[34:37], v[160:163], v[168:171], v[34:37]
	v_mfma_f32_16x16x32_bf16 v[38:41], v[122:125], v[176:179], v[38:41]
	v_mfma_f32_16x16x32_bf16 v[42:45], v[160:163], v[176:179], v[42:45]
	v_mfma_f32_16x16x32_bf16 v[46:49], v[122:125], v[184:187], v[46:49]
	v_mfma_f32_16x16x32_bf16 v[50:53], v[160:163], v[184:187], v[50:53]
	v_mfma_f32_16x16x32_bf16 v[54:57], v[122:125], v[192:195], v[54:57]
	v_mfma_f32_16x16x32_bf16 v[96:99], v[132:135], v[172:175], v[90:93]
	s_setprio 0
	s_setprio 1
	v_mfma_f32_16x16x32_bf16 v[34:37], v[164:167], v[172:175], v[34:37]
	v_mfma_f32_16x16x32_bf16 v[38:41], v[132:135], v[180:183], v[38:41]
	v_mfma_f32_16x16x32_bf16 v[42:45], v[164:167], v[180:183], v[42:45]
	v_mfma_f32_16x16x32_bf16 v[46:49], v[132:135], v[188:191], v[46:49]
	v_mfma_f32_16x16x32_bf16 v[50:53], v[164:167], v[188:191], v[50:53]
	v_mfma_f32_16x16x32_bf16 v[54:57], v[132:135], v[196:199], v[54:57]
	v_mfma_f32_16x16x32_bf16 v[58:61], v[160:163], v[192:195], v[58:61]
	v_mfma_f32_16x16x32_bf16 v[168:171], v[164:167], v[196:199], v[58:61]
	s_setprio 0
	s_barrier
	s_mov_b32 m0, s47
	v_lshl_add_u64 v[230:231], s[22:23], 0, v[216:217]
	s_nop 2
	ds_read_b128 v[58:61], v131 offset:16384
	ds_read_b128 v[90:93], v131 offset:17408
	ds_read_b128 v[172:175], v131 offset:18432
	ds_read_b128 v[176:179], v131 offset:19456
	ds_read_b128 v[180:183], v131 offset:20480
	ds_read_b128 v[184:187], v131 offset:21504
	ds_read_b128 v[188:191], v131 offset:22528
	ds_read_b128 v[192:195], v131 offset:23552
	global_load_lds_dwordx4 v[230:231], off
	v_lshl_add_u64 v[0:1], v[230:231], 0, s[90:91]
	s_mov_b32 m0, s44
	v_lshl_add_u64 v[222:223], s[20:21], 0, v[128:129]
	global_load_lds_dwordx4 v[0:1], off
	v_lshl_add_u64 v[0:1], v[230:231], 0, s[74:75]
	s_mov_b32 m0, s45
	s_mov_b64 s[44:45], 0x8000
	global_load_lds_dwordx4 v[0:1], off
	v_lshl_add_u64 v[0:1], v[230:231], 0, s[94:95]
	s_mov_b32 m0, s46
	s_nop 0
	global_load_lds_dwordx4 v[0:1], off
	s_mov_b32 m0, s19
	v_lshl_add_u64 v[0:1], v[222:223], 0, s[44:45]
	global_load_lds_dwordx4 v[222:223], off
	s_mov_b32 m0, s24
	s_nop 0
	global_load_lds_dwordx4 v[0:1], off
	s_waitcnt vmcnt(8)
	s_waitcnt lgkmcnt(0)
	s_barrier
	s_setprio 1
	v_mfma_f32_16x16x32_bf16 v[0:3], v[106:109], v[188:191], v[2:5]
	v_mfma_f32_16x16x32_bf16 v[4:7], v[114:117], v[188:191], v[6:9]
	v_mfma_f32_16x16x32_bf16 v[136:139], v[106:109], v[58:61], v[136:139]
	v_mfma_f32_16x16x32_bf16 v[140:143], v[114:117], v[58:61], v[140:143]
	v_mfma_f32_16x16x32_bf16 v[144:147], v[106:109], v[172:175], v[144:147]
	v_mfma_f32_16x16x32_bf16 v[148:151], v[114:117], v[172:175], v[148:151]
	v_mfma_f32_16x16x32_bf16 v[152:155], v[106:109], v[180:183], v[152:155]
	v_mfma_f32_16x16x32_bf16 v[156:159], v[114:117], v[180:183], v[156:159]
	s_setprio 0
	s_setprio 1
	v_mfma_f32_16x16x32_bf16 v[0:3], v[110:113], v[192:195], v[0:3]
	v_mfma_f32_16x16x32_bf16 v[4:7], v[118:121], v[192:195], v[4:7]
	v_mfma_f32_16x16x32_bf16 v[136:139], v[110:113], v[90:93], v[136:139]
	v_mfma_f32_16x16x32_bf16 v[140:143], v[118:121], v[90:93], v[140:143]
	v_mfma_f32_16x16x32_bf16 v[144:147], v[110:113], v[176:179], v[144:147]
	v_mfma_f32_16x16x32_bf16 v[148:151], v[118:121], v[176:179], v[148:151]
	v_mfma_f32_16x16x32_bf16 v[152:155], v[110:113], v[184:187], v[152:155]
	v_mfma_f32_16x16x32_bf16 v[156:159], v[118:121], v[184:187], v[156:159]
	s_setprio 0
	s_setprio 1
	v_mfma_f32_16x16x32_bf16 v[8:11], v[122:125], v[58:61], v[10:13]
	v_mfma_f32_16x16x32_bf16 v[196:199], v[132:135], v[90:93], v[8:11]
	v_mfma_f32_16x16x32_bf16 v[8:11], v[160:163], v[58:61], v[14:17]
	v_mfma_f32_16x16x32_bf16 v[208:211], v[164:167], v[90:93], v[8:11]
	v_mfma_f32_16x16x32_bf16 v[8:11], v[122:125], v[172:175], v[26:29]
	v_mfma_f32_16x16x32_bf16 v[212:215], v[132:135], v[176:179], v[8:11]
	v_mfma_f32_16x16x32_bf16 v[8:11], v[160:163], v[172:175], v[30:33]
	v_mfma_f32_16x16x32_bf16 v[172:175], v[164:167], v[176:179], v[8:11]
	s_setprio 0
	s_setprio 1
	v_mfma_f32_16x16x32_bf16 v[8:11], v[122:125], v[180:183], v[62:65]
	v_mfma_f32_16x16x32_bf16 v[176:179], v[132:135], v[184:187], v[8:11]
	v_mfma_f32_16x16x32_bf16 v[8:11], v[160:163], v[180:183], v[102:105]
	v_mfma_f32_16x16x32_bf16 v[180:183], v[164:167], v[184:187], v[8:11]
	v_mfma_f32_16x16x32_bf16 v[8:11], v[122:125], v[188:191], v[18:21]
	v_mfma_f32_16x16x32_bf16 v[132:135], v[132:135], v[192:195], v[8:11]
	v_mfma_f32_16x16x32_bf16 v[8:11], v[160:163], v[188:191], v[22:25]
	v_mfma_f32_16x16x32_bf16 v[160:163], v[164:167], v[192:195], v[8:11]
	s_setprio 0
	s_barrier
; #define PG8_STAGE(bufoff, gbase, voff) do { _Pragma("unroll") for (int _i = 0; _i < 2; ++_i) \
;         __builtin_amdgcn_global_load_lds((const GAS unsigned*)((const GAS char*)(gbase) + (size_t)_i * r64##voff + (vo##voff)), (LAS unsigned*)(lds + (bufoff) + ldsw + _i * 8192), 16, 0, 0); } while (0)
; #define PG8_LDA(dst, b, h) do { _Pragma("unroll") for (int m = 0; m < 4; ++m) _Pragma("unroll") for (int k = 0; k < 2; ++k) dst[m][k] = *(const LAS bf16x8*)(lds + PG8_SA(b, h) + aoff + m * 2048 + k * 1024); } while (0)
; #define PG8_WAIT_V(n) asm volatile("s_waitcnt vmcnt(" #n ")" ::: "memory")
; #define PG8_WAIT_L(n) asm volatile("s_waitcnt lgkmcnt(" #n ")" ::: "memory")
; #define PG8_BAR __builtin_amdgcn_s_barrier()
; template <class Epi, class Map, bool ALIGN_EPI>
; __device__ __forceinline__ void gemm_phase(const int tid, LAS unsigned char* lds, const int lda, const int ldb, const int K, const Map& MP, const StaticOrder& S, const Epi& E) {
;     ...
;         for (int t = 0; t < nt; t += 2) {
;             const bool last = (t == nt - 2);
;             const char* a1 = cA + (size_t)(t + 1) * kstep;
;             const char* a2 = last ? nA : cA + (size_t)(t + 2) * kstep; const char* b2 = last ? nB : cB + (size_t)(t + 2) * kstep;
;             const char* a3 = a2 + kstep; const char* b3 = b2 + kstep;
;             PG8_LDB(B0, 0, 0); PG8_LDB(B1, 0, 1); PG8_SCHED; PG8_LDA(At, 0, 0); PG8_STAGE(PG8_SA(1, 1), a1 + hstepA, A);
;             PG8_WAIT_V(8); PG8_WAIT_L(0); PG8_BAR; PG8_MMA(0, 0, At, B0); PG8_MMA(0, 1, At, B1); PG8_BAR; PG8_SCHED;
;             PG8_LDA(At, 0, 1); PG8_STAGE(PG8_SB(0, 0), b2, B); PG8_STAGE(PG8_SB(0, 1), b2 + hstepB, B); PG8_STAGE(PG8_SA(0, 0), a2, A);
;             PG8_WAIT_V(8); PG8_WAIT_L(0); PG8_BAR; PG8_MMA(1, 0, At, B0); PG8_MMA(1, 1, At, B1); PG8_BAR; PG8_SCHED;
;             PG8_LDB(B0, 1, 0); PG8_LDB(B1, 1, 1); PG8_SCHED; PG8_LDA(At, 1, 0); PG8_STAGE(PG8_SA(0, 1), a2 + hstepA, A);
;             PG8_WAIT_V(8); PG8_WAIT_L(0); PG8_BAR; PG8_MMA(0, 0, At, B0); PG8_MMA(0, 1, At, B1); PG8_BAR; PG8_SCHED;
;             PG8_LDA(At, 1, 1); PG8_STAGE(PG8_SB(1, 0), b3, B); PG8_STAGE(PG8_SB(1, 1), b3 + hstepB, B); PG8_STAGE(PG8_SA(1, 0), a3, A);
;             PG8_WAIT_V(8); PG8_WAIT_L(0); PG8_BAR; PG8_MMA(1, 0, At, B0); PG8_MMA(1, 1, At, B1); PG8_BAR; PG8_SCHED;
;         }
;         if constexpr (ALIGN_EPI) { if (wr == 0) PG8_BAR; }
	s_nop 4
	ds_read_b128 v[8:11], v218
	ds_read_b128 v[12:15], v218 offset:1024
	ds_read_b128 v[16:19], v218 offset:2048
	ds_read_b128 v[20:23], v218 offset:3072
	ds_read_b128 v[164:167], v219
	ds_read_b128 v[184:187], v219 offset:1024
	ds_read_b128 v[188:191], v219 offset:2048
	ds_read_b128 v[192:195], v219 offset:3072
	s_mov_b64 s[44:45], 0x10000
	s_mov_b32 m0, s28
	v_lshl_add_u64 v[32:33], v[222:223], 0, s[44:45]
	s_mov_b64 s[44:45], 0x18000
	ds_read_b128 v[24:27], v131 offset:32768
	ds_read_b128 v[28:31], v131 offset:33792
	ds_read_b128 v[240:243], v131 offset:34816
	ds_read_b128 v[244:247], v131 offset:35840
	ds_read_b128 v[248:251], v131 offset:36864
	ds_read_b128 v[218:221], v131 offset:37888
	ds_read_b128 v[226:229], v131 offset:38912
	ds_read_b128 v[236:239], v131 offset:39936
	global_load_lds_dwordx4 v[32:33], off
	v_lshl_add_u64 v[32:33], v[222:223], 0, s[44:45]
	s_mov_b32 m0, s29
	s_nop 0
	global_load_lds_dwordx4 v[32:33], off
	s_waitcnt vmcnt(8)
	s_waitcnt lgkmcnt(0)
	s_barrier
	s_setprio 1
	v_mfma_f32_16x16x32_bf16 v[58:61], v[8:11], v[24:27], v[66:69]
	v_mfma_f32_16x16x32_bf16 v[124:127], v[12:15], v[28:31], v[58:61]
	v_mfma_f32_16x16x32_bf16 v[58:61], v[16:19], v[24:27], v[70:73]
	v_mfma_f32_16x16x32_bf16 v[120:123], v[20:23], v[28:31], v[58:61]
	v_mfma_f32_16x16x32_bf16 v[58:61], v[8:11], v[240:243], v[74:77]
	v_mfma_f32_16x16x32_bf16 v[108:111], v[12:15], v[244:247], v[58:61]
	v_mfma_f32_16x16x32_bf16 v[58:61], v[16:19], v[240:243], v[78:81]
	v_mfma_f32_16x16x32_bf16 v[104:107], v[20:23], v[244:247], v[58:61]
	s_setprio 0
	s_setprio 1
	v_mfma_f32_16x16x32_bf16 v[58:61], v[8:11], v[248:251], v[82:85]
	v_mfma_f32_16x16x32_bf16 v[92:95], v[12:15], v[218:221], v[58:61]
	v_mfma_f32_16x16x32_bf16 v[58:61], v[16:19], v[248:251], v[86:89]
	v_mfma_f32_16x16x32_bf16 v[88:91], v[20:23], v[218:221], v[58:61]
	v_mfma_f32_16x16x32_bf16 v[58:61], v[8:11], v[226:229], v[200:203]
	v_mfma_f32_16x16x32_bf16 v[68:71], v[12:15], v[236:239], v[58:61]
	v_mfma_f32_16x16x32_bf16 v[58:61], v[16:19], v[226:229], v[204:207]
	v_mfma_f32_16x16x32_bf16 v[60:63], v[20:23], v[236:239], v[58:61]
	s_setprio 0
	s_setprio 1
	v_mfma_f32_16x16x32_bf16 v[64:67], v[164:167], v[24:27], v[96:99]
	v_mfma_f32_16x16x32_bf16 v[24:27], v[188:191], v[24:27], v[34:37]
	v_mfma_f32_16x16x32_bf16 v[112:115], v[192:195], v[28:31], v[24:27]
	v_mfma_f32_16x16x32_bf16 v[24:27], v[164:167], v[240:243], v[38:41]
	v_mfma_f32_16x16x32_bf16 v[100:103], v[184:187], v[244:247], v[24:27]
	v_mfma_f32_16x16x32_bf16 v[24:27], v[188:191], v[240:243], v[42:45]
	v_mfma_f32_16x16x32_bf16 v[96:99], v[192:195], v[244:247], v[24:27]
	v_mfma_f32_16x16x32_bf16 v[24:27], v[164:167], v[248:251], v[46:49]
	s_setprio 0
	s_setprio 1
	v_mfma_f32_16x16x32_bf16 v[84:87], v[184:187], v[218:221], v[24:27]
	v_mfma_f32_16x16x32_bf16 v[24:27], v[188:191], v[248:251], v[50:53]
	v_mfma_f32_16x16x32_bf16 v[80:83], v[192:195], v[218:221], v[24:27]
	v_mfma_f32_16x16x32_bf16 v[24:27], v[164:167], v[226:229], v[54:57]
	v_mfma_f32_16x16x32_bf16 v[52:55], v[184:187], v[236:239], v[24:27]
	v_mfma_f32_16x16x32_bf16 v[24:27], v[188:191], v[226:229], v[168:171]
	v_mfma_f32_16x16x32_bf16 v[116:119], v[184:187], v[28:31], v[64:67]
	v_mfma_f32_16x16x32_bf16 v[48:51], v[192:195], v[236:239], v[24:27]
	s_setprio 0
	s_barrier
	s_mov_b32 m0, s56
	s_nop 2
	v_lshl_add_u64 v[24:25], v[230:231], 0, s[50:51]
	ds_read_b128 v[32:35], v131 offset:49152
	ds_read_b128 v[36:39], v131 offset:50176
	ds_read_b128 v[168:171], v131 offset:51200
	ds_read_b128 v[200:203], v131 offset:52224
	ds_read_b128 v[204:207], v131 offset:53248
	ds_read_b128 v[218:221], v131 offset:54272
	ds_read_b128 v[226:229], v131 offset:55296
	ds_read_b128 v[236:239], v131 offset:56320
	global_load_lds_dwordx4 v[24:25], off
	v_lshl_add_u64 v[24:25], v[230:231], 0, s[54:55]
	s_mov_b32 m0, s49
	s_mov_b64 s[44:45], 0x8080
	global_load_lds_dwordx4 v[24:25], off
	v_lshl_add_u64 v[24:25], v[230:231], 0, s[96:97]
	s_mov_b32 m0, s52
	s_nop 0
	global_load_lds_dwordx4 v[24:25], off
	v_lshl_add_u64 v[24:25], v[230:231], 0, s[6:7]
	s_mov_b32 m0, s53
	s_nop 0
	global_load_lds_dwordx4 v[24:25], off
	v_lshl_add_u64 v[24:25], v[222:223], 0, s[50:51]
	s_mov_b32 m0, s33
	s_nop 0
	global_load_lds_dwordx4 v[24:25], off
	v_lshl_add_u64 v[24:25], v[222:223], 0, s[44:45]
	s_mov_b32 m0, s34
	s_nop 0
	global_load_lds_dwordx4 v[24:25], off
	s_waitcnt vmcnt(8)
	s_waitcnt lgkmcnt(0)
	s_barrier
	s_setprio 1
	v_mfma_f32_16x16x32_bf16 v[24:27], v[8:11], v[32:35], v[136:139]
	v_mfma_f32_16x16x32_bf16 v[76:79], v[12:15], v[36:39], v[24:27]
	v_mfma_f32_16x16x32_bf16 v[24:27], v[16:19], v[32:35], v[140:143]
	v_mfma_f32_16x16x32_bf16 v[72:75], v[20:23], v[36:39], v[24:27]
	v_mfma_f32_16x16x32_bf16 v[24:27], v[8:11], v[168:171], v[144:147]
	v_mfma_f32_16x16x32_bf16 v[44:47], v[12:15], v[200:203], v[24:27]
	v_mfma_f32_16x16x32_bf16 v[24:27], v[16:19], v[168:171], v[148:151]
	v_mfma_f32_16x16x32_bf16 v[40:43], v[20:23], v[200:203], v[24:27]
	s_setprio 0
	s_setprio 1
	v_mfma_f32_16x16x32_bf16 v[24:27], v[8:11], v[204:207], v[152:155]
	v_mfma_f32_16x16x32_bf16 v[0:3], v[8:11], v[226:229], v[0:3]
	v_mfma_f32_16x16x32_bf16 v[28:31], v[12:15], v[218:221], v[24:27]
	v_mfma_f32_16x16x32_bf16 v[24:27], v[16:19], v[204:207], v[156:159]
	v_mfma_f32_16x16x32_bf16 v[12:15], v[12:15], v[236:239], v[0:3]
	v_mfma_f32_16x16x32_bf16 v[0:3], v[16:19], v[226:229], v[4:7]
	v_mfma_f32_16x16x32_bf16 v[24:27], v[20:23], v[218:221], v[24:27]
	v_mfma_f32_16x16x32_bf16 v[8:11], v[20:23], v[236:239], v[0:3]
	s_setprio 0
	s_setprio 1
	v_mfma_f32_16x16x32_bf16 v[0:3], v[164:167], v[32:35], v[196:199]
	v_mfma_f32_16x16x32_bf16 v[64:67], v[184:187], v[36:39], v[0:3]
	v_mfma_f32_16x16x32_bf16 v[0:3], v[188:191], v[32:35], v[208:211]
	v_mfma_f32_16x16x32_bf16 v[56:59], v[192:195], v[36:39], v[0:3]
	v_mfma_f32_16x16x32_bf16 v[0:3], v[164:167], v[168:171], v[212:215]
	v_mfma_f32_16x16x32_bf16 v[36:39], v[184:187], v[200:203], v[0:3]
	v_mfma_f32_16x16x32_bf16 v[0:3], v[188:191], v[168:171], v[172:175]
	v_mfma_f32_16x16x32_bf16 v[32:35], v[192:195], v[200:203], v[0:3]
	s_setprio 0
	s_setprio 1
	v_mfma_f32_16x16x32_bf16 v[0:3], v[164:167], v[204:207], v[176:179]
	v_mfma_f32_16x16x32_bf16 v[20:23], v[184:187], v[218:221], v[0:3]
	v_mfma_f32_16x16x32_bf16 v[0:3], v[188:191], v[204:207], v[180:183]
	v_mfma_f32_16x16x32_bf16 v[16:19], v[192:195], v[218:221], v[0:3]
	v_mfma_f32_16x16x32_bf16 v[0:3], v[164:167], v[226:229], v[132:135]
	v_mfma_f32_16x16x32_bf16 v[4:7], v[184:187], v[236:239], v[0:3]
	v_mfma_f32_16x16x32_bf16 v[0:3], v[188:191], v[226:229], v[160:163]
	v_mfma_f32_16x16x32_bf16 v[0:3], v[192:195], v[236:239], v[0:3]
	s_setprio 0
	s_barrier
	s_andn2_b64 vcc, exec, s[4:5]
	s_cbranch_vccnz .LBB0_675
	s_barrier

; #define PG8_STAGE(bufoff, gbase, voff) do { _Pragma("unroll") for (int _i = 0; _i < 2; ++_i) \
;         __builtin_amdgcn_global_load_lds((const GAS unsigned*)((const GAS char*)(gbase) + (size_t)_i * r64##voff + (vo##voff)), (LAS unsigned*)(lds + (bufoff) + ldsw + _i * 8192), 16, 0, 0); } while (0)
; #define PG8_LDA(dst, b, h) do { _Pragma("unroll") for (int m = 0; m < 4; ++m) _Pragma("unroll") for (int k = 0; k < 2; ++k) dst[m][k] = *(const LAS bf16x8*)(lds + PG8_SA(b, h) + aoff + m * 2048 + k * 1024); } while (0)
; #define PG8_LDB(dst, b, h) do { _Pragma("unroll") for (int n = 0; n < 2; ++n) _Pragma("unroll") for (int k = 0; k < 2; ++k) dst[n][k] = *(const LAS bf16x8*)(lds + PG8_SB(b, h) + boff + n * 2048 + k * 1024); } while (0)
; #define PG8_BAR __builtin_amdgcn_s_barrier()
; template <class Epi, class Map, bool ALIGN_EPI>
; __device__ __forceinline__ void gemm_phase(const int tid, LAS unsigned char* lds, const int lda, const int ldb, const int K, const Map& MP, const StaticOrder& S, const Epi& E) {
;     ...
;         for (int t = 0; t < nt; t += 2) {
;             const bool last = (t == nt - 2);
;             const char* a1 = cA + (size_t)(t + 1) * kstep;
;             const char* a2 = last ? nA : cA + (size_t)(t + 2) * kstep; const char* b2 = last ? nB : cB + (size_t)(t + 2) * kstep;
;             const char* a3 = a2 + kstep; const char* b3 = b2 + kstep;
;             PG8_LDB(B0, 0, 0); PG8_LDB(B1, 0, 1); PG8_SCHED; PG8_LDA(At, 0, 0); PG8_STAGE(PG8_SA(1, 1), a1 + hstepA, A);
;             PG8_WAIT_V(8); PG8_WAIT_L(0); PG8_BAR; PG8_MMA(0, 0, At, B0); PG8_MMA(0, 1, At, B1); PG8_BAR; PG8_SCHED;
;             PG8_LDA(At, 0, 1); PG8_STAGE(PG8_SB(0, 0), b2, B); PG8_STAGE(PG8_SB(0, 1), b2 + hstepB, B); PG8_STAGE(PG8_SA(0, 0), a2, A);
;             PG8_WAIT_V(8); PG8_WAIT_L(0); PG8_BAR; PG8_MMA(1, 0, At, B0); PG8_MMA(1, 1, At, B1); PG8_BAR; PG8_SCHED;
;             PG8_LDB(B0, 1, 0); PG8_LDB(B1, 1, 1); PG8_SCHED; PG8_LDA(At, 1, 0); PG8_STAGE(PG8_SA(0, 1), a2 + hstepA, A);
;             PG8_WAIT_V(8); PG8_WAIT_L(0); PG8_BAR; PG8_MMA(0, 0, At, B0); PG8_MMA(0, 1, At, B1); PG8_BAR; PG8_SCHED;
;             PG8_LDA(At, 1, 1); PG8_STAGE(PG8_SB(1, 0), b3, B); PG8_STAGE(PG8_SB(1, 1), b3 + hstepB, B); PG8_STAGE(PG8_SA(1, 0), a3, A);
;             PG8_WAIT_V(8); PG8_WAIT_L(0); PG8_BAR; PG8_MMA(1, 0, At, B0); PG8_MMA(1, 1, At, B1); PG8_BAR; PG8_SCHED;
;         }
.LBB0_751:
	s_add_u32 s42, s10, 0xfff00080
	s_addc_u32 s43, s11, -1
	s_add_i32 s47, 0, 0x10000
	s_cmp_eq_u32 s46, 28
	s_cselect_b32 s43, s89, s43
	s_cselect_b32 s42, s88, s42
	s_cselect_b32 s81, s93, s79
	s_cselect_b32 s80, s92, s71
	s_add_i32 s82, 0, 0x14000
	v_add_u32_e32 v144, s47, v160
	v_add_u32_e32 v162, s82, v160
	ds_read_b128 v[128:131], v144
	ds_read_b128 v[132:135], v144 offset:1024
	ds_read_b128 v[140:143], v144 offset:2048
	ds_read_b128 v[144:147], v144 offset:3072
	ds_read_b128 v[148:151], v162
	ds_read_b128 v[152:155], v162 offset:1024
	ds_read_b128 v[156:159], v162 offset:2048
	ds_read_b128 v[162:165], v162 offset:3072
	v_lshl_add_u64 v[198:199], s[10:11], 0, v[138:139]
	s_add_i32 m0, s19, 0xc000
	ds_read_b128 v[166:169], v161
	ds_read_b128 v[170:173], v161 offset:1024
	ds_read_b128 v[174:177], v161 offset:2048
	ds_read_b128 v[178:181], v161 offset:3072
	ds_read_b128 v[182:185], v161 offset:4096
	ds_read_b128 v[186:189], v161 offset:5120
	ds_read_b128 v[190:193], v161 offset:6144
	ds_read_b128 v[194:197], v161 offset:7168
	global_load_lds_dwordx4 v[198:199], off
	v_lshl_add_u64 v[198:199], v[198:199], 0, s[0:1]
	s_add_i32 m0, s19, 0xe000
	s_nop 0
	global_load_lds_dwordx4 v[198:199], off
	s_waitcnt vmcnt(8)
	s_waitcnt lgkmcnt(0)
	s_barrier
	s_setprio 1
	v_mfma_f32_16x16x32_bf16 v[124:127], v[128:131], v[166:169], v[124:127]
	v_mfma_f32_16x16x32_bf16 v[120:123], v[140:143], v[166:169], v[120:123]
	v_mfma_f32_16x16x32_bf16 v[116:119], v[128:131], v[174:177], v[116:119]
	v_mfma_f32_16x16x32_bf16 v[112:115], v[140:143], v[174:177], v[112:115]
	v_mfma_f32_16x16x32_bf16 v[108:111], v[128:131], v[182:185], v[108:111]
	v_mfma_f32_16x16x32_bf16 v[104:107], v[140:143], v[182:185], v[104:107]
	v_mfma_f32_16x16x32_bf16 v[100:103], v[128:131], v[190:193], v[100:103]
	v_mfma_f32_16x16x32_bf16 v[96:99], v[140:143], v[190:193], v[96:99]
	s_setprio 0
	s_setprio 1
	v_mfma_f32_16x16x32_bf16 v[124:127], v[132:135], v[170:173], v[124:127]
	v_mfma_f32_16x16x32_bf16 v[120:123], v[144:147], v[170:173], v[120:123]
	v_mfma_f32_16x16x32_bf16 v[116:119], v[132:135], v[178:181], v[116:119]
	v_mfma_f32_16x16x32_bf16 v[112:115], v[144:147], v[178:181], v[112:115]
	v_mfma_f32_16x16x32_bf16 v[108:111], v[132:135], v[186:189], v[108:111]
	v_mfma_f32_16x16x32_bf16 v[104:107], v[144:147], v[186:189], v[104:107]
	v_mfma_f32_16x16x32_bf16 v[100:103], v[132:135], v[194:197], v[100:103]
	v_mfma_f32_16x16x32_bf16 v[96:99], v[144:147], v[194:197], v[96:99]
	s_setprio 0
	s_setprio 1
	v_mfma_f32_16x16x32_bf16 v[92:95], v[148:151], v[166:169], v[92:95]
	v_mfma_f32_16x16x32_bf16 v[88:91], v[156:159], v[166:169], v[88:91]
	v_mfma_f32_16x16x32_bf16 v[84:87], v[148:151], v[174:177], v[84:87]
	v_mfma_f32_16x16x32_bf16 v[80:83], v[156:159], v[174:177], v[80:83]
	v_mfma_f32_16x16x32_bf16 v[76:79], v[148:151], v[182:185], v[76:79]
	v_mfma_f32_16x16x32_bf16 v[72:75], v[156:159], v[182:185], v[72:75]
	v_mfma_f32_16x16x32_bf16 v[68:71], v[148:151], v[190:193], v[68:71]
	v_mfma_f32_16x16x32_bf16 v[64:67], v[156:159], v[190:193], v[64:67]
	s_setprio 0
	s_setprio 1
	v_mfma_f32_16x16x32_bf16 v[92:95], v[152:155], v[170:173], v[92:95]
	v_mfma_f32_16x16x32_bf16 v[88:91], v[162:165], v[170:173], v[88:91]
	v_mfma_f32_16x16x32_bf16 v[84:87], v[152:155], v[178:181], v[84:87]
	v_mfma_f32_16x16x32_bf16 v[80:83], v[162:165], v[178:181], v[80:83]
	v_mfma_f32_16x16x32_bf16 v[76:79], v[152:155], v[186:189], v[76:79]
	v_mfma_f32_16x16x32_bf16 v[72:75], v[162:165], v[186:189], v[72:75]
	v_mfma_f32_16x16x32_bf16 v[68:71], v[152:155], v[194:197], v[68:71]
	v_mfma_f32_16x16x32_bf16 v[64:67], v[162:165], v[194:197], v[64:67]
	s_setprio 0
	s_barrier
	s_add_i32 s47, s47, s14
	v_lshl_add_u64 v[198:199], s[80:81], 0, v[136:137]
	s_mov_b32 m0, s47
	ds_read_b128 v[166:169], v161 offset:16384
	ds_read_b128 v[170:173], v161 offset:17408
	ds_read_b128 v[174:177], v161 offset:18432
	ds_read_b128 v[178:181], v161 offset:19456
	ds_read_b128 v[182:185], v161 offset:20480
	ds_read_b128 v[186:189], v161 offset:21504
	ds_read_b128 v[190:193], v161 offset:22528
	ds_read_b128 v[194:197], v161 offset:23552
	global_load_lds_dwordx4 v[198:199], off
	v_lshl_add_u64 v[200:201], v[198:199], 0, s[0:1]
	s_add_i32 m0, s47, 0x2000
	s_add_i32 s47, s82, s14
	global_load_lds_dwordx4 v[200:201], off
	v_lshl_add_u64 v[200:201], v[198:199], 0, vcc
	s_mov_b32 m0, s47
	s_nop 0
	global_load_lds_dwordx4 v[200:201], off
	v_lshl_add_u64 v[200:201], v[198:199], 0, s[16:17]
	s_add_i32 m0, s47, 0x2000
	s_nop 0
	global_load_lds_dwordx4 v[200:201], off
	v_lshl_add_u64 v[200:201], s[42:43], 0, v[138:139]
	s_mov_b32 m0, s19
	v_lshl_add_u64 v[202:203], v[200:201], 0, s[0:1]
	global_load_lds_dwordx4 v[200:201], off
	s_mov_b32 m0, s24
	s_nop 0
	global_load_lds_dwordx4 v[202:203], off
	s_waitcnt vmcnt(8)
	s_waitcnt lgkmcnt(0)
	s_barrier
; #define PG8_STAGE(bufoff, gbase, voff) do { _Pragma("unroll") for (int _i = 0; _i < 2; ++_i) \
;         __builtin_amdgcn_global_load_lds((const GAS unsigned*)((const GAS char*)(gbase) + (size_t)_i * r64##voff + (vo##voff)), (LAS unsigned*)(lds + (bufoff) + ldsw + _i * 8192), 16, 0, 0); } while (0)
; #define PG8_LDA(dst, b, h) do { _Pragma("unroll") for (int m = 0; m < 4; ++m) _Pragma("unroll") for (int k = 0; k < 2; ++k) dst[m][k] = *(const LAS bf16x8*)(lds + PG8_SA(b, h) + aoff + m * 2048 + k * 1024); } while (0)
; #define PG8_LDB(dst, b, h) do { _Pragma("unroll") for (int n = 0; n < 2; ++n) _Pragma("unroll") for (int k = 0; k < 2; ++k) dst[n][k] = *(const LAS bf16x8*)(lds + PG8_SB(b, h) + boff + n * 2048 + k * 1024); } while (0)
; #define PG8_BAR __builtin_amdgcn_s_barrier()
; template <class Epi, class Map, bool ALIGN_EPI>
; __device__ __forceinline__ void gemm_phase(const int tid, LAS unsigned char* lds, const int lda, const int ldb, const int K, const Map& MP, const StaticOrder& S, const Epi& E) {
;     ...
;         for (int t = 0; t < nt; t += 2) {
;             const bool last = (t == nt - 2);
;             const char* a1 = cA + (size_t)(t + 1) * kstep;
;             const char* a2 = last ? nA : cA + (size_t)(t + 2) * kstep; const char* b2 = last ? nB : cB + (size_t)(t + 2) * kstep;
;             const char* a3 = a2 + kstep; const char* b3 = b2 + kstep;
;             PG8_LDB(B0, 0, 0); PG8_LDB(B1, 0, 1); PG8_SCHED; PG8_LDA(At, 0, 0); PG8_STAGE(PG8_SA(1, 1), a1 + hstepA, A);
;             PG8_WAIT_V(8); PG8_WAIT_L(0); PG8_BAR; PG8_MMA(0, 0, At, B0); PG8_MMA(0, 1, At, B1); PG8_BAR; PG8_SCHED;
;             PG8_LDA(At, 0, 1); PG8_STAGE(PG8_SB(0, 0), b2, B); PG8_STAGE(PG8_SB(0, 1), b2 + hstepB, B); PG8_STAGE(PG8_SA(0, 0), a2, A);
;             PG8_WAIT_V(8); PG8_WAIT_L(0); PG8_BAR; PG8_MMA(1, 0, At, B0); PG8_MMA(1, 1, At, B1); PG8_BAR; PG8_SCHED;
;             PG8_LDB(B0, 1, 0); PG8_LDB(B1, 1, 1); PG8_SCHED; PG8_LDA(At, 1, 0); PG8_STAGE(PG8_SA(0, 1), a2 + hstepA, A);
;             PG8_WAIT_V(8); PG8_WAIT_L(0); PG8_BAR; PG8_MMA(0, 0, At, B0); PG8_MMA(0, 1, At, B1); PG8_BAR; PG8_SCHED;
;             PG8_LDA(At, 1, 1); PG8_STAGE(PG8_SB(1, 0), b3, B); PG8_STAGE(PG8_SB(1, 1), b3 + hstepB, B); PG8_STAGE(PG8_SA(1, 0), a3, A);
;             PG8_WAIT_V(8); PG8_WAIT_L(0); PG8_BAR; PG8_MMA(1, 0, At, B0); PG8_MMA(1, 1, At, B1); PG8_BAR; PG8_SCHED;
;         }
	s_setprio 1
	v_mfma_f32_16x16x32_bf16 v[60:63], v[128:131], v[166:169], v[60:63]
	v_mfma_f32_16x16x32_bf16 v[56:59], v[140:143], v[166:169], v[56:59]
	v_mfma_f32_16x16x32_bf16 v[52:55], v[128:131], v[174:177], v[52:55]
	v_mfma_f32_16x16x32_bf16 v[48:51], v[140:143], v[174:177], v[48:51]
	v_mfma_f32_16x16x32_bf16 v[44:47], v[128:131], v[182:185], v[44:47]
	v_mfma_f32_16x16x32_bf16 v[40:43], v[140:143], v[182:185], v[40:43]
	v_mfma_f32_16x16x32_bf16 v[36:39], v[128:131], v[190:193], v[36:39]
	v_mfma_f32_16x16x32_bf16 v[32:35], v[140:143], v[190:193], v[32:35]
	s_setprio 0
	s_setprio 1
	v_mfma_f32_16x16x32_bf16 v[60:63], v[132:135], v[170:173], v[60:63]
	v_mfma_f32_16x16x32_bf16 v[56:59], v[144:147], v[170:173], v[56:59]
	v_mfma_f32_16x16x32_bf16 v[52:55], v[132:135], v[178:181], v[52:55]
	v_mfma_f32_16x16x32_bf16 v[48:51], v[144:147], v[178:181], v[48:51]
	v_mfma_f32_16x16x32_bf16 v[44:47], v[132:135], v[186:189], v[44:47]
	v_mfma_f32_16x16x32_bf16 v[40:43], v[144:147], v[186:189], v[40:43]
	v_mfma_f32_16x16x32_bf16 v[36:39], v[132:135], v[194:197], v[36:39]
	v_mfma_f32_16x16x32_bf16 v[32:35], v[144:147], v[194:197], v[32:35]
	s_setprio 0
	s_setprio 1
	v_mfma_f32_16x16x32_bf16 v[28:31], v[148:151], v[166:169], v[28:31]
	v_mfma_f32_16x16x32_bf16 v[24:27], v[156:159], v[166:169], v[24:27]
	v_mfma_f32_16x16x32_bf16 v[20:23], v[148:151], v[174:177], v[20:23]
	v_mfma_f32_16x16x32_bf16 v[16:19], v[156:159], v[174:177], v[16:19]
	v_mfma_f32_16x16x32_bf16 v[12:15], v[148:151], v[182:185], v[12:15]
	v_mfma_f32_16x16x32_bf16 v[8:11], v[156:159], v[182:185], v[8:11]
	v_mfma_f32_16x16x32_bf16 v[4:7], v[148:151], v[190:193], v[4:7]
	v_mfma_f32_16x16x32_bf16 v[0:3], v[156:159], v[190:193], v[0:3]
	s_setprio 0
	s_setprio 1
	v_mfma_f32_16x16x32_bf16 v[28:31], v[152:155], v[170:173], v[28:31]
	v_mfma_f32_16x16x32_bf16 v[24:27], v[162:165], v[170:173], v[24:27]
	v_mfma_f32_16x16x32_bf16 v[20:23], v[152:155], v[178:181], v[20:23]
	v_mfma_f32_16x16x32_bf16 v[16:19], v[162:165], v[178:181], v[16:19]
	v_mfma_f32_16x16x32_bf16 v[12:15], v[152:155], v[186:189], v[12:15]
	v_mfma_f32_16x16x32_bf16 v[8:11], v[162:165], v[186:189], v[8:11]
	v_mfma_f32_16x16x32_bf16 v[4:7], v[152:155], v[194:197], v[4:7]
	v_mfma_f32_16x16x32_bf16 v[0:3], v[162:165], v[194:197], v[0:3]
	s_setprio 0
	s_barrier
	s_add_i32 s42, 0, 0x18000
	s_add_i32 s43, 0, 0x1c000
	v_add_u32_e32 v144, s42, v160
	v_add_u32_e32 v162, s43, v160
	ds_read_b128 v[128:131], v144
	ds_read_b128 v[132:135], v144 offset:1024
	ds_read_b128 v[140:143], v144 offset:2048
	ds_read_b128 v[144:147], v144 offset:3072
	ds_read_b128 v[148:151], v162
	ds_read_b128 v[152:155], v162 offset:1024
	ds_read_b128 v[156:159], v162 offset:2048
	ds_read_b128 v[162:165], v162 offset:3072
	s_mov_b32 m0, s28
	v_lshl_add_u64 v[202:203], v[200:201], 0, vcc
	ds_read_b128 v[166:169], v161 offset:32768
	ds_read_b128 v[170:173], v161 offset:33792
	ds_read_b128 v[174:177], v161 offset:34816
	ds_read_b128 v[178:181], v161 offset:35840
	ds_read_b128 v[182:185], v161 offset:36864
	ds_read_b128 v[186:189], v161 offset:37888
	ds_read_b128 v[190:193], v161 offset:38912
	ds_read_b128 v[194:197], v161 offset:39936
	global_load_lds_dwordx4 v[202:203], off
	v_lshl_add_u64 v[202:203], v[200:201], 0, s[16:17]
	s_mov_b32 m0, s29
	s_nop 0
	global_load_lds_dwordx4 v[202:203], off
	s_waitcnt vmcnt(8)
	s_waitcnt lgkmcnt(0)
	s_barrier
	s_setprio 1
	v_mfma_f32_16x16x32_bf16 v[124:127], v[128:131], v[166:169], v[124:127]
	v_mfma_f32_16x16x32_bf16 v[120:123], v[140:143], v[166:169], v[120:123]
	v_mfma_f32_16x16x32_bf16 v[116:119], v[128:131], v[174:177], v[116:119]
	v_mfma_f32_16x16x32_bf16 v[112:115], v[140:143], v[174:177], v[112:115]
	v_mfma_f32_16x16x32_bf16 v[108:111], v[128:131], v[182:185], v[108:111]
	v_mfma_f32_16x16x32_bf16 v[104:107], v[140:143], v[182:185], v[104:107]
	v_mfma_f32_16x16x32_bf16 v[100:103], v[128:131], v[190:193], v[100:103]
	v_mfma_f32_16x16x32_bf16 v[96:99], v[140:143], v[190:193], v[96:99]
	s_setprio 0
	s_setprio 1
	v_mfma_f32_16x16x32_bf16 v[124:127], v[132:135], v[170:173], v[124:127]
	v_mfma_f32_16x16x32_bf16 v[120:123], v[144:147], v[170:173], v[120:123]
	v_mfma_f32_16x16x32_bf16 v[116:119], v[132:135], v[178:181], v[116:119]
	v_mfma_f32_16x16x32_bf16 v[112:115], v[144:147], v[178:181], v[112:115]
	v_mfma_f32_16x16x32_bf16 v[108:111], v[132:135], v[186:189], v[108:111]
	v_mfma_f32_16x16x32_bf16 v[104:107], v[144:147], v[186:189], v[104:107]
	v_mfma_f32_16x16x32_bf16 v[100:103], v[132:135], v[194:197], v[100:103]
	v_mfma_f32_16x16x32_bf16 v[96:99], v[144:147], v[194:197], v[96:99]
	s_setprio 0
	s_setprio 1
	v_mfma_f32_16x16x32_bf16 v[92:95], v[148:151], v[166:169], v[92:95]
	v_mfma_f32_16x16x32_bf16 v[88:91], v[156:159], v[166:169], v[88:91]
	v_mfma_f32_16x16x32_bf16 v[84:87], v[148:151], v[174:177], v[84:87]
	v_mfma_f32_16x16x32_bf16 v[80:83], v[156:159], v[174:177], v[80:83]
	v_mfma_f32_16x16x32_bf16 v[76:79], v[148:151], v[182:185], v[76:79]
	v_mfma_f32_16x16x32_bf16 v[72:75], v[156:159], v[182:185], v[72:75]
	v_mfma_f32_16x16x32_bf16 v[68:71], v[148:151], v[190:193], v[68:71]
	v_mfma_f32_16x16x32_bf16 v[64:67], v[156:159], v[190:193], v[64:67]
	s_setprio 0
	s_setprio 1
	v_mfma_f32_16x16x32_bf16 v[92:95], v[152:155], v[170:173], v[92:95]
	v_mfma_f32_16x16x32_bf16 v[88:91], v[162:165], v[170:173], v[88:91]
	v_mfma_f32_16x16x32_bf16 v[84:87], v[152:155], v[178:181], v[84:87]
	v_mfma_f32_16x16x32_bf16 v[80:83], v[162:165], v[178:181], v[80:83]
	v_mfma_f32_16x16x32_bf16 v[76:79], v[152:155], v[186:189], v[76:79]
	v_mfma_f32_16x16x32_bf16 v[72:75], v[162:165], v[186:189], v[72:75]
	v_mfma_f32_16x16x32_bf16 v[68:71], v[152:155], v[194:197], v[68:71]
	v_mfma_f32_16x16x32_bf16 v[64:67], v[162:165], v[194:197], v[64:67]
	s_setprio 0
	s_barrier
; #define PG8_STAGE(bufoff, gbase, voff) do { _Pragma("unroll") for (int _i = 0; _i < 2; ++_i) \
;         __builtin_amdgcn_global_load_lds((const GAS unsigned*)((const GAS char*)(gbase) + (size_t)_i * r64##voff + (vo##voff)), (LAS unsigned*)(lds + (bufoff) + ldsw + _i * 8192), 16, 0, 0); } while (0)
; #define PG8_LDA(dst, b, h) do { _Pragma("unroll") for (int m = 0; m < 4; ++m) _Pragma("unroll") for (int k = 0; k < 2; ++k) dst[m][k] = *(const LAS bf16x8*)(lds + PG8_SA(b, h) + aoff + m * 2048 + k * 1024); } while (0)
; #define PG8_LDB(dst, b, h) do { _Pragma("unroll") for (int n = 0; n < 2; ++n) _Pragma("unroll") for (int k = 0; k < 2; ++k) dst[n][k] = *(const LAS bf16x8*)(lds + PG8_SB(b, h) + boff + n * 2048 + k * 1024); } while (0)
; #define PG8_BAR __builtin_amdgcn_s_barrier()
; template <class Epi, class Map, bool ALIGN_EPI>
; __device__ __forceinline__ void gemm_phase(const int tid, LAS unsigned char* lds, const int lda, const int ldb, const int K, const Map& MP, const StaticOrder& S, const Epi& E) {
;     ...
;         for (int t = 0; t < nt; t += 2) {
;             const bool last = (t == nt - 2);
;             const char* a1 = cA + (size_t)(t + 1) * kstep;
;             const char* a2 = last ? nA : cA + (size_t)(t + 2) * kstep; const char* b2 = last ? nB : cB + (size_t)(t + 2) * kstep;
;             const char* a3 = a2 + kstep; const char* b3 = b2 + kstep;
;             PG8_LDB(B0, 0, 0); PG8_LDB(B1, 0, 1); PG8_SCHED; PG8_LDA(At, 0, 0); PG8_STAGE(PG8_SA(1, 1), a1 + hstepA, A);
;             PG8_WAIT_V(8); PG8_WAIT_L(0); PG8_BAR; PG8_MMA(0, 0, At, B0); PG8_MMA(0, 1, At, B1); PG8_BAR; PG8_SCHED;
;             PG8_LDA(At, 0, 1); PG8_STAGE(PG8_SB(0, 0), b2, B); PG8_STAGE(PG8_SB(0, 1), b2 + hstepB, B); PG8_STAGE(PG8_SA(0, 0), a2, A);
;             PG8_WAIT_V(8); PG8_WAIT_L(0); PG8_BAR; PG8_MMA(1, 0, At, B0); PG8_MMA(1, 1, At, B1); PG8_BAR; PG8_SCHED;
;             PG8_LDB(B0, 1, 0); PG8_LDB(B1, 1, 1); PG8_SCHED; PG8_LDA(At, 1, 0); PG8_STAGE(PG8_SA(0, 1), a2 + hstepA, A);
;             PG8_WAIT_V(8); PG8_WAIT_L(0); PG8_BAR; PG8_MMA(0, 0, At, B0); PG8_MMA(0, 1, At, B1); PG8_BAR; PG8_SCHED;
;             PG8_LDA(At, 1, 1); PG8_STAGE(PG8_SB(1, 0), b3, B); PG8_STAGE(PG8_SB(1, 1), b3 + hstepB, B); PG8_STAGE(PG8_SA(1, 0), a3, A);
;             PG8_WAIT_V(8); PG8_WAIT_L(0); PG8_BAR; PG8_MMA(1, 0, At, B0); PG8_MMA(1, 1, At, B1); PG8_BAR; PG8_SCHED;
;         }
	s_add_i32 s42, s42, s14
	v_lshl_add_u64 v[202:203], v[198:199], 0, s[50:51]
	s_mov_b32 m0, s42
	ds_read_b128 v[166:169], v161 offset:49152
	ds_read_b128 v[170:173], v161 offset:50176
	ds_read_b128 v[174:177], v161 offset:51200
	ds_read_b128 v[178:181], v161 offset:52224
	ds_read_b128 v[182:185], v161 offset:53248
	ds_read_b128 v[186:189], v161 offset:54272
	ds_read_b128 v[190:193], v161 offset:55296
	ds_read_b128 v[194:197], v161 offset:56320
	global_load_lds_dwordx4 v[202:203], off
	v_lshl_add_u64 v[202:203], v[198:199], 0, s[20:21]
	s_add_i32 m0, s42, 0x2000
	s_add_i32 s42, s43, s14
	global_load_lds_dwordx4 v[202:203], off
	v_lshl_add_u64 v[202:203], v[198:199], 0, s[22:23]
	s_mov_b32 m0, s42
	v_lshl_add_u64 v[198:199], v[198:199], 0, s[44:45]
	global_load_lds_dwordx4 v[202:203], off
	s_add_i32 m0, s42, 0x2000
	s_nop 0
	global_load_lds_dwordx4 v[198:199], off
	v_lshl_add_u64 v[198:199], v[200:201], 0, s[50:51]
	s_mov_b32 m0, s35
	s_nop 0
	global_load_lds_dwordx4 v[198:199], off
	v_lshl_add_u64 v[198:199], v[200:201], 0, s[20:21]
	s_mov_b32 m0, s36
	s_nop 0
	global_load_lds_dwordx4 v[198:199], off
	s_waitcnt vmcnt(8)
	s_waitcnt lgkmcnt(0)
	s_barrier
	s_setprio 1
	v_mfma_f32_16x16x32_bf16 v[60:63], v[128:131], v[166:169], v[60:63]
	v_mfma_f32_16x16x32_bf16 v[56:59], v[140:143], v[166:169], v[56:59]
	v_mfma_f32_16x16x32_bf16 v[52:55], v[128:131], v[174:177], v[52:55]
	v_mfma_f32_16x16x32_bf16 v[48:51], v[140:143], v[174:177], v[48:51]
	v_mfma_f32_16x16x32_bf16 v[44:47], v[128:131], v[182:185], v[44:47]
	v_mfma_f32_16x16x32_bf16 v[40:43], v[140:143], v[182:185], v[40:43]
	v_mfma_f32_16x16x32_bf16 v[36:39], v[128:131], v[190:193], v[36:39]
	v_mfma_f32_16x16x32_bf16 v[32:35], v[140:143], v[190:193], v[32:35]
	s_setprio 0
	s_setprio 1
	v_mfma_f32_16x16x32_bf16 v[60:63], v[132:135], v[170:173], v[60:63]
	v_mfma_f32_16x16x32_bf16 v[56:59], v[144:147], v[170:173], v[56:59]
	v_mfma_f32_16x16x32_bf16 v[52:55], v[132:135], v[178:181], v[52:55]
	v_mfma_f32_16x16x32_bf16 v[48:51], v[144:147], v[178:181], v[48:51]
	v_mfma_f32_16x16x32_bf16 v[44:47], v[132:135], v[186:189], v[44:47]
	v_mfma_f32_16x16x32_bf16 v[40:43], v[144:147], v[186:189], v[40:43]
	v_mfma_f32_16x16x32_bf16 v[36:39], v[132:135], v[194:197], v[36:39]
	v_mfma_f32_16x16x32_bf16 v[32:35], v[144:147], v[194:197], v[32:35]
	s_setprio 0
	s_setprio 1
	v_mfma_f32_16x16x32_bf16 v[28:31], v[148:151], v[166:169], v[28:31]
	v_mfma_f32_16x16x32_bf16 v[24:27], v[156:159], v[166:169], v[24:27]
	v_mfma_f32_16x16x32_bf16 v[20:23], v[148:151], v[174:177], v[20:23]
	v_mfma_f32_16x16x32_bf16 v[16:19], v[156:159], v[174:177], v[16:19]
	v_mfma_f32_16x16x32_bf16 v[12:15], v[148:151], v[182:185], v[12:15]
	v_mfma_f32_16x16x32_bf16 v[8:11], v[156:159], v[182:185], v[8:11]
	v_mfma_f32_16x16x32_bf16 v[4:7], v[148:151], v[190:193], v[4:7]
	v_mfma_f32_16x16x32_bf16 v[0:3], v[156:159], v[190:193], v[0:3]
	s_setprio 0
	s_setprio 1
	v_mfma_f32_16x16x32_bf16 v[28:31], v[152:155], v[170:173], v[28:31]
	v_mfma_f32_16x16x32_bf16 v[24:27], v[162:165], v[170:173], v[24:27]
	v_mfma_f32_16x16x32_bf16 v[20:23], v[152:155], v[178:181], v[20:23]
	v_mfma_f32_16x16x32_bf16 v[16:19], v[162:165], v[178:181], v[16:19]
	v_mfma_f32_16x16x32_bf16 v[12:15], v[152:155], v[186:189], v[12:15]
	v_mfma_f32_16x16x32_bf16 v[8:11], v[162:165], v[186:189], v[8:11]
	v_mfma_f32_16x16x32_bf16 v[4:7], v[152:155], v[194:197], v[4:7]
	v_mfma_f32_16x16x32_bf16 v[0:3], v[162:165], v[194:197], v[0:3]
	s_setprio 0
	s_barrier
	s_add_i32 s46, s46, 2
	s_add_u32 s71, s71, 0x100
	s_addc_u32 s79, s79, 0
	s_add_u32 s10, s10, 0x100
	s_addc_u32 s11, s11, 0
	s_cmp_gt_u32 s46, 29
	s_cbranch_scc0 .LBB0_751
	s_and_b64 vcc, exec, s[4:5]
	s_cbranch_vccz .LBB0_754
	s_barrier

; #define PG8_STAGE(bufoff, gbase, voff) do { _Pragma("unroll") for (int _i = 0; _i < 2; ++_i) \
;         __builtin_amdgcn_global_load_lds((const GAS unsigned*)((const GAS char*)(gbase) + (size_t)_i * r64##voff + (vo##voff)), (LAS unsigned*)(lds + (bufoff) + ldsw + _i * 8192), 16, 0, 0); } while (0)
; #define PG8_LDA(dst, b, h) do { _Pragma("unroll") for (int m = 0; m < 4; ++m) _Pragma("unroll") for (int k = 0; k < 2; ++k) dst[m][k] = *(const LAS bf16x8*)(lds + PG8_SA(b, h) + aoff + m * 2048 + k * 1024); } while (0)
; #define PG8_LDB(dst, b, h) do { _Pragma("unroll") for (int n = 0; n < 2; ++n) _Pragma("unroll") for (int k = 0; k < 2; ++k) dst[n][k] = *(const LAS bf16x8*)(lds + PG8_SB(b, h) + boff + n * 2048 + k * 1024); } while (0)
; #define PG8_BAR __builtin_amdgcn_s_barrier()
; template <class Epi, class Map, bool ALIGN_EPI>
; __device__ __forceinline__ void gemm_phase(const int tid, LAS unsigned char* lds, const int lda, const int ldb, const int K, const Map& MP, const StaticOrder& S, const Epi& E) {
;     ...
;         for (int t = 0; t < nt; t += 2) {
;             const bool last = (t == nt - 2);
;             const char* a1 = cA + (size_t)(t + 1) * kstep;
;             const char* a2 = last ? nA : cA + (size_t)(t + 2) * kstep; const char* b2 = last ? nB : cB + (size_t)(t + 2) * kstep;
;             const char* a3 = a2 + kstep; const char* b3 = b2 + kstep;
;             PG8_LDB(B0, 0, 0); PG8_LDB(B1, 0, 1); PG8_SCHED; PG8_LDA(At, 0, 0); PG8_STAGE(PG8_SA(1, 1), a1 + hstepA, A);
;             PG8_WAIT_V(8); PG8_WAIT_L(0); PG8_BAR; PG8_MMA(0, 0, At, B0); PG8_MMA(0, 1, At, B1); PG8_BAR; PG8_SCHED;
;             PG8_LDA(At, 0, 1); PG8_STAGE(PG8_SB(0, 0), b2, B); PG8_STAGE(PG8_SB(0, 1), b2 + hstepB, B); PG8_STAGE(PG8_SA(0, 0), a2, A);
;             PG8_WAIT_V(8); PG8_WAIT_L(0); PG8_BAR; PG8_MMA(1, 0, At, B0); PG8_MMA(1, 1, At, B1); PG8_BAR; PG8_SCHED;
;             PG8_LDB(B0, 1, 0); PG8_LDB(B1, 1, 1); PG8_SCHED; PG8_LDA(At, 1, 0); PG8_STAGE(PG8_SA(0, 1), a2 + hstepA, A);
;             PG8_WAIT_V(8); PG8_WAIT_L(0); PG8_BAR; PG8_MMA(0, 0, At, B0); PG8_MMA(0, 1, At, B1); PG8_BAR; PG8_SCHED;
;             PG8_LDA(At, 1, 1); PG8_STAGE(PG8_SB(1, 0), b3, B); PG8_STAGE(PG8_SB(1, 1), b3 + hstepB, B); PG8_STAGE(PG8_SA(1, 0), a3, A);
;             PG8_WAIT_V(8); PG8_WAIT_L(0); PG8_BAR; PG8_MMA(1, 0, At, B0); PG8_MMA(1, 1, At, B1); PG8_BAR; PG8_SCHED;
;         }
.LBB0_835:
	s_add_u32 s44, s42, 0xfffc0080
	s_addc_u32 s45, s43, -1
	s_add_i32 s47, 0, 0x10000
	s_cmp_eq_u32 s46, 12
	s_cselect_b32 s45, s23, s45
	s_cselect_b32 s44, s22, s44
	s_cselect_b32 s57, s49, s21
	s_cselect_b32 s56, s48, s17
	s_add_i32 s53, 0, 0x14000
	s_waitcnt vmcnt(0)
	v_add_u32_e32 v60, s47, v150
	v_add_u32_e32 v148, s53, v150
	ds_read_b128 v[48:51], v60
	ds_read_b128 v[52:55], v60 offset:1024
	ds_read_b128 v[56:59], v60 offset:2048
	ds_read_b128 v[60:63], v60 offset:3072
	ds_read_b128 v[152:155], v148
	ds_read_b128 v[156:159], v148 offset:1024
	ds_read_b128 v[160:163], v148 offset:2048
	ds_read_b128 v[164:167], v148 offset:3072
	v_lshl_add_u64 v[148:149], s[42:43], 0, v[146:147]
	s_add_i32 m0, s19, 0xc000
	ds_read_b128 v[168:171], v151
	ds_read_b128 v[172:175], v151 offset:1024
	ds_read_b128 v[176:179], v151 offset:2048
	ds_read_b128 v[180:183], v151 offset:3072
	ds_read_b128 v[184:187], v151 offset:4096
	ds_read_b128 v[188:191], v151 offset:5120
	ds_read_b128 v[192:195], v151 offset:6144
	ds_read_b128 v[196:199], v151 offset:7168
	global_load_lds_dwordx4 v[148:149], off
	v_lshl_add_u64 v[148:149], v[148:149], 0, s[90:91]
	s_add_i32 m0, s19, 0xe000
	s_nop 0
	global_load_lds_dwordx4 v[148:149], off
	s_waitcnt vmcnt(8)
	s_waitcnt lgkmcnt(0)
	s_barrier
	s_setprio 1
	v_mfma_f32_16x16x32_bf16 v[136:139], v[48:51], v[168:171], v[136:139]
	v_mfma_f32_16x16x32_bf16 v[140:143], v[56:59], v[168:171], v[140:143]
	v_mfma_f32_16x16x32_bf16 v[120:123], v[48:51], v[176:179], v[120:123]
	v_mfma_f32_16x16x32_bf16 v[124:127], v[56:59], v[176:179], v[124:127]
	v_mfma_f32_16x16x32_bf16 v[104:107], v[48:51], v[184:187], v[104:107]
	v_mfma_f32_16x16x32_bf16 v[108:111], v[56:59], v[184:187], v[108:111]
	v_mfma_f32_16x16x32_bf16 v[88:91], v[48:51], v[192:195], v[88:91]
	v_mfma_f32_16x16x32_bf16 v[92:95], v[56:59], v[192:195], v[92:95]
	s_setprio 0
	s_setprio 1
	v_mfma_f32_16x16x32_bf16 v[136:139], v[52:55], v[172:175], v[136:139]
	v_mfma_f32_16x16x32_bf16 v[140:143], v[60:63], v[172:175], v[140:143]
	v_mfma_f32_16x16x32_bf16 v[120:123], v[52:55], v[180:183], v[120:123]
	v_mfma_f32_16x16x32_bf16 v[124:127], v[60:63], v[180:183], v[124:127]
	v_mfma_f32_16x16x32_bf16 v[104:107], v[52:55], v[188:191], v[104:107]
	v_mfma_f32_16x16x32_bf16 v[108:111], v[60:63], v[188:191], v[108:111]
	v_mfma_f32_16x16x32_bf16 v[88:91], v[52:55], v[196:199], v[88:91]
	v_mfma_f32_16x16x32_bf16 v[92:95], v[60:63], v[196:199], v[92:95]
	s_setprio 0
	s_setprio 1
	v_mfma_f32_16x16x32_bf16 v[132:135], v[152:155], v[168:171], v[132:135]
	v_mfma_f32_16x16x32_bf16 v[128:131], v[160:163], v[168:171], v[128:131]
	v_mfma_f32_16x16x32_bf16 v[116:119], v[152:155], v[176:179], v[116:119]
	v_mfma_f32_16x16x32_bf16 v[112:115], v[160:163], v[176:179], v[112:115]
	v_mfma_f32_16x16x32_bf16 v[100:103], v[152:155], v[184:187], v[100:103]
	v_mfma_f32_16x16x32_bf16 v[96:99], v[160:163], v[184:187], v[96:99]
	v_mfma_f32_16x16x32_bf16 v[84:87], v[152:155], v[192:195], v[84:87]
	v_mfma_f32_16x16x32_bf16 v[80:83], v[160:163], v[192:195], v[80:83]
	s_setprio 0
	s_setprio 1
	v_mfma_f32_16x16x32_bf16 v[132:135], v[156:159], v[172:175], v[132:135]
	v_mfma_f32_16x16x32_bf16 v[128:131], v[164:167], v[172:175], v[128:131]
	v_mfma_f32_16x16x32_bf16 v[116:119], v[156:159], v[180:183], v[116:119]
	v_mfma_f32_16x16x32_bf16 v[112:115], v[164:167], v[180:183], v[112:115]
	v_mfma_f32_16x16x32_bf16 v[100:103], v[156:159], v[188:191], v[100:103]
	v_mfma_f32_16x16x32_bf16 v[96:99], v[164:167], v[188:191], v[96:99]
	v_mfma_f32_16x16x32_bf16 v[84:87], v[156:159], v[196:199], v[84:87]
	v_mfma_f32_16x16x32_bf16 v[80:83], v[164:167], v[196:199], v[80:83]
	s_setprio 0
	s_barrier
	s_add_i32 s47, s47, s18
	v_lshl_add_u64 v[148:149], s[56:57], 0, v[144:145]
	s_mov_b32 m0, s47
	ds_read_b128 v[168:171], v151 offset:16384
	ds_read_b128 v[172:175], v151 offset:17408
	ds_read_b128 v[176:179], v151 offset:18432
	ds_read_b128 v[180:183], v151 offset:19456
	ds_read_b128 v[184:187], v151 offset:20480
	ds_read_b128 v[188:191], v151 offset:21504
	ds_read_b128 v[192:195], v151 offset:22528
	ds_read_b128 v[196:199], v151 offset:23552
	global_load_lds_dwordx4 v[148:149], off
	v_lshl_add_u64 v[200:201], v[148:149], 0, s[90:91]
	s_add_i32 m0, s47, 0x2000
	s_add_i32 s47, s53, s18
	global_load_lds_dwordx4 v[200:201], off
	v_lshl_add_u64 v[200:201], v[148:149], 0, s[74:75]
	s_mov_b32 m0, s47
	s_nop 0
	global_load_lds_dwordx4 v[200:201], off
	v_lshl_add_u64 v[200:201], v[148:149], 0, s[94:95]
	s_add_i32 m0, s47, 0x2000
	s_nop 0
	global_load_lds_dwordx4 v[200:201], off
	v_lshl_add_u64 v[200:201], s[44:45], 0, v[146:147]
	s_mov_b32 m0, s19
	v_lshl_add_u64 v[202:203], v[200:201], 0, s[90:91]
	global_load_lds_dwordx4 v[200:201], off
	s_mov_b32 m0, s24
	s_nop 0
	global_load_lds_dwordx4 v[202:203], off
	s_waitcnt vmcnt(8)
	s_waitcnt lgkmcnt(0)
	s_barrier
; #define PG8_STAGE(bufoff, gbase, voff) do { _Pragma("unroll") for (int _i = 0; _i < 2; ++_i) \
;         __builtin_amdgcn_global_load_lds((const GAS unsigned*)((const GAS char*)(gbase) + (size_t)_i * r64##voff + (vo##voff)), (LAS unsigned*)(lds + (bufoff) + ldsw + _i * 8192), 16, 0, 0); } while (0)
; #define PG8_LDA(dst, b, h) do { _Pragma("unroll") for (int m = 0; m < 4; ++m) _Pragma("unroll") for (int k = 0; k < 2; ++k) dst[m][k] = *(const LAS bf16x8*)(lds + PG8_SA(b, h) + aoff + m * 2048 + k * 1024); } while (0)
; #define PG8_LDB(dst, b, h) do { _Pragma("unroll") for (int n = 0; n < 2; ++n) _Pragma("unroll") for (int k = 0; k < 2; ++k) dst[n][k] = *(const LAS bf16x8*)(lds + PG8_SB(b, h) + boff + n * 2048 + k * 1024); } while (0)
; #define PG8_BAR __builtin_amdgcn_s_barrier()
; template <class Epi, class Map, bool ALIGN_EPI>
; __device__ __forceinline__ void gemm_phase(const int tid, LAS unsigned char* lds, const int lda, const int ldb, const int K, const Map& MP, const StaticOrder& S, const Epi& E) {
;     ...
;         for (int t = 0; t < nt; t += 2) {
;             const bool last = (t == nt - 2);
;             const char* a1 = cA + (size_t)(t + 1) * kstep;
;             const char* a2 = last ? nA : cA + (size_t)(t + 2) * kstep; const char* b2 = last ? nB : cB + (size_t)(t + 2) * kstep;
;             const char* a3 = a2 + kstep; const char* b3 = b2 + kstep;
;             PG8_LDB(B0, 0, 0); PG8_LDB(B1, 0, 1); PG8_SCHED; PG8_LDA(At, 0, 0); PG8_STAGE(PG8_SA(1, 1), a1 + hstepA, A);
;             PG8_WAIT_V(8); PG8_WAIT_L(0); PG8_BAR; PG8_MMA(0, 0, At, B0); PG8_MMA(0, 1, At, B1); PG8_BAR; PG8_SCHED;
;             PG8_LDA(At, 0, 1); PG8_STAGE(PG8_SB(0, 0), b2, B); PG8_STAGE(PG8_SB(0, 1), b2 + hstepB, B); PG8_STAGE(PG8_SA(0, 0), a2, A);
;             PG8_WAIT_V(8); PG8_WAIT_L(0); PG8_BAR; PG8_MMA(1, 0, At, B0); PG8_MMA(1, 1, At, B1); PG8_BAR; PG8_SCHED;
;             PG8_LDB(B0, 1, 0); PG8_LDB(B1, 1, 1); PG8_SCHED; PG8_LDA(At, 1, 0); PG8_STAGE(PG8_SA(0, 1), a2 + hstepA, A);
;             PG8_WAIT_V(8); PG8_WAIT_L(0); PG8_BAR; PG8_MMA(0, 0, At, B0); PG8_MMA(0, 1, At, B1); PG8_BAR; PG8_SCHED;
;             PG8_LDA(At, 1, 1); PG8_STAGE(PG8_SB(1, 0), b3, B); PG8_STAGE(PG8_SB(1, 1), b3 + hstepB, B); PG8_STAGE(PG8_SA(1, 0), a3, A);
;             PG8_WAIT_V(8); PG8_WAIT_L(0); PG8_BAR; PG8_MMA(1, 0, At, B0); PG8_MMA(1, 1, At, B1); PG8_BAR; PG8_SCHED;
;         }
	s_setprio 1
	v_mfma_f32_16x16x32_bf16 v[72:75], v[48:51], v[168:171], v[72:75]
	v_mfma_f32_16x16x32_bf16 v[76:79], v[56:59], v[168:171], v[76:79]
	v_mfma_f32_16x16x32_bf16 v[40:43], v[48:51], v[176:179], v[40:43]
	v_mfma_f32_16x16x32_bf16 v[44:47], v[56:59], v[176:179], v[44:47]
	v_mfma_f32_16x16x32_bf16 v[24:27], v[48:51], v[184:187], v[24:27]
	v_mfma_f32_16x16x32_bf16 v[28:31], v[56:59], v[184:187], v[28:31]
	v_mfma_f32_16x16x32_bf16 v[8:11], v[48:51], v[192:195], v[8:11]
	v_mfma_f32_16x16x32_bf16 v[12:15], v[56:59], v[192:195], v[12:15]
	s_setprio 0
	s_setprio 1
	v_mfma_f32_16x16x32_bf16 v[72:75], v[52:55], v[172:175], v[72:75]
	v_mfma_f32_16x16x32_bf16 v[76:79], v[60:63], v[172:175], v[76:79]
	v_mfma_f32_16x16x32_bf16 v[40:43], v[52:55], v[180:183], v[40:43]
	v_mfma_f32_16x16x32_bf16 v[44:47], v[60:63], v[180:183], v[44:47]
	v_mfma_f32_16x16x32_bf16 v[24:27], v[52:55], v[188:191], v[24:27]
	v_mfma_f32_16x16x32_bf16 v[28:31], v[60:63], v[188:191], v[28:31]
	v_mfma_f32_16x16x32_bf16 v[8:11], v[52:55], v[196:199], v[8:11]
	v_mfma_f32_16x16x32_bf16 v[12:15], v[60:63], v[196:199], v[12:15]
	s_setprio 0
	s_setprio 1
	v_mfma_f32_16x16x32_bf16 v[36:39], v[152:155], v[176:179], v[36:39]
	v_mfma_f32_16x16x32_bf16 v[32:35], v[160:163], v[176:179], v[32:35]
	v_mfma_f32_16x16x32_bf16 v[20:23], v[152:155], v[184:187], v[20:23]
	v_mfma_f32_16x16x32_bf16 v[16:19], v[160:163], v[184:187], v[16:19]
	v_mfma_f32_16x16x32_bf16 v[4:7], v[152:155], v[192:195], v[4:7]
	v_mfma_f32_16x16x32_bf16 v[0:3], v[160:163], v[192:195], v[0:3]
	v_mfma_f32_16x16x32_bf16 v[48:51], v[152:155], v[168:171], v[68:71]
	v_mfma_f32_16x16x32_bf16 v[52:55], v[160:163], v[168:171], v[64:67]
	s_setprio 0
	s_setprio 1
	v_mfma_f32_16x16x32_bf16 v[36:39], v[156:159], v[180:183], v[36:39]
	v_mfma_f32_16x16x32_bf16 v[32:35], v[164:167], v[180:183], v[32:35]
	v_mfma_f32_16x16x32_bf16 v[20:23], v[156:159], v[188:191], v[20:23]
	v_mfma_f32_16x16x32_bf16 v[16:19], v[164:167], v[188:191], v[16:19]
	v_mfma_f32_16x16x32_bf16 v[4:7], v[156:159], v[196:199], v[4:7]
	v_mfma_f32_16x16x32_bf16 v[0:3], v[164:167], v[196:199], v[0:3]
	v_mfma_f32_16x16x32_bf16 v[48:51], v[156:159], v[172:175], v[48:51]
	v_mfma_f32_16x16x32_bf16 v[52:55], v[164:167], v[172:175], v[52:55]
	s_setprio 0
	s_barrier
	s_add_i32 s44, 0, 0x18000
	s_add_i32 s45, 0, 0x1c000
	v_add_u32_e32 v68, s44, v150
	v_add_u32_e32 v164, s45, v150
	ds_read_b128 v[56:59], v68
	ds_read_b128 v[60:63], v68 offset:1024
	ds_read_b128 v[64:67], v68 offset:2048
	ds_read_b128 v[68:71], v68 offset:3072
	ds_read_b128 v[152:155], v164
	ds_read_b128 v[156:159], v164 offset:1024
	ds_read_b128 v[160:163], v164 offset:2048
	ds_read_b128 v[164:167], v164 offset:3072
	s_mov_b32 m0, s28
	v_lshl_add_u64 v[202:203], v[200:201], 0, s[74:75]
	ds_read_b128 v[168:171], v151 offset:32768
	ds_read_b128 v[172:175], v151 offset:33792
	ds_read_b128 v[176:179], v151 offset:34816
	ds_read_b128 v[180:183], v151 offset:35840
	ds_read_b128 v[184:187], v151 offset:36864
	ds_read_b128 v[188:191], v151 offset:37888
	ds_read_b128 v[192:195], v151 offset:38912
	ds_read_b128 v[196:199], v151 offset:39936
	global_load_lds_dwordx4 v[202:203], off
	v_lshl_add_u64 v[202:203], v[200:201], 0, s[94:95]
	s_mov_b32 m0, s29
	s_nop 0
	global_load_lds_dwordx4 v[202:203], off
	s_waitcnt vmcnt(8)
	s_waitcnt lgkmcnt(0)
	s_barrier
	s_setprio 1
	v_mfma_f32_16x16x32_bf16 v[136:139], v[56:59], v[168:171], v[136:139]
	v_mfma_f32_16x16x32_bf16 v[140:143], v[64:67], v[168:171], v[140:143]
	v_mfma_f32_16x16x32_bf16 v[120:123], v[56:59], v[176:179], v[120:123]
	v_mfma_f32_16x16x32_bf16 v[124:127], v[64:67], v[176:179], v[124:127]
	v_mfma_f32_16x16x32_bf16 v[104:107], v[56:59], v[184:187], v[104:107]
	v_mfma_f32_16x16x32_bf16 v[108:111], v[64:67], v[184:187], v[108:111]
	v_mfma_f32_16x16x32_bf16 v[88:91], v[56:59], v[192:195], v[88:91]
	v_mfma_f32_16x16x32_bf16 v[92:95], v[64:67], v[192:195], v[92:95]
	s_setprio 0
	s_setprio 1
	v_mfma_f32_16x16x32_bf16 v[136:139], v[60:63], v[172:175], v[136:139]
	v_mfma_f32_16x16x32_bf16 v[140:143], v[68:71], v[172:175], v[140:143]
	v_mfma_f32_16x16x32_bf16 v[120:123], v[60:63], v[180:183], v[120:123]
	v_mfma_f32_16x16x32_bf16 v[124:127], v[68:71], v[180:183], v[124:127]
	v_mfma_f32_16x16x32_bf16 v[104:107], v[60:63], v[188:191], v[104:107]
	v_mfma_f32_16x16x32_bf16 v[108:111], v[68:71], v[188:191], v[108:111]
	v_mfma_f32_16x16x32_bf16 v[88:91], v[60:63], v[196:199], v[88:91]
	v_mfma_f32_16x16x32_bf16 v[92:95], v[68:71], v[196:199], v[92:95]
	s_setprio 0
	s_setprio 1
	v_mfma_f32_16x16x32_bf16 v[132:135], v[152:155], v[168:171], v[132:135]
	v_mfma_f32_16x16x32_bf16 v[128:131], v[160:163], v[168:171], v[128:131]
	v_mfma_f32_16x16x32_bf16 v[116:119], v[152:155], v[176:179], v[116:119]
	v_mfma_f32_16x16x32_bf16 v[112:115], v[160:163], v[176:179], v[112:115]
	v_mfma_f32_16x16x32_bf16 v[100:103], v[152:155], v[184:187], v[100:103]
	v_mfma_f32_16x16x32_bf16 v[96:99], v[160:163], v[184:187], v[96:99]
	v_mfma_f32_16x16x32_bf16 v[84:87], v[152:155], v[192:195], v[84:87]
	v_mfma_f32_16x16x32_bf16 v[80:83], v[160:163], v[192:195], v[80:83]
	s_setprio 0
	s_setprio 1
	v_mfma_f32_16x16x32_bf16 v[132:135], v[156:159], v[172:175], v[132:135]
	v_mfma_f32_16x16x32_bf16 v[128:131], v[164:167], v[172:175], v[128:131]
	v_mfma_f32_16x16x32_bf16 v[116:119], v[156:159], v[180:183], v[116:119]
	v_mfma_f32_16x16x32_bf16 v[112:115], v[164:167], v[180:183], v[112:115]
	v_mfma_f32_16x16x32_bf16 v[100:103], v[156:159], v[188:191], v[100:103]
	v_mfma_f32_16x16x32_bf16 v[96:99], v[164:167], v[188:191], v[96:99]
	v_mfma_f32_16x16x32_bf16 v[84:87], v[156:159], v[196:199], v[84:87]
	v_mfma_f32_16x16x32_bf16 v[80:83], v[164:167], v[196:199], v[80:83]
	s_setprio 0
	s_barrier
; #define PG8_STAGE(bufoff, gbase, voff) do { _Pragma("unroll") for (int _i = 0; _i < 2; ++_i) \
;         __builtin_amdgcn_global_load_lds((const GAS unsigned*)((const GAS char*)(gbase) + (size_t)_i * r64##voff + (vo##voff)), (LAS unsigned*)(lds + (bufoff) + ldsw + _i * 8192), 16, 0, 0); } while (0)
; #define PG8_LDA(dst, b, h) do { _Pragma("unroll") for (int m = 0; m < 4; ++m) _Pragma("unroll") for (int k = 0; k < 2; ++k) dst[m][k] = *(const LAS bf16x8*)(lds + PG8_SA(b, h) + aoff + m * 2048 + k * 1024); } while (0)
; #define PG8_LDB(dst, b, h) do { _Pragma("unroll") for (int n = 0; n < 2; ++n) _Pragma("unroll") for (int k = 0; k < 2; ++k) dst[n][k] = *(const LAS bf16x8*)(lds + PG8_SB(b, h) + boff + n * 2048 + k * 1024); } while (0)
; #define PG8_BAR __builtin_amdgcn_s_barrier()
; template <class Epi, class Map, bool ALIGN_EPI>
; __device__ __forceinline__ void gemm_phase(const int tid, LAS unsigned char* lds, const int lda, const int ldb, const int K, const Map& MP, const StaticOrder& S, const Epi& E) {
;     ...
;         for (int t = 0; t < nt; t += 2) {
;             const bool last = (t == nt - 2);
;             const char* a1 = cA + (size_t)(t + 1) * kstep;
;             const char* a2 = last ? nA : cA + (size_t)(t + 2) * kstep; const char* b2 = last ? nB : cB + (size_t)(t + 2) * kstep;
;             const char* a3 = a2 + kstep; const char* b3 = b2 + kstep;
;             PG8_LDB(B0, 0, 0); PG8_LDB(B1, 0, 1); PG8_SCHED; PG8_LDA(At, 0, 0); PG8_STAGE(PG8_SA(1, 1), a1 + hstepA, A);
;             PG8_WAIT_V(8); PG8_WAIT_L(0); PG8_BAR; PG8_MMA(0, 0, At, B0); PG8_MMA(0, 1, At, B1); PG8_BAR; PG8_SCHED;
;             PG8_LDA(At, 0, 1); PG8_STAGE(PG8_SB(0, 0), b2, B); PG8_STAGE(PG8_SB(0, 1), b2 + hstepB, B); PG8_STAGE(PG8_SA(0, 0), a2, A);
;             PG8_WAIT_V(8); PG8_WAIT_L(0); PG8_BAR; PG8_MMA(1, 0, At, B0); PG8_MMA(1, 1, At, B1); PG8_BAR; PG8_SCHED;
;             PG8_LDB(B0, 1, 0); PG8_LDB(B1, 1, 1); PG8_SCHED; PG8_LDA(At, 1, 0); PG8_STAGE(PG8_SA(0, 1), a2 + hstepA, A);
;             PG8_WAIT_V(8); PG8_WAIT_L(0); PG8_BAR; PG8_MMA(0, 0, At, B0); PG8_MMA(0, 1, At, B1); PG8_BAR; PG8_SCHED;
;             PG8_LDA(At, 1, 1); PG8_STAGE(PG8_SB(1, 0), b3, B); PG8_STAGE(PG8_SB(1, 1), b3 + hstepB, B); PG8_STAGE(PG8_SA(1, 0), a3, A);
;             PG8_WAIT_V(8); PG8_WAIT_L(0); PG8_BAR; PG8_MMA(1, 0, At, B0); PG8_MMA(1, 1, At, B1); PG8_BAR; PG8_SCHED;
;         }
	s_add_i32 s44, s44, s18
	v_lshl_add_u64 v[202:203], v[148:149], 0, s[50:51]
	s_mov_b32 m0, s44
	ds_read_b128 v[168:171], v151 offset:49152
	ds_read_b128 v[172:175], v151 offset:50176
	ds_read_b128 v[176:179], v151 offset:51200
	ds_read_b128 v[180:183], v151 offset:52224
	ds_read_b128 v[184:187], v151 offset:53248
	ds_read_b128 v[188:191], v151 offset:54272
	ds_read_b128 v[192:195], v151 offset:55296
	ds_read_b128 v[196:199], v151 offset:56320
	global_load_lds_dwordx4 v[202:203], off
	v_lshl_add_u64 v[202:203], v[148:149], 0, s[54:55]
	s_add_i32 m0, s44, 0x2000
	s_add_i32 s44, s45, s18
	global_load_lds_dwordx4 v[202:203], off
	v_lshl_add_u64 v[202:203], v[148:149], 0, s[96:97]
	s_mov_b32 m0, s44
	v_lshl_add_u64 v[148:149], v[148:149], 0, s[6:7]
	global_load_lds_dwordx4 v[202:203], off
	s_add_i32 m0, s44, 0x2000
	s_nop 0
	global_load_lds_dwordx4 v[148:149], off
	v_lshl_add_u64 v[148:149], v[200:201], 0, s[50:51]
	s_mov_b32 m0, s33
	s_nop 0
	global_load_lds_dwordx4 v[148:149], off
	v_lshl_add_u64 v[148:149], v[200:201], 0, s[54:55]
	s_mov_b32 m0, s34
	s_nop 0
	global_load_lds_dwordx4 v[148:149], off
	s_waitcnt vmcnt(8)
	s_waitcnt lgkmcnt(0)
	s_barrier
	s_setprio 1
	v_mfma_f32_16x16x32_bf16 v[72:75], v[56:59], v[168:171], v[72:75]
	v_mfma_f32_16x16x32_bf16 v[76:79], v[64:67], v[168:171], v[76:79]
	v_mfma_f32_16x16x32_bf16 v[40:43], v[56:59], v[176:179], v[40:43]
	v_mfma_f32_16x16x32_bf16 v[44:47], v[64:67], v[176:179], v[44:47]
	v_mfma_f32_16x16x32_bf16 v[24:27], v[56:59], v[184:187], v[24:27]
	v_mfma_f32_16x16x32_bf16 v[28:31], v[64:67], v[184:187], v[28:31]
	v_mfma_f32_16x16x32_bf16 v[8:11], v[56:59], v[192:195], v[8:11]
	v_mfma_f32_16x16x32_bf16 v[12:15], v[64:67], v[192:195], v[12:15]
	s_setprio 0
	s_setprio 1
	v_mfma_f32_16x16x32_bf16 v[72:75], v[60:63], v[172:175], v[72:75]
	v_mfma_f32_16x16x32_bf16 v[76:79], v[68:71], v[172:175], v[76:79]
	v_mfma_f32_16x16x32_bf16 v[40:43], v[60:63], v[180:183], v[40:43]
	v_mfma_f32_16x16x32_bf16 v[44:47], v[68:71], v[180:183], v[44:47]
	v_mfma_f32_16x16x32_bf16 v[24:27], v[60:63], v[188:191], v[24:27]
	v_mfma_f32_16x16x32_bf16 v[28:31], v[68:71], v[188:191], v[28:31]
	v_mfma_f32_16x16x32_bf16 v[8:11], v[60:63], v[196:199], v[8:11]
	v_mfma_f32_16x16x32_bf16 v[12:15], v[68:71], v[196:199], v[12:15]
	s_setprio 0
	s_setprio 1
	v_mfma_f32_16x16x32_bf16 v[48:51], v[152:155], v[168:171], v[48:51]
	v_mfma_f32_16x16x32_bf16 v[68:71], v[156:159], v[172:175], v[48:51]
	v_mfma_f32_16x16x32_bf16 v[48:51], v[160:163], v[168:171], v[52:55]
	v_mfma_f32_16x16x32_bf16 v[36:39], v[152:155], v[176:179], v[36:39]
	v_mfma_f32_16x16x32_bf16 v[32:35], v[160:163], v[176:179], v[32:35]
	v_mfma_f32_16x16x32_bf16 v[20:23], v[152:155], v[184:187], v[20:23]
	v_mfma_f32_16x16x32_bf16 v[16:19], v[160:163], v[184:187], v[16:19]
	v_mfma_f32_16x16x32_bf16 v[4:7], v[152:155], v[192:195], v[4:7]
	s_setprio 0
	s_setprio 1
	v_mfma_f32_16x16x32_bf16 v[0:3], v[160:163], v[192:195], v[0:3]
	v_mfma_f32_16x16x32_bf16 v[64:67], v[164:167], v[172:175], v[48:51]
	v_mfma_f32_16x16x32_bf16 v[36:39], v[156:159], v[180:183], v[36:39]
	v_mfma_f32_16x16x32_bf16 v[32:35], v[164:167], v[180:183], v[32:35]
	v_mfma_f32_16x16x32_bf16 v[20:23], v[156:159], v[188:191], v[20:23]
	v_mfma_f32_16x16x32_bf16 v[16:19], v[164:167], v[188:191], v[16:19]
	v_mfma_f32_16x16x32_bf16 v[4:7], v[156:159], v[196:199], v[4:7]
	v_mfma_f32_16x16x32_bf16 v[0:3], v[164:167], v[196:199], v[0:3]
	s_setprio 0
	s_barrier
	s_add_i32 s46, s46, 2
	s_add_u32 s17, s17, 0x100
	s_addc_u32 s21, s21, 0
	s_add_u32 s42, s42, 0x100
	s_addc_u32 s43, s43, 0
	s_cmp_gt_u32 s46, 13
	s_cbranch_scc0 .LBB0_835
	s_and_b64 vcc, exec, s[10:11]
	s_cbranch_vccz .LBB0_838
	s_barrier

; #define PG8_STAGE(bufoff, gbase, voff) do { _Pragma("unroll") for (int _i = 0; _i < 2; ++_i) \
;         __builtin_amdgcn_global_load_lds((const GAS unsigned*)((const GAS char*)(gbase) + (size_t)_i * r64##voff + (vo##voff)), (LAS unsigned*)(lds + (bufoff) + ldsw + _i * 8192), 16, 0, 0); } while (0)
; #define PG8_LDA(dst, b, h) do { _Pragma("unroll") for (int m = 0; m < 4; ++m) _Pragma("unroll") for (int k = 0; k < 2; ++k) dst[m][k] = *(const LAS bf16x8*)(lds + PG8_SA(b, h) + aoff + m * 2048 + k * 1024); } while (0)
; #define PG8_LDB(dst, b, h) do { _Pragma("unroll") for (int n = 0; n < 2; ++n) _Pragma("unroll") for (int k = 0; k < 2; ++k) dst[n][k] = *(const LAS bf16x8*)(lds + PG8_SB(b, h) + boff + n * 2048 + k * 1024); } while (0)
; #define PG8_BAR __builtin_amdgcn_s_barrier()
; template <class Epi, class Map, bool ALIGN_EPI>
; __device__ __forceinline__ void gemm_phase(const int tid, LAS unsigned char* lds, const int lda, const int ldb, const int K, const Map& MP, const StaticOrder& S, const Epi& E) {
;     ...
;         for (int t = 0; t < nt; t += 2) {
;             const bool last = (t == nt - 2);
;             const char* a1 = cA + (size_t)(t + 1) * kstep;
;             const char* a2 = last ? nA : cA + (size_t)(t + 2) * kstep; const char* b2 = last ? nB : cB + (size_t)(t + 2) * kstep;
;             const char* a3 = a2 + kstep; const char* b3 = b2 + kstep;
;             PG8_LDB(B0, 0, 0); PG8_LDB(B1, 0, 1); PG8_SCHED; PG8_LDA(At, 0, 0); PG8_STAGE(PG8_SA(1, 1), a1 + hstepA, A);
;             PG8_WAIT_V(8); PG8_WAIT_L(0); PG8_BAR; PG8_MMA(0, 0, At, B0); PG8_MMA(0, 1, At, B1); PG8_BAR; PG8_SCHED;
;             PG8_LDA(At, 0, 1); PG8_STAGE(PG8_SB(0, 0), b2, B); PG8_STAGE(PG8_SB(0, 1), b2 + hstepB, B); PG8_STAGE(PG8_SA(0, 0), a2, A);
;             PG8_WAIT_V(8); PG8_WAIT_L(0); PG8_BAR; PG8_MMA(1, 0, At, B0); PG8_MMA(1, 1, At, B1); PG8_BAR; PG8_SCHED;
;             PG8_LDB(B0, 1, 0); PG8_LDB(B1, 1, 1); PG8_SCHED; PG8_LDA(At, 1, 0); PG8_STAGE(PG8_SA(0, 1), a2 + hstepA, A);
;             PG8_WAIT_V(8); PG8_WAIT_L(0); PG8_BAR; PG8_MMA(0, 0, At, B0); PG8_MMA(0, 1, At, B1); PG8_BAR; PG8_SCHED;
;             PG8_LDA(At, 1, 1); PG8_STAGE(PG8_SB(1, 0), b3, B); PG8_STAGE(PG8_SB(1, 1), b3 + hstepB, B); PG8_STAGE(PG8_SA(1, 0), a3, A);
;             PG8_WAIT_V(8); PG8_WAIT_L(0); PG8_BAR; PG8_MMA(1, 0, At, B0); PG8_MMA(1, 1, At, B1); PG8_BAR; PG8_SCHED;
;         }
.LBB0_1042:
	s_add_i32 s47, s42, 2
	s_add_u32 s78, s10, 0x80
	s_addc_u32 s43, s11, 0
	s_add_i32 s80, 0, 0x10000
	s_cmp_eq_u32 s24, s42
	s_cselect_b32 s43, s69, s43
	s_cselect_b32 s42, s68, s78
	s_cselect_b32 s79, s77, s46
	s_cselect_b32 s78, s76, s45
	s_add_i32 s81, 0, 0x14000
	v_add_u32_e32 v140, s80, v178
	v_add_u32_e32 v156, s81, v178
	ds_read_b128 v[128:131], v140
	ds_read_b128 v[132:135], v140 offset:1024
	ds_read_b128 v[136:139], v140 offset:2048
	ds_read_b128 v[140:143], v140 offset:3072
	ds_read_b128 v[144:147], v156
	ds_read_b128 v[148:151], v156 offset:1024
	ds_read_b128 v[152:155], v156 offset:2048
	ds_read_b128 v[156:159], v156 offset:3072
	v_lshl_add_u64 v[176:177], s[10:11], 0, v[164:165]
	s_add_i32 m0, s34, 0xc000
	ds_read_b128 v[168:171], v179
	ds_read_b128 v[172:175], v179 offset:1024
	ds_read_b128 v[180:183], v179 offset:2048
	ds_read_b128 v[184:187], v179 offset:3072
	ds_read_b128 v[188:191], v179 offset:4096
	ds_read_b128 v[192:195], v179 offset:5120
	ds_read_b128 v[196:199], v179 offset:6144
	ds_read_b128 v[200:203], v179 offset:7168
	global_load_lds_dwordx4 v[176:177], off
	v_lshl_add_u64 v[176:177], s[10:11], 0, v[166:167]
	s_add_i32 m0, s34, 0xe000
	s_nop 0
	global_load_lds_dwordx4 v[176:177], off
	s_waitcnt vmcnt(8)
	s_waitcnt lgkmcnt(0)
	s_barrier
	s_setprio 1
	v_mfma_f32_16x16x32_bf16 v[40:43], v[128:131], v[168:171], v[40:43]
	v_mfma_f32_16x16x32_bf16 v[24:27], v[136:139], v[168:171], v[24:27]
	v_mfma_f32_16x16x32_bf16 v[32:35], v[128:131], v[180:183], v[32:35]
	v_mfma_f32_16x16x32_bf16 v[28:31], v[136:139], v[180:183], v[28:31]
	v_mfma_f32_16x16x32_bf16 v[52:55], v[128:131], v[188:191], v[52:55]
	v_mfma_f32_16x16x32_bf16 v[48:51], v[136:139], v[188:191], v[48:51]
	v_mfma_f32_16x16x32_bf16 v[68:71], v[128:131], v[196:199], v[68:71]
	v_mfma_f32_16x16x32_bf16 v[64:67], v[136:139], v[196:199], v[64:67]
	s_setprio 0
	s_setprio 1
	v_mfma_f32_16x16x32_bf16 v[40:43], v[132:135], v[172:175], v[40:43]
	v_mfma_f32_16x16x32_bf16 v[24:27], v[140:143], v[172:175], v[24:27]
	v_mfma_f32_16x16x32_bf16 v[32:35], v[132:135], v[184:187], v[32:35]
	v_mfma_f32_16x16x32_bf16 v[28:31], v[140:143], v[184:187], v[28:31]
	v_mfma_f32_16x16x32_bf16 v[52:55], v[132:135], v[192:195], v[52:55]
	v_mfma_f32_16x16x32_bf16 v[48:51], v[140:143], v[192:195], v[48:51]
	v_mfma_f32_16x16x32_bf16 v[68:71], v[132:135], v[200:203], v[68:71]
	v_mfma_f32_16x16x32_bf16 v[64:67], v[140:143], v[200:203], v[64:67]
	s_setprio 0
	s_setprio 1
	v_mfma_f32_16x16x32_bf16 v[0:3], v[144:147], v[168:171], v[0:3]
	v_mfma_f32_16x16x32_bf16 v[4:7], v[152:155], v[168:171], v[4:7]
	v_mfma_f32_16x16x32_bf16 v[8:11], v[144:147], v[180:183], v[8:11]
	v_mfma_f32_16x16x32_bf16 v[12:15], v[152:155], v[180:183], v[12:15]
	v_mfma_f32_16x16x32_bf16 v[16:19], v[144:147], v[188:191], v[16:19]
	v_mfma_f32_16x16x32_bf16 v[20:23], v[152:155], v[188:191], v[20:23]
	v_mfma_f32_16x16x32_bf16 v[36:39], v[144:147], v[196:199], v[36:39]
	v_mfma_f32_16x16x32_bf16 v[44:47], v[152:155], v[196:199], v[44:47]
	s_setprio 0
	s_setprio 1
	v_mfma_f32_16x16x32_bf16 v[0:3], v[148:151], v[172:175], v[0:3]
	v_mfma_f32_16x16x32_bf16 v[4:7], v[156:159], v[172:175], v[4:7]
	v_mfma_f32_16x16x32_bf16 v[8:11], v[148:151], v[184:187], v[8:11]
	v_mfma_f32_16x16x32_bf16 v[12:15], v[156:159], v[184:187], v[12:15]
	v_mfma_f32_16x16x32_bf16 v[16:19], v[148:151], v[192:195], v[16:19]
	v_mfma_f32_16x16x32_bf16 v[20:23], v[156:159], v[192:195], v[20:23]
	v_mfma_f32_16x16x32_bf16 v[36:39], v[148:151], v[200:203], v[36:39]
	v_mfma_f32_16x16x32_bf16 v[44:47], v[156:159], v[200:203], v[44:47]
	s_setprio 0
	s_barrier
	s_add_i32 s80, s80, s14
	v_lshl_add_u64 v[176:177], s[78:79], 0, v[160:161]
	s_mov_b32 m0, s80
	ds_read_b128 v[168:171], v179 offset:16384
	ds_read_b128 v[172:175], v179 offset:17408
	ds_read_b128 v[180:183], v179 offset:18432
	ds_read_b128 v[184:187], v179 offset:19456
	ds_read_b128 v[188:191], v179 offset:20480
	ds_read_b128 v[192:195], v179 offset:21504
	ds_read_b128 v[196:199], v179 offset:22528
	ds_read_b128 v[200:203], v179 offset:23552
	global_load_lds_dwordx4 v[176:177], off
	s_add_i32 m0, s80, 0x2000
	s_add_u32 s78, s78, s72
	v_lshl_add_u64 v[204:205], v[176:177], 0, s[2:3]
	s_addc_u32 s79, s79, 0
	global_load_lds_dwordx4 v[204:205], off
	v_lshl_add_u64 v[204:205], s[78:79], 0, v[160:161]
	s_add_i32 s78, s81, s14
	s_mov_b32 m0, s78
	v_lshl_add_u64 v[206:207], v[204:205], 0, s[2:3]
	global_load_lds_dwordx4 v[204:205], off
	s_add_i32 m0, s78, 0x2000
	s_nop 0
	global_load_lds_dwordx4 v[206:207], off
	v_lshl_add_u64 v[206:207], s[42:43], 0, v[162:163]
	s_mov_b32 m0, s34
	v_lshl_add_u64 v[208:209], v[206:207], 0, s[2:3]
	global_load_lds_dwordx4 v[206:207], off
	s_mov_b32 m0, s35
	s_nop 0
	global_load_lds_dwordx4 v[208:209], off
	s_waitcnt vmcnt(8)
	s_waitcnt lgkmcnt(0)
	s_barrier
; #define PG8_STAGE(bufoff, gbase, voff) do { _Pragma("unroll") for (int _i = 0; _i < 2; ++_i) \
;         __builtin_amdgcn_global_load_lds((const GAS unsigned*)((const GAS char*)(gbase) + (size_t)_i * r64##voff + (vo##voff)), (LAS unsigned*)(lds + (bufoff) + ldsw + _i * 8192), 16, 0, 0); } while (0)
; #define PG8_LDA(dst, b, h) do { _Pragma("unroll") for (int m = 0; m < 4; ++m) _Pragma("unroll") for (int k = 0; k < 2; ++k) dst[m][k] = *(const LAS bf16x8*)(lds + PG8_SA(b, h) + aoff + m * 2048 + k * 1024); } while (0)
; #define PG8_LDB(dst, b, h) do { _Pragma("unroll") for (int n = 0; n < 2; ++n) _Pragma("unroll") for (int k = 0; k < 2; ++k) dst[n][k] = *(const LAS bf16x8*)(lds + PG8_SB(b, h) + boff + n * 2048 + k * 1024); } while (0)
; #define PG8_BAR __builtin_amdgcn_s_barrier()
; template <class Epi, class Map, bool ALIGN_EPI>
; __device__ __forceinline__ void gemm_phase(const int tid, LAS unsigned char* lds, const int lda, const int ldb, const int K, const Map& MP, const StaticOrder& S, const Epi& E) {
;     ...
;         for (int t = 0; t < nt; t += 2) {
;             const bool last = (t == nt - 2);
;             const char* a1 = cA + (size_t)(t + 1) * kstep;
;             const char* a2 = last ? nA : cA + (size_t)(t + 2) * kstep; const char* b2 = last ? nB : cB + (size_t)(t + 2) * kstep;
;             const char* a3 = a2 + kstep; const char* b3 = b2 + kstep;
;             PG8_LDB(B0, 0, 0); PG8_LDB(B1, 0, 1); PG8_SCHED; PG8_LDA(At, 0, 0); PG8_STAGE(PG8_SA(1, 1), a1 + hstepA, A);
;             PG8_WAIT_V(8); PG8_WAIT_L(0); PG8_BAR; PG8_MMA(0, 0, At, B0); PG8_MMA(0, 1, At, B1); PG8_BAR; PG8_SCHED;
;             PG8_LDA(At, 0, 1); PG8_STAGE(PG8_SB(0, 0), b2, B); PG8_STAGE(PG8_SB(0, 1), b2 + hstepB, B); PG8_STAGE(PG8_SA(0, 0), a2, A);
;             PG8_WAIT_V(8); PG8_WAIT_L(0); PG8_BAR; PG8_MMA(1, 0, At, B0); PG8_MMA(1, 1, At, B1); PG8_BAR; PG8_SCHED;
;             PG8_LDB(B0, 1, 0); PG8_LDB(B1, 1, 1); PG8_SCHED; PG8_LDA(At, 1, 0); PG8_STAGE(PG8_SA(0, 1), a2 + hstepA, A);
;             PG8_WAIT_V(8); PG8_WAIT_L(0); PG8_BAR; PG8_MMA(0, 0, At, B0); PG8_MMA(0, 1, At, B1); PG8_BAR; PG8_SCHED;
;             PG8_LDA(At, 1, 1); PG8_STAGE(PG8_SB(1, 0), b3, B); PG8_STAGE(PG8_SB(1, 1), b3 + hstepB, B); PG8_STAGE(PG8_SA(1, 0), a3, A);
;             PG8_WAIT_V(8); PG8_WAIT_L(0); PG8_BAR; PG8_MMA(1, 0, At, B0); PG8_MMA(1, 1, At, B1); PG8_BAR; PG8_SCHED;
;         }
	s_setprio 1
	v_mfma_f32_16x16x32_bf16 v[84:87], v[128:131], v[168:171], v[84:87]
	v_mfma_f32_16x16x32_bf16 v[80:83], v[136:139], v[168:171], v[80:83]
	v_mfma_f32_16x16x32_bf16 v[116:119], v[128:131], v[180:183], v[116:119]
	v_mfma_f32_16x16x32_bf16 v[96:99], v[136:139], v[180:183], v[96:99]
	v_mfma_f32_16x16x32_bf16 v[124:127], v[128:131], v[188:191], v[124:127]
	v_mfma_f32_16x16x32_bf16 v[120:123], v[136:139], v[188:191], v[120:123]
	v_mfma_f32_16x16x32_bf16 v[108:111], v[128:131], v[196:199], v[108:111]
	v_mfma_f32_16x16x32_bf16 v[112:115], v[136:139], v[196:199], v[112:115]
	s_setprio 0
	s_setprio 1
	v_mfma_f32_16x16x32_bf16 v[84:87], v[132:135], v[172:175], v[84:87]
	v_mfma_f32_16x16x32_bf16 v[80:83], v[140:143], v[172:175], v[80:83]
	v_mfma_f32_16x16x32_bf16 v[116:119], v[132:135], v[184:187], v[116:119]
	v_mfma_f32_16x16x32_bf16 v[96:99], v[140:143], v[184:187], v[96:99]
	v_mfma_f32_16x16x32_bf16 v[124:127], v[132:135], v[192:195], v[124:127]
	v_mfma_f32_16x16x32_bf16 v[120:123], v[140:143], v[192:195], v[120:123]
	v_mfma_f32_16x16x32_bf16 v[108:111], v[132:135], v[200:203], v[108:111]
	v_mfma_f32_16x16x32_bf16 v[112:115], v[140:143], v[200:203], v[112:115]
	s_setprio 0
	s_setprio 1
	v_mfma_f32_16x16x32_bf16 v[56:59], v[144:147], v[168:171], v[56:59]
	v_mfma_f32_16x16x32_bf16 v[60:63], v[152:155], v[168:171], v[60:63]
	v_mfma_f32_16x16x32_bf16 v[72:75], v[144:147], v[180:183], v[72:75]
	v_mfma_f32_16x16x32_bf16 v[76:79], v[152:155], v[180:183], v[76:79]
	v_mfma_f32_16x16x32_bf16 v[92:95], v[144:147], v[188:191], v[92:95]
	v_mfma_f32_16x16x32_bf16 v[100:103], v[152:155], v[188:191], v[100:103]
	v_mfma_f32_16x16x32_bf16 v[104:107], v[144:147], v[196:199], v[104:107]
	v_mfma_f32_16x16x32_bf16 v[88:91], v[152:155], v[196:199], v[88:91]
	s_setprio 0
	s_setprio 1
	v_mfma_f32_16x16x32_bf16 v[56:59], v[148:151], v[172:175], v[56:59]
	v_mfma_f32_16x16x32_bf16 v[60:63], v[156:159], v[172:175], v[60:63]
	v_mfma_f32_16x16x32_bf16 v[72:75], v[148:151], v[184:187], v[72:75]
	v_mfma_f32_16x16x32_bf16 v[76:79], v[156:159], v[184:187], v[76:79]
	v_mfma_f32_16x16x32_bf16 v[92:95], v[148:151], v[192:195], v[92:95]
	v_mfma_f32_16x16x32_bf16 v[100:103], v[156:159], v[192:195], v[100:103]
	v_mfma_f32_16x16x32_bf16 v[104:107], v[148:151], v[200:203], v[104:107]
	v_mfma_f32_16x16x32_bf16 v[88:91], v[156:159], v[200:203], v[88:91]
	s_setprio 0
	s_barrier
	s_add_i32 s78, 0, 0x18000
	s_add_i32 s79, 0, 0x1c000
	v_add_u32_e32 v140, s78, v178
	v_add_u32_e32 v156, s79, v178
	ds_read_b128 v[128:131], v140
	ds_read_b128 v[132:135], v140 offset:1024
	ds_read_b128 v[136:139], v140 offset:2048
	ds_read_b128 v[140:143], v140 offset:3072
	ds_read_b128 v[144:147], v156
	ds_read_b128 v[148:151], v156 offset:1024
	ds_read_b128 v[152:155], v156 offset:2048
	ds_read_b128 v[156:159], v156 offset:3072
	s_add_u32 s42, s42, s72
	s_addc_u32 s43, s43, 0
	s_mov_b32 m0, s36
	v_lshl_add_u64 v[210:211], s[42:43], 0, v[162:163]
	ds_read_b128 v[168:171], v179 offset:32768
	ds_read_b128 v[172:175], v179 offset:33792
	ds_read_b128 v[180:183], v179 offset:34816
	ds_read_b128 v[184:187], v179 offset:35840
	ds_read_b128 v[188:191], v179 offset:36864
	ds_read_b128 v[192:195], v179 offset:37888
	ds_read_b128 v[196:199], v179 offset:38912
	ds_read_b128 v[200:203], v179 offset:39936
	global_load_lds_dwordx4 v[210:211], off
	v_lshl_add_u64 v[210:211], v[210:211], 0, s[2:3]
	s_mov_b32 m0, s37
	s_nop 0
	global_load_lds_dwordx4 v[210:211], off
	s_waitcnt vmcnt(8)
	s_waitcnt lgkmcnt(0)
	s_barrier
	s_setprio 1
	v_mfma_f32_16x16x32_bf16 v[40:43], v[128:131], v[168:171], v[40:43]
	v_mfma_f32_16x16x32_bf16 v[24:27], v[136:139], v[168:171], v[24:27]
	v_mfma_f32_16x16x32_bf16 v[32:35], v[128:131], v[180:183], v[32:35]
	v_mfma_f32_16x16x32_bf16 v[28:31], v[136:139], v[180:183], v[28:31]
	v_mfma_f32_16x16x32_bf16 v[52:55], v[128:131], v[188:191], v[52:55]
	v_mfma_f32_16x16x32_bf16 v[48:51], v[136:139], v[188:191], v[48:51]
	v_mfma_f32_16x16x32_bf16 v[68:71], v[128:131], v[196:199], v[68:71]
	v_mfma_f32_16x16x32_bf16 v[64:67], v[136:139], v[196:199], v[64:67]
	s_setprio 0
	s_setprio 1
	v_mfma_f32_16x16x32_bf16 v[40:43], v[132:135], v[172:175], v[40:43]
	v_mfma_f32_16x16x32_bf16 v[24:27], v[140:143], v[172:175], v[24:27]
	v_mfma_f32_16x16x32_bf16 v[32:35], v[132:135], v[184:187], v[32:35]
	v_mfma_f32_16x16x32_bf16 v[28:31], v[140:143], v[184:187], v[28:31]
	v_mfma_f32_16x16x32_bf16 v[52:55], v[132:135], v[192:195], v[52:55]
	v_mfma_f32_16x16x32_bf16 v[48:51], v[140:143], v[192:195], v[48:51]
	v_mfma_f32_16x16x32_bf16 v[68:71], v[132:135], v[200:203], v[68:71]
	v_mfma_f32_16x16x32_bf16 v[64:67], v[140:143], v[200:203], v[64:67]
	s_setprio 0
	s_setprio 1
	v_mfma_f32_16x16x32_bf16 v[0:3], v[144:147], v[168:171], v[0:3]
	v_mfma_f32_16x16x32_bf16 v[4:7], v[152:155], v[168:171], v[4:7]
	v_mfma_f32_16x16x32_bf16 v[8:11], v[144:147], v[180:183], v[8:11]
	v_mfma_f32_16x16x32_bf16 v[12:15], v[152:155], v[180:183], v[12:15]
	v_mfma_f32_16x16x32_bf16 v[16:19], v[144:147], v[188:191], v[16:19]
	v_mfma_f32_16x16x32_bf16 v[20:23], v[152:155], v[188:191], v[20:23]
	v_mfma_f32_16x16x32_bf16 v[36:39], v[144:147], v[196:199], v[36:39]
	v_mfma_f32_16x16x32_bf16 v[44:47], v[152:155], v[196:199], v[44:47]
	s_setprio 0
	s_setprio 1
	v_mfma_f32_16x16x32_bf16 v[0:3], v[148:151], v[172:175], v[0:3]
	v_mfma_f32_16x16x32_bf16 v[4:7], v[156:159], v[172:175], v[4:7]
	v_mfma_f32_16x16x32_bf16 v[8:11], v[148:151], v[184:187], v[8:11]
	v_mfma_f32_16x16x32_bf16 v[12:15], v[156:159], v[184:187], v[12:15]
	v_mfma_f32_16x16x32_bf16 v[16:19], v[148:151], v[192:195], v[16:19]
	v_mfma_f32_16x16x32_bf16 v[20:23], v[156:159], v[192:195], v[20:23]
	v_mfma_f32_16x16x32_bf16 v[36:39], v[148:151], v[200:203], v[36:39]
	v_mfma_f32_16x16x32_bf16 v[44:47], v[156:159], v[200:203], v[44:47]
	s_setprio 0
	s_barrier
; #define PG8_STAGE(bufoff, gbase, voff) do { _Pragma("unroll") for (int _i = 0; _i < 2; ++_i) \
;         __builtin_amdgcn_global_load_lds((const GAS unsigned*)((const GAS char*)(gbase) + (size_t)_i * r64##voff + (vo##voff)), (LAS unsigned*)(lds + (bufoff) + ldsw + _i * 8192), 16, 0, 0); } while (0)
; #define PG8_LDA(dst, b, h) do { _Pragma("unroll") for (int m = 0; m < 4; ++m) _Pragma("unroll") for (int k = 0; k < 2; ++k) dst[m][k] = *(const LAS bf16x8*)(lds + PG8_SA(b, h) + aoff + m * 2048 + k * 1024); } while (0)
; #define PG8_LDB(dst, b, h) do { _Pragma("unroll") for (int n = 0; n < 2; ++n) _Pragma("unroll") for (int k = 0; k < 2; ++k) dst[n][k] = *(const LAS bf16x8*)(lds + PG8_SB(b, h) + boff + n * 2048 + k * 1024); } while (0)
; #define PG8_BAR __builtin_amdgcn_s_barrier()
; template <class Epi, class Map, bool ALIGN_EPI>
; __device__ __forceinline__ void gemm_phase(const int tid, LAS unsigned char* lds, const int lda, const int ldb, const int K, const Map& MP, const StaticOrder& S, const Epi& E) {
;     ...
;         for (int t = 0; t < nt; t += 2) {
;             const bool last = (t == nt - 2);
;             const char* a1 = cA + (size_t)(t + 1) * kstep;
;             const char* a2 = last ? nA : cA + (size_t)(t + 2) * kstep; const char* b2 = last ? nB : cB + (size_t)(t + 2) * kstep;
;             const char* a3 = a2 + kstep; const char* b3 = b2 + kstep;
;             PG8_LDB(B0, 0, 0); PG8_LDB(B1, 0, 1); PG8_SCHED; PG8_LDA(At, 0, 0); PG8_STAGE(PG8_SA(1, 1), a1 + hstepA, A);
;             PG8_WAIT_V(8); PG8_WAIT_L(0); PG8_BAR; PG8_MMA(0, 0, At, B0); PG8_MMA(0, 1, At, B1); PG8_BAR; PG8_SCHED;
;             PG8_LDA(At, 0, 1); PG8_STAGE(PG8_SB(0, 0), b2, B); PG8_STAGE(PG8_SB(0, 1), b2 + hstepB, B); PG8_STAGE(PG8_SA(0, 0), a2, A);
;             PG8_WAIT_V(8); PG8_WAIT_L(0); PG8_BAR; PG8_MMA(1, 0, At, B0); PG8_MMA(1, 1, At, B1); PG8_BAR; PG8_SCHED;
;             PG8_LDB(B0, 1, 0); PG8_LDB(B1, 1, 1); PG8_SCHED; PG8_LDA(At, 1, 0); PG8_STAGE(PG8_SA(0, 1), a2 + hstepA, A);
;             PG8_WAIT_V(8); PG8_WAIT_L(0); PG8_BAR; PG8_MMA(0, 0, At, B0); PG8_MMA(0, 1, At, B1); PG8_BAR; PG8_SCHED;
;             PG8_LDA(At, 1, 1); PG8_STAGE(PG8_SB(1, 0), b3, B); PG8_STAGE(PG8_SB(1, 1), b3 + hstepB, B); PG8_STAGE(PG8_SA(1, 0), a3, A);
;             PG8_WAIT_V(8); PG8_WAIT_L(0); PG8_BAR; PG8_MMA(1, 0, At, B0); PG8_MMA(1, 1, At, B1); PG8_BAR; PG8_SCHED;
;         }
	s_add_i32 s42, s78, s14
	v_lshl_add_u64 v[176:177], v[176:177], 0, s[50:51]
	s_mov_b32 m0, s42
	ds_read_b128 v[168:171], v179 offset:49152
	ds_read_b128 v[172:175], v179 offset:50176
	ds_read_b128 v[180:183], v179 offset:51200
	ds_read_b128 v[184:187], v179 offset:52224
	ds_read_b128 v[188:191], v179 offset:53248
	ds_read_b128 v[192:195], v179 offset:54272
	ds_read_b128 v[196:199], v179 offset:55296
	ds_read_b128 v[200:203], v179 offset:56320
	global_load_lds_dwordx4 v[176:177], off
	v_lshl_add_u64 v[176:177], v[176:177], 0, s[2:3]
	s_add_i32 m0, s42, 0x2000
	s_add_i32 s42, s79, s14
	global_load_lds_dwordx4 v[176:177], off
	v_lshl_add_u64 v[176:177], v[204:205], 0, s[50:51]
	s_mov_b32 m0, s42
	s_nop 0
	global_load_lds_dwordx4 v[176:177], off
	v_lshl_add_u64 v[176:177], v[176:177], 0, s[2:3]
	s_add_i32 m0, s42, 0x2000
	s_nop 0
	global_load_lds_dwordx4 v[176:177], off
	v_lshl_add_u64 v[176:177], v[206:207], 0, s[50:51]
	s_mov_b32 m0, s28
	s_nop 0
	global_load_lds_dwordx4 v[176:177], off
	v_lshl_add_u64 v[176:177], v[208:209], 0, s[50:51]
	s_mov_b32 m0, s29
	s_nop 0
	global_load_lds_dwordx4 v[176:177], off
	s_waitcnt vmcnt(8)
	s_waitcnt lgkmcnt(0)
	s_barrier
	s_setprio 1
	v_mfma_f32_16x16x32_bf16 v[84:87], v[128:131], v[168:171], v[84:87]
	v_mfma_f32_16x16x32_bf16 v[80:83], v[136:139], v[168:171], v[80:83]
	v_mfma_f32_16x16x32_bf16 v[116:119], v[128:131], v[180:183], v[116:119]
	v_mfma_f32_16x16x32_bf16 v[96:99], v[136:139], v[180:183], v[96:99]
	v_mfma_f32_16x16x32_bf16 v[124:127], v[128:131], v[188:191], v[124:127]
	v_mfma_f32_16x16x32_bf16 v[120:123], v[136:139], v[188:191], v[120:123]
	v_mfma_f32_16x16x32_bf16 v[108:111], v[128:131], v[196:199], v[108:111]
	v_mfma_f32_16x16x32_bf16 v[112:115], v[136:139], v[196:199], v[112:115]
	s_setprio 0
	s_setprio 1
	v_mfma_f32_16x16x32_bf16 v[84:87], v[132:135], v[172:175], v[84:87]
	v_mfma_f32_16x16x32_bf16 v[80:83], v[140:143], v[172:175], v[80:83]
	v_mfma_f32_16x16x32_bf16 v[116:119], v[132:135], v[184:187], v[116:119]
	v_mfma_f32_16x16x32_bf16 v[96:99], v[140:143], v[184:187], v[96:99]
	v_mfma_f32_16x16x32_bf16 v[124:127], v[132:135], v[192:195], v[124:127]
	v_mfma_f32_16x16x32_bf16 v[120:123], v[140:143], v[192:195], v[120:123]
	v_mfma_f32_16x16x32_bf16 v[108:111], v[132:135], v[200:203], v[108:111]
	v_mfma_f32_16x16x32_bf16 v[112:115], v[140:143], v[200:203], v[112:115]
	s_setprio 0
	s_setprio 1
	v_mfma_f32_16x16x32_bf16 v[56:59], v[144:147], v[168:171], v[56:59]
	v_mfma_f32_16x16x32_bf16 v[60:63], v[152:155], v[168:171], v[60:63]
	v_mfma_f32_16x16x32_bf16 v[72:75], v[144:147], v[180:183], v[72:75]
	v_mfma_f32_16x16x32_bf16 v[76:79], v[152:155], v[180:183], v[76:79]
	v_mfma_f32_16x16x32_bf16 v[92:95], v[144:147], v[188:191], v[92:95]
	v_mfma_f32_16x16x32_bf16 v[100:103], v[152:155], v[188:191], v[100:103]
	v_mfma_f32_16x16x32_bf16 v[104:107], v[144:147], v[196:199], v[104:107]
	v_mfma_f32_16x16x32_bf16 v[88:91], v[152:155], v[196:199], v[88:91]
	s_setprio 0
	s_setprio 1
	v_mfma_f32_16x16x32_bf16 v[56:59], v[148:151], v[172:175], v[56:59]
	v_mfma_f32_16x16x32_bf16 v[60:63], v[156:159], v[172:175], v[60:63]
	v_mfma_f32_16x16x32_bf16 v[72:75], v[148:151], v[184:187], v[72:75]
	v_mfma_f32_16x16x32_bf16 v[76:79], v[156:159], v[184:187], v[76:79]
	v_mfma_f32_16x16x32_bf16 v[92:95], v[148:151], v[192:195], v[92:95]
	v_mfma_f32_16x16x32_bf16 v[100:103], v[156:159], v[192:195], v[100:103]
	v_mfma_f32_16x16x32_bf16 v[104:107], v[148:151], v[200:203], v[104:107]
	v_mfma_f32_16x16x32_bf16 v[88:91], v[156:159], v[200:203], v[88:91]
	s_setprio 0
	s_barrier
	s_add_u32 s10, s10, 0x100
	s_addc_u32 s11, s11, 0
	s_add_u32 s45, s45, 0x100
	s_addc_u32 s46, s46, 0
	s_cmp_ge_u32 s47, s30
	s_mov_b32 s42, s47
	s_cbranch_scc0 .LBB0_1042
	s_and_b64 vcc, exec, s[56:57]
	s_cbranch_vccz .LBB0_1045
	s_barrier
